# RESID GEMM epilogue de-serialised: residual loads streamed 16 ahead of stores with counted vmcnt (same arithmetic); NSA flash loops: fragment prefetch + no-mask fast path
# speedup vs baseline: 1.0559x; 1.0559x over previous
; #define MFMA(a, b, c) __builtin_amdgcn_mfma_f32_32x32x16_bf16((a), (b), (c), 0, 0, 0)
;     ...
;   float mc = m * c2;
;   if (MODE == 2) mc = selbit ? mc : 1e30f;
;   const f32x2v c2v = {c2, c2}, mcv = {-mc, -mc};
;   f32x2v rs2 = {0.f, 0.f};
; #pragma unroll
;   for (int ks = 0; ks < 2; ++ks)
; #pragma unroll
;     for (int st = 0; st < 2; ++st) {
;       union { unsigned u[4]; bf16x8 v; } pf;
; #pragma unroll
;       for (int j = 0; j < 4; ++j) {
;         const int i0 = 8 * st + 2 * j;
;         f32x2v t = {S[ks][i0], S[ks][i0 + 1]};
;         t = __builtin_elementwise_fma(t, c2v, mcv);
;         f32x2v pv;
;         if (variant == 1) { pv = t; } else {
;         pv.x = __builtin_amdgcn_exp2f(t.x);
;         pv.y = __builtin_amdgcn_exp2f(t.y);
;         }
;         if (MODE != 0) {
;           if (need_mask) {
;             pv.x = (S[ks][i0] > -1e29f) ? pv.x : 0.f;
;             pv.y = (S[ks][i0 + 1] > -1e29f) ? pv.y : 0.f;
;           }
;         }
;         rs2 += pv;
;         pf.u[j] = __builtin_bit_cast(unsigned, __builtin_convertvector(pv, hwbf16x2));
;       }
; #pragma unroll
;       for (int d = 0; d < DV / 32; ++d) {
;         const char* vp = base + C::KBYTES + (d * 32 + lr) * C::VSTR + (ks * 32 + 16 * st + 4 * lh) * 2;
;         const s16x4 lo = *(const s16x4*)vp, hi = *(const s16x4*)(vp + 16);
;         const bf16x8 vf = __builtin_shufflevector(lo, hi, 0, 1, 2, 3, 4, 5, 6, 7);
;         O[d] = MFMA(vf, pf.v, O[d]);
;       }
;     }
;   float rs = rs2.x + rs2.y;
;   rs += __shfl_xor(rs, 32);
;   l += rs;
.LBB0_424:
	s_cmp_eq_u64 s[8:9], 0
	s_cbranch_scc1 .Lfast_sel1
	v_mul_f32_e32 v110, 0xbe38aa3b, v110
	v_cndmask_b32_e64 v110, v208, v110, s[10:11]
	v_pk_fma_f32 v[120:121], v[82:83], s[96:97], v[110:111] op_sel_hi:[1,0,0]
	v_cmp_lt_f32_e32 vcc, s33, v82
	v_exp_f32_e32 v119, v120
	v_exp_f32_e32 v120, v121
	v_cndmask_b32_e32 v82, 0, v119, vcc
	v_cmp_lt_f32_e32 vcc, s33, v83
	v_cndmask_b32_e64 v128, v119, v82, s[8:9]
	s_nop 0
	v_cndmask_b32_e32 v83, 0, v120, vcc
	v_cndmask_b32_e64 v129, v120, v83, s[8:9]
	v_pk_fma_f32 v[82:83], v[84:85], s[96:97], v[110:111] op_sel_hi:[1,0,0]
	v_cmp_lt_f32_e32 vcc, s33, v84
	v_exp_f32_e32 v82, v82
	v_exp_f32_e32 v83, v83
	v_cvt_pk_bf16_f32 v120, v128, v129
	v_cndmask_b32_e32 v84, 0, v82, vcc
	v_cmp_lt_f32_e32 vcc, s33, v85
	v_cndmask_b32_e64 v152, v82, v84, s[8:9]
	s_nop 0
	v_cndmask_b32_e32 v85, 0, v83, vcc
	v_cndmask_b32_e64 v153, v83, v85, s[8:9]
	v_pk_fma_f32 v[82:83], v[86:87], s[96:97], v[110:111] op_sel_hi:[1,0,0]
	v_cmp_lt_f32_e32 vcc, s33, v86
	v_exp_f32_e32 v82, v82
	v_exp_f32_e32 v83, v83
	v_cvt_pk_bf16_f32 v121, v152, v153
	v_cndmask_b32_e32 v84, 0, v82, vcc
	v_cmp_lt_f32_e32 vcc, s33, v87
	v_cndmask_b32_e64 v154, v82, v84, s[8:9]
	s_nop 0
	v_cndmask_b32_e32 v85, 0, v83, vcc
	v_cndmask_b32_e64 v155, v83, v85, s[8:9]
	v_pk_fma_f32 v[82:83], v[88:89], s[96:97], v[110:111] op_sel_hi:[1,0,0]
	v_cmp_lt_f32_e32 vcc, s33, v88
	v_exp_f32_e32 v82, v82
	v_exp_f32_e32 v83, v83
	v_cvt_pk_bf16_f32 v122, v154, v155
	v_cndmask_b32_e32 v84, 0, v82, vcc
	v_cmp_lt_f32_e32 vcc, s33, v89
	v_cndmask_b32_e64 v88, v82, v84, s[8:9]
	s_nop 0
	v_cndmask_b32_e32 v85, 0, v83, vcc
	v_cndmask_b32_e64 v89, v83, v85, s[8:9]
	s_nop 0
	s_nop 0
	s_nop 0
	s_nop 0
	v_cvt_pk_bf16_f32 v123, v88, v89
	s_nop 0
	v_cmp_lt_f32_e32 vcc, s33, v90
	s_waitcnt lgkmcnt(0)
	v_mfma_f32_32x32x16_bf16 v[50:65], v[216:219], v[120:123], v[50:65]
	s_nop 0
	s_waitcnt lgkmcnt(0)
	v_mfma_f32_32x32x16_bf16 v[34:49], v[220:223], v[120:123], v[34:49]
	v_add_f32_e64 v84, v128, 0
	v_add_f32_e64 v85, v129, 0
	v_add_f32_e64 v84, v152, v84
	v_add_f32_e64 v85, v153, v85
	v_add_f32_e64 v84, v154, v84
	v_add_f32_e64 v85, v155, v85
	v_pk_add_f32 v[120:121], v[88:89], v[84:85]
	v_pk_fma_f32 v[84:85], v[90:91], s[96:97], v[110:111] op_sel_hi:[1,0,0]
	s_nop 0
	v_exp_f32_e32 v84, v84
	v_exp_f32_e32 v85, v85
	v_cndmask_b32_e32 v86, 0, v84, vcc
	v_cmp_lt_f32_e32 vcc, s33, v91
	v_cndmask_b32_e64 v122, v84, v86, s[8:9]
	s_nop 0
	v_cndmask_b32_e32 v87, 0, v85, vcc
	v_cndmask_b32_e64 v123, v85, v87, s[8:9]
	v_pk_fma_f32 v[86:87], v[92:93], s[96:97], v[110:111] op_sel_hi:[1,0,0]
	v_cmp_lt_f32_e32 vcc, s33, v92
	v_exp_f32_e32 v85, v86
	v_exp_f32_e32 v86, v87
	v_cvt_pk_bf16_f32 v84, v122, v123
	v_cndmask_b32_e32 v87, 0, v85, vcc
	v_cmp_lt_f32_e32 vcc, s33, v93
	v_cndmask_b32_e64 v92, v85, v87, s[8:9]
	s_nop 0
	v_cndmask_b32_e32 v88, 0, v86, vcc
	v_cndmask_b32_e64 v93, v86, v88, s[8:9]
	v_pk_fma_f32 v[86:87], v[94:95], s[96:97], v[110:111] op_sel_hi:[1,0,0]
	v_cmp_lt_f32_e32 vcc, s33, v94
	v_exp_f32_e32 v86, v86
	v_exp_f32_e32 v87, v87
	v_cvt_pk_bf16_f32 v85, v92, v93
	v_cndmask_b32_e32 v88, 0, v86, vcc
	v_cmp_lt_f32_e32 vcc, s33, v95
	v_cndmask_b32_e64 v94, v86, v88, s[8:9]
	s_nop 0
	v_cndmask_b32_e32 v89, 0, v87, vcc
	v_cndmask_b32_e64 v95, v87, v89, s[8:9]
	v_pk_fma_f32 v[88:89], v[96:97], s[96:97], v[110:111] op_sel_hi:[1,0,0]
	v_cmp_lt_f32_e32 vcc, s33, v96
	v_exp_f32_e32 v87, v88
	v_exp_f32_e32 v88, v89
	v_cvt_pk_bf16_f32 v86, v94, v95
	v_cndmask_b32_e32 v89, 0, v87, vcc
	v_cmp_lt_f32_e32 vcc, s33, v97
	v_cndmask_b32_e64 v96, v87, v89, s[8:9]
	s_nop 0
	v_cndmask_b32_e32 v90, 0, v88, vcc
	v_cndmask_b32_e64 v97, v88, v90, s[8:9]
	s_nop 0
	v_cvt_pk_bf16_f32 v87, v96, v97
	v_cmp_lt_f32_e32 vcc, s33, v66
	s_nop 0
	v_mfma_f32_32x32x16_bf16 v[50:65], v[224:227], v[84:87], v[50:65]
	s_waitcnt lgkmcnt(0)
	v_mfma_f32_32x32x16_bf16 v[34:49], v[228:231], v[84:87], v[34:49]
	v_fma_f32 v86, v66, s96, v110
	v_fma_f32 v87, v67, s96, v110
	v_fma_f32 v88, v68, s96, v110
	v_fma_f32 v89, v69, s96, v110
	v_exp_f32_e32 v86, v86
	v_exp_f32_e32 v87, v87
	v_pk_add_f32 v[84:85], v[122:123], v[120:121]
	v_cndmask_b32_e32 v66, 0, v86, vcc
	v_cmp_lt_f32_e32 vcc, s33, v67
	v_pk_add_f32 v[84:85], v[92:93], v[84:85]
	v_cndmask_b32_e64 v86, v86, v66, s[8:9]
	v_cndmask_b32_e32 v67, 0, v87, vcc
	v_cndmask_b32_e64 v87, v87, v67, s[8:9]
	v_exp_f32_e32 v67, v88
	v_exp_f32_e32 v88, v89
	v_cmp_lt_f32_e32 vcc, s33, v68
	v_cvt_pk_bf16_f32 v66, v86, v87
	v_pk_add_f32 v[84:85], v[94:95], v[84:85]
	v_cndmask_b32_e32 v68, 0, v67, vcc
	v_cmp_lt_f32_e32 vcc, s33, v69
	v_pk_add_f32 v[84:85], v[96:97], v[84:85]
	s_nop 0
	v_cndmask_b32_e32 v69, 0, v88, vcc
	v_cndmask_b32_e64 v89, v88, v69, s[8:9]
	v_cndmask_b32_e64 v88, v67, v68, s[8:9]
	v_pk_fma_f32 v[68:69], v[70:71], s[96:97], v[110:111] op_sel_hi:[1,0,0]
	v_cmp_lt_f32_e32 vcc, s33, v70
	v_exp_f32_e32 v68, v68
	v_exp_f32_e32 v69, v69
	v_cvt_pk_bf16_f32 v67, v88, v89
	v_cndmask_b32_e32 v70, 0, v68, vcc
	v_cmp_lt_f32_e32 vcc, s33, v71
	v_cndmask_b32_e64 v90, v68, v70, s[8:9]
	s_nop 0
	v_cndmask_b32_e32 v71, 0, v69, vcc
	v_cndmask_b32_e64 v91, v69, v71, s[8:9]
	v_pk_fma_f32 v[70:71], v[72:73], s[96:97], v[110:111] op_sel_hi:[1,0,0]
	v_cmp_lt_f32_e32 vcc, s33, v72
	v_exp_f32_e32 v69, v70
	v_exp_f32_e32 v70, v71
	v_cvt_pk_bf16_f32 v68, v90, v91
	v_cndmask_b32_e32 v71, 0, v69, vcc
	v_cmp_lt_f32_e32 vcc, s33, v73
	v_cndmask_b32_e64 v92, v69, v71, s[8:9]
	s_nop 0
	v_cndmask_b32_e32 v72, 0, v70, vcc
	v_cndmask_b32_e64 v93, v70, v72, s[8:9]
	s_nop 0
	v_cvt_pk_bf16_f32 v69, v92, v93
	v_cmp_lt_f32_e32 vcc, s33, v74
	s_waitcnt lgkmcnt(0)
; #define MFMA(a, b, c) __builtin_amdgcn_mfma_f32_32x32x16_bf16((a), (b), (c), 0, 0, 0)
;     ...
;   for (int ks = 0; ks < 2; ++ks)
; #pragma unroll
;     for (int st = 0; st < 2; ++st) {
;       union { unsigned u[4]; bf16x8 v; } pf;
; #pragma unroll
;       for (int j = 0; j < 4; ++j) {
;         const int i0 = 8 * st + 2 * j;
;         f32x2v t = {S[ks][i0], S[ks][i0 + 1]};
;         t = __builtin_elementwise_fma(t, c2v, mcv);
;         f32x2v pv;
;         if (variant == 1) { pv = t; } else {
;         pv.x = __builtin_amdgcn_exp2f(t.x);
;         pv.y = __builtin_amdgcn_exp2f(t.y);
;         }
;         if (MODE != 0) {
;           if (need_mask) {
;             pv.x = (S[ks][i0] > -1e29f) ? pv.x : 0.f;
;             pv.y = (S[ks][i0 + 1] > -1e29f) ? pv.y : 0.f;
;           }
;         }
;         rs2 += pv;
;         pf.u[j] = __builtin_bit_cast(unsigned, __builtin_convertvector(pv, hwbf16x2));
;       }
; #pragma unroll
;       for (int d = 0; d < DV / 32; ++d) {
;         const char* vp = base + C::KBYTES + (d * 32 + lr) * C::VSTR + (ks * 32 + 16 * st + 4 * lh) * 2;
;         const s16x4 lo = *(const s16x4*)vp, hi = *(const s16x4*)(vp + 16);
;         const bf16x8 vf = __builtin_shufflevector(lo, hi, 0, 1, 2, 3, 4, 5, 6, 7);
;         O[d] = MFMA(vf, pf.v, O[d]);
;       }
;     }
;   float rs = rs2.x + rs2.y;
;   rs += __shfl_xor(rs, 32);
;   l += rs;
	v_mfma_f32_32x32x16_bf16 v[50:65], v[232:235], v[66:69], v[50:65]
	s_nop 0
	s_waitcnt lgkmcnt(0)
	v_mfma_f32_32x32x16_bf16 v[34:49], v[236:239], v[66:69], v[34:49]
	v_add_f32_e64 v66, v86, v84
	v_add_f32_e64 v67, v87, v85
	v_add_f32_e64 v66, v88, v66
	v_add_f32_e64 v67, v89, v67
	v_add_f32_e64 v66, v90, v66
	v_add_f32_e64 v67, v91, v67
	v_pk_add_f32 v[84:85], v[92:93], v[66:67]
	v_pk_fma_f32 v[66:67], v[74:75], s[96:97], v[110:111] op_sel_hi:[1,0,0]
	s_nop 0
	v_exp_f32_e32 v66, v66
	v_exp_f32_e32 v67, v67
	v_cndmask_b32_e32 v68, 0, v66, vcc
	v_cmp_lt_f32_e32 vcc, s33, v75
	v_cndmask_b32_e64 v74, v66, v68, s[8:9]
	s_nop 0
	v_cndmask_b32_e32 v69, 0, v67, vcc
	v_cndmask_b32_e64 v75, v67, v69, s[8:9]
	v_pk_fma_f32 v[68:69], v[76:77], s[96:97], v[110:111] op_sel_hi:[1,0,0]
	v_cmp_lt_f32_e32 vcc, s33, v76
	v_exp_f32_e32 v67, v68
	v_exp_f32_e32 v68, v69
	v_cvt_pk_bf16_f32 v66, v74, v75
	v_cndmask_b32_e32 v69, 0, v67, vcc
	v_cmp_lt_f32_e32 vcc, s33, v77
	v_cndmask_b32_e64 v76, v67, v69, s[8:9]
	s_nop 0
	v_cndmask_b32_e32 v70, 0, v68, vcc
	v_cndmask_b32_e64 v77, v68, v70, s[8:9]
	v_pk_fma_f32 v[68:69], v[78:79], s[96:97], v[110:111] op_sel_hi:[1,0,0]
	v_cmp_lt_f32_e32 vcc, s33, v78
	v_exp_f32_e32 v68, v68
	v_exp_f32_e32 v69, v69
	v_cvt_pk_bf16_f32 v67, v76, v77
	v_cndmask_b32_e32 v70, 0, v68, vcc
	v_cmp_lt_f32_e32 vcc, s33, v79
	v_cndmask_b32_e64 v78, v68, v70, s[8:9]
	s_nop 0
	v_cndmask_b32_e32 v71, 0, v69, vcc
	v_cndmask_b32_e64 v79, v69, v71, s[8:9]
	v_pk_fma_f32 v[70:71], v[80:81], s[96:97], v[110:111] op_sel_hi:[1,0,0]
	v_cmp_lt_f32_e32 vcc, s33, v80
	v_exp_f32_e32 v69, v70
	v_exp_f32_e32 v70, v71
	v_cvt_pk_bf16_f32 v68, v78, v79
	v_cndmask_b32_e32 v71, 0, v69, vcc
	v_cmp_lt_f32_e32 vcc, s33, v81
	v_cndmask_b32_e64 v80, v69, v71, s[8:9]
	s_nop 0
	v_cndmask_b32_e32 v72, 0, v70, vcc
	v_cndmask_b32_e64 v81, v70, v72, s[8:9]
	s_nop 0
	v_cvt_pk_bf16_f32 v69, v80, v81
	s_waitcnt lgkmcnt(0)
	s_nop 0
	v_mfma_f32_32x32x16_bf16 v[50:65], v[240:243], v[66:69], v[50:65]
	s_nop 0
	s_waitcnt lgkmcnt(0)
	v_mfma_f32_32x32x16_bf16 v[34:49], v[244:247], v[66:69], v[34:49]
	v_add_f32_e64 v66, v74, v84
	v_add_f32_e64 v67, v75, v85
	v_add_f32_e64 v66, v76, v66
	v_add_f32_e64 v67, v77, v67
	v_add_f32_e64 v66, v78, v66
	v_add_f32_e64 v67, v79, v67
	v_pk_add_f32 v[66:67], v[80:81], v[66:67]
	s_nop 0
	v_add_f32_e32 v66, v66, v67
	ds_bpermute_b32 v67, v165, v66
	s_waitcnt lgkmcnt(0)
	v_add_f32_e32 v66, v66, v67
	v_add_f32_e32 v164, v164, v66
	s_branch .LBB0_425
.Lfast_sel1:
	v_mul_f32_e32 v110, 0xbe38aa3b, v110
	v_cndmask_b32_e64 v110, v208, v110, s[10:11]
	v_pk_fma_f32 v[120:121], v[82:83], s[96:97], v[110:111] op_sel_hi:[1,0,0]
	v_exp_f32_e32 v128, v120
	v_exp_f32_e32 v129, v121
	v_pk_fma_f32 v[82:83], v[84:85], s[96:97], v[110:111] op_sel_hi:[1,0,0]
	v_exp_f32_e32 v152, v82
	v_exp_f32_e32 v153, v83
	v_cvt_pk_bf16_f32 v120, v128, v129
	v_pk_fma_f32 v[82:83], v[86:87], s[96:97], v[110:111] op_sel_hi:[1,0,0]
	v_exp_f32_e32 v154, v82
	v_exp_f32_e32 v155, v83
	v_cvt_pk_bf16_f32 v121, v152, v153
	v_pk_fma_f32 v[82:83], v[88:89], s[96:97], v[110:111] op_sel_hi:[1,0,0]
	v_exp_f32_e32 v88, v82
	v_exp_f32_e32 v89, v83
	v_cvt_pk_bf16_f32 v122, v154, v155
	v_cvt_pk_bf16_f32 v123, v88, v89
	s_waitcnt lgkmcnt(0)
	s_nop 0
	v_mfma_f32_32x32x16_bf16 v[50:65], v[216:219], v[120:123], v[50:65]
	s_waitcnt lgkmcnt(0)
	v_mfma_f32_32x32x16_bf16 v[34:49], v[220:223], v[120:123], v[34:49]
	v_add_f32_e64 v84, v128, 0
	v_add_f32_e64 v85, v129, 0
	v_add_f32_e64 v84, v152, v84
	v_add_f32_e64 v85, v153, v85
	v_add_f32_e64 v84, v154, v84
	v_add_f32_e64 v85, v155, v85
	v_pk_add_f32 v[120:121], v[88:89], v[84:85]
	v_pk_fma_f32 v[84:85], v[90:91], s[96:97], v[110:111] op_sel_hi:[1,0,0]
	v_exp_f32_e32 v122, v84
	v_exp_f32_e32 v123, v85
	v_pk_fma_f32 v[86:87], v[92:93], s[96:97], v[110:111] op_sel_hi:[1,0,0]
	v_exp_f32_e32 v92, v86
	v_exp_f32_e32 v93, v87
	v_cvt_pk_bf16_f32 v84, v122, v123
	v_pk_fma_f32 v[86:87], v[94:95], s[96:97], v[110:111] op_sel_hi:[1,0,0]
	v_exp_f32_e32 v94, v86
	v_exp_f32_e32 v95, v87
	v_cvt_pk_bf16_f32 v85, v92, v93
	v_pk_fma_f32 v[88:89], v[96:97], s[96:97], v[110:111] op_sel_hi:[1,0,0]
	v_exp_f32_e32 v96, v88
	v_exp_f32_e32 v97, v89
	v_cvt_pk_bf16_f32 v86, v94, v95
	v_cvt_pk_bf16_f32 v87, v96, v97
	s_nop 1
	v_mfma_f32_32x32x16_bf16 v[50:65], v[224:227], v[84:87], v[50:65]
	s_waitcnt lgkmcnt(0)
	v_mfma_f32_32x32x16_bf16 v[34:49], v[228:231], v[84:87], v[34:49]
	v_fma_f32 v86, v66, s96, v110
	v_fma_f32 v87, v67, s96, v110
	v_fma_f32 v88, v68, s96, v110
	v_fma_f32 v89, v69, s96, v110
	v_exp_f32_e32 v86, v86
	v_exp_f32_e32 v87, v87
	v_pk_add_f32 v[84:85], v[122:123], v[120:121]
	v_pk_add_f32 v[84:85], v[92:93], v[84:85]
	v_exp_f32_e32 v88, v88
	v_exp_f32_e32 v89, v89
	v_cvt_pk_bf16_f32 v66, v86, v87
	v_pk_add_f32 v[84:85], v[94:95], v[84:85]
	v_pk_add_f32 v[84:85], v[96:97], v[84:85]
	v_pk_fma_f32 v[68:69], v[70:71], s[96:97], v[110:111] op_sel_hi:[1,0,0]
	v_exp_f32_e32 v90, v68
	v_exp_f32_e32 v91, v69
	v_cvt_pk_bf16_f32 v67, v88, v89
	v_pk_fma_f32 v[70:71], v[72:73], s[96:97], v[110:111] op_sel_hi:[1,0,0]
	v_exp_f32_e32 v92, v70
	v_exp_f32_e32 v93, v71
	v_cvt_pk_bf16_f32 v68, v90, v91
	v_cvt_pk_bf16_f32 v69, v92, v93
	s_waitcnt lgkmcnt(0)
	s_nop 0
	v_mfma_f32_32x32x16_bf16 v[50:65], v[232:235], v[66:69], v[50:65]
	s_waitcnt lgkmcnt(0)
	v_mfma_f32_32x32x16_bf16 v[34:49], v[236:239], v[66:69], v[34:49]
	v_add_f32_e64 v66, v86, v84
	v_add_f32_e64 v67, v87, v85
	v_add_f32_e64 v66, v88, v66
	v_add_f32_e64 v67, v89, v67
	v_add_f32_e64 v66, v90, v66
	v_add_f32_e64 v67, v91, v67
	v_pk_add_f32 v[84:85], v[92:93], v[66:67]
	v_pk_fma_f32 v[66:67], v[74:75], s[96:97], v[110:111] op_sel_hi:[1,0,0]
	v_exp_f32_e32 v74, v66
	v_exp_f32_e32 v75, v67
	v_pk_fma_f32 v[68:69], v[76:77], s[96:97], v[110:111] op_sel_hi:[1,0,0]
	v_exp_f32_e32 v76, v68
	v_exp_f32_e32 v77, v69
	v_cvt_pk_bf16_f32 v66, v74, v75
	v_pk_fma_f32 v[68:69], v[78:79], s[96:97], v[110:111] op_sel_hi:[1,0,0]
	v_exp_f32_e32 v78, v68
	v_exp_f32_e32 v79, v69
	v_cvt_pk_bf16_f32 v67, v76, v77
	v_pk_fma_f32 v[70:71], v[80:81], s[96:97], v[110:111] op_sel_hi:[1,0,0]
	v_exp_f32_e32 v80, v70
	v_exp_f32_e32 v81, v71
	v_cvt_pk_bf16_f32 v68, v78, v79
	v_cvt_pk_bf16_f32 v69, v80, v81
	s_waitcnt lgkmcnt(0)
	s_nop 0
	v_mfma_f32_32x32x16_bf16 v[50:65], v[240:243], v[66:69], v[50:65]
	s_waitcnt lgkmcnt(0)
	v_mfma_f32_32x32x16_bf16 v[34:49], v[244:247], v[66:69], v[34:49]
	v_add_f32_e64 v66, v74, v84
	v_add_f32_e64 v67, v75, v85
	v_add_f32_e64 v66, v76, v66
	v_add_f32_e64 v67, v77, v67
	v_add_f32_e64 v66, v78, v66
	v_add_f32_e64 v67, v79, v67
	v_pk_add_f32 v[66:67], v[80:81], v[66:67]
	v_add_f32_e32 v66, v66, v67
	ds_bpermute_b32 v67, v165, v66
	s_waitcnt lgkmcnt(0)
	v_add_f32_e32 v66, v66, v67
	v_add_f32_e32 v164, v164, v66

; #define MFMA(a, b, c) __builtin_amdgcn_mfma_f32_32x32x16_bf16((a), (b), (c), 0, 0, 0)
; DI int crow(int i, int h) { return (i & 3) + 8 * (i >> 2) + 4 * h; }
; template <int DK, int DV, int MODE>
; DI void fa_qk(f32x16 (&S)[2], const bf16x8 (&q)[DK / 16], const char* base, int lr, int lh) {
;   using C = FA<DK, DV>;
; #pragma unroll
;   for (int ks = 0; ks < 2; ++ks) {
; #pragma unroll
;     for (int kk = 0; kk < DK / 16; ++kk) {
;       const bf16x8 kf = *(const bf16x8*)(base + (ks * 32 + lr) * C::KSTR + (kk * 2 + lh) * 16);
;       if (kk == 0) {
; #pragma unroll
;         for (int i = 0; i < 16; ++i) S[ks][i] = 0.f;
;       }
;       S[ks] = MFMA(kf, q[kk], S[ks]);
;     }
;   }
; }
;     ...
;   if (MODE != 0) need_mask = (kb * 64 + 63 > wave_qmax - 31);
;   if (MODE == 2) selbit = (sel >> kb) & 1ull;
;   if (MODE == 3) need_mask = need_mask || (kb * 64 <= wave_qmax - 512);
;   const float c2 = scale * 1.4426950408889634f;
;   if (need_mask) {
; #pragma unroll
;     for (int ks = 0; ks < 2; ++ks)
; #pragma unroll
;       for (int i = 0; i < 16; ++i) {
;         const int key = kb * 64 + ks * 32 + crow(i, lh);
;         bool valid = key <= qpos;
;         if (MODE == 2) valid = valid && selbit;
;         if (MODE == 3) valid = valid && (qpos - key < 512);
;         S[ks][i] = valid ? S[ks][i] : -1e30f;
;       }
;   }
.LBB0_436:
	v_lshrrev_b64 v[66:67], s0, v[98:99]
	s_sub_i32 s8, s7, 63
	v_and_b32_e32 v66, 1, v66
	s_cmp_le_u32 s8, s20
	v_cmp_ne_u32_e32 vcc, 0, v66
	s_cselect_b64 s[8:9], -1, 0
	s_cmp_lg_u64 vcc, 0
	s_cselect_b64 s[10:11], -1, 0
	s_and_b64 s[8:9], s[10:11], s[8:9]
	s_andn2_b64 vcc, exec, s[8:9]
	v_cmp_eq_u32_e64 s[10:11], 1, v66
	s_cbranch_vccnz .LBB0_425
	s_add_i32 s6, s6, 0
	v_add3_u32 v110, s6, v115, v114
	ds_read_b128 v[216:219], v110
	ds_read_b128 v[220:223], v110 offset:32
	ds_read_b128 v[224:227], v110 offset:64
	ds_read_b128 v[228:231], v110 offset:96
	ds_read_b128 v[232:235], v110 offset:4608
	ds_read_b128 v[236:239], v110 offset:4640
	ds_read_b128 v[240:243], v110 offset:4672
	ds_read_b128 v[244:247], v110 offset:4704
	s_cmp_gt_u32 s7, s35
	s_cselect_b64 s[8:9], -1, 0
	s_cmp_le_u32 s7, s35
	s_waitcnt lgkmcnt(7)
	v_mfma_f32_32x32x16_bf16 v[82:97], v[216:219], v[138:141], 0
	s_waitcnt lgkmcnt(6)
	v_mfma_f32_32x32x16_bf16 v[82:97], v[220:223], v[130:133], v[82:97]
	s_waitcnt lgkmcnt(5)
	v_mfma_f32_32x32x16_bf16 v[82:97], v[224:227], v[134:137], v[82:97]
	s_waitcnt lgkmcnt(4)
	v_mfma_f32_32x32x16_bf16 v[82:97], v[228:231], v[142:145], v[82:97]
	s_waitcnt lgkmcnt(3)
	v_mfma_f32_32x32x16_bf16 v[66:81], v[232:235], v[138:141], 0
	s_waitcnt lgkmcnt(2)
	v_mfma_f32_32x32x16_bf16 v[66:81], v[236:239], v[130:133], v[66:81]
	s_waitcnt lgkmcnt(1)
	v_mfma_f32_32x32x16_bf16 v[66:81], v[240:243], v[134:137], v[66:81]
	s_waitcnt lgkmcnt(0)
	v_mfma_f32_32x32x16_bf16 v[66:81], v[244:247], v[142:145], v[66:81]
	v_add3_u32 v247, s6, v117, v115
	v_add_u32_e32 v243, 0x2000, v247
	v_add_u32_e32 v247, 0x3000, v247
	ds_read2_b64 v[216:219], v243 offset0:128 offset1:130
	ds_read2_b64 v[220:223], v247 offset0:192 offset1:194
	ds_read2_b64 v[224:227], v243 offset0:132 offset1:134
	ds_read2_b64 v[228:231], v247 offset0:196 offset1:198
	ds_read2_b64 v[232:235], v243 offset0:136 offset1:138
	ds_read2_b64 v[236:239], v247 offset0:200 offset1:202
	ds_read2_b64 v[240:243], v243 offset0:140 offset1:142
	ds_read2_b64 v[244:247], v247 offset0:204 offset1:206
	s_cbranch_scc1 .LBB0_439
	v_add_u32_e32 v110, s7, v116
	v_subrev_u32_e32 v119, 63, v110
	v_cmp_le_i32_e32 vcc, v119, v148
	s_and_b64 vcc, vcc, s[10:11]
	s_nop 0
	v_cndmask_b32_e32 v82, v208, v82, vcc
	v_cmp_lt_i32_e32 vcc, v119, v148
	s_and_b64 vcc, vcc, s[10:11]
	v_subrev_u32_e32 v119, 61, v110
	v_cndmask_b32_e32 v83, v208, v83, vcc
	v_cmp_le_i32_e32 vcc, v119, v148
	s_and_b64 vcc, vcc, s[10:11]
	v_subrev_u32_e32 v119, 60, v110
	v_cndmask_b32_e32 v84, v208, v84, vcc
	v_cmp_le_i32_e32 vcc, v119, v148
	s_and_b64 vcc, vcc, s[10:11]
	v_subrev_u32_e32 v119, 55, v110
	v_cndmask_b32_e32 v85, v208, v85, vcc
	v_cmp_le_i32_e32 vcc, v119, v148
	s_and_b64 vcc, vcc, s[10:11]
	v_subrev_u32_e32 v119, 54, v110
	v_cndmask_b32_e32 v86, v208, v86, vcc
	v_cmp_le_i32_e32 vcc, v119, v148
	s_and_b64 vcc, vcc, s[10:11]
	v_subrev_u32_e32 v119, 53, v110
	v_cndmask_b32_e32 v87, v208, v87, vcc
	v_cmp_le_i32_e32 vcc, v119, v148
	s_and_b64 vcc, vcc, s[10:11]
	v_subrev_u32_e32 v119, 52, v110
	v_cndmask_b32_e32 v88, v208, v88, vcc
	v_cmp_le_i32_e32 vcc, v119, v148
	s_and_b64 vcc, vcc, s[10:11]
	v_subrev_u32_e32 v119, 47, v110
	v_cndmask_b32_e32 v89, v208, v89, vcc
	v_cmp_le_i32_e32 vcc, v119, v148
	s_and_b64 vcc, vcc, s[10:11]
	v_subrev_u32_e32 v119, 46, v110
	v_cndmask_b32_e32 v90, v208, v90, vcc
	v_cmp_le_i32_e32 vcc, v119, v148
	s_and_b64 vcc, vcc, s[10:11]
	v_subrev_u32_e32 v119, 45, v110
	v_cndmask_b32_e32 v91, v208, v91, vcc
	v_cmp_le_i32_e32 vcc, v119, v148
	s_and_b64 vcc, vcc, s[10:11]
	v_subrev_u32_e32 v119, 44, v110
	v_cndmask_b32_e32 v92, v208, v92, vcc
	v_cmp_le_i32_e32 vcc, v119, v148
	s_and_b64 vcc, vcc, s[10:11]
	v_subrev_u32_e32 v119, 39, v110
	v_cndmask_b32_e32 v93, v208, v93, vcc
	v_cmp_le_i32_e32 vcc, v119, v148
	s_and_b64 vcc, vcc, s[10:11]
	v_subrev_u32_e32 v119, 38, v110
	v_cndmask_b32_e32 v94, v208, v94, vcc
	v_cmp_le_i32_e32 vcc, v119, v148
	s_and_b64 vcc, vcc, s[10:11]
	v_subrev_u32_e32 v119, 37, v110
	v_cndmask_b32_e32 v95, v208, v95, vcc
	v_cmp_le_i32_e32 vcc, v119, v148
	s_and_b64 vcc, vcc, s[10:11]
	v_subrev_u32_e32 v119, 36, v110
	v_cndmask_b32_e32 v96, v208, v96, vcc
	v_cmp_le_i32_e32 vcc, v119, v148
	s_and_b64 vcc, vcc, s[10:11]
	v_subrev_u32_e32 v119, 31, v110
	v_cndmask_b32_e32 v97, v208, v97, vcc
	v_cmp_le_i32_e32 vcc, v119, v148
	s_and_b64 vcc, vcc, s[10:11]
	v_subrev_u32_e32 v119, 30, v110
	v_cndmask_b32_e32 v66, v208, v66, vcc
	v_cmp_le_i32_e32 vcc, v119, v148
	s_and_b64 vcc, vcc, s[10:11]
	v_subrev_u32_e32 v119, 29, v110
	v_cndmask_b32_e32 v67, v208, v67, vcc
	v_cmp_le_i32_e32 vcc, v119, v148
	s_and_b64 vcc, vcc, s[10:11]
	v_subrev_u32_e32 v119, 28, v110
	v_cndmask_b32_e32 v68, v208, v68, vcc
	v_cmp_le_i32_e32 vcc, v119, v148
	s_and_b64 vcc, vcc, s[10:11]
	v_subrev_u32_e32 v119, 23, v110
	v_cndmask_b32_e32 v69, v208, v69, vcc
	v_cmp_le_i32_e32 vcc, v119, v148
	s_and_b64 vcc, vcc, s[10:11]
	v_subrev_u32_e32 v119, 22, v110
	v_cndmask_b32_e32 v70, v208, v70, vcc
	v_cmp_le_i32_e32 vcc, v119, v148
	s_and_b64 vcc, vcc, s[10:11]
	v_subrev_u32_e32 v119, 21, v110
	v_cndmask_b32_e32 v71, v208, v71, vcc
	v_cmp_le_i32_e32 vcc, v119, v148
	s_and_b64 vcc, vcc, s[10:11]
	v_subrev_u32_e32 v119, 20, v110
	v_cndmask_b32_e32 v72, v208, v72, vcc
	v_cmp_le_i32_e32 vcc, v119, v148
	s_and_b64 vcc, vcc, s[10:11]
	v_add_u32_e32 v119, -15, v110
	v_cndmask_b32_e32 v73, v208, v73, vcc
	v_cmp_le_i32_e32 vcc, v119, v148
	s_and_b64 vcc, vcc, s[10:11]
	v_add_u32_e32 v119, -14, v110
	v_cndmask_b32_e32 v74, v208, v74, vcc
	v_cmp_le_i32_e32 vcc, v119, v148
	s_and_b64 vcc, vcc, s[10:11]
	v_add_u32_e32 v119, -13, v110
	v_cndmask_b32_e32 v75, v208, v75, vcc
	v_cmp_le_i32_e32 vcc, v119, v148
	s_and_b64 vcc, vcc, s[10:11]
	v_add_u32_e32 v119, -12, v110
	v_cndmask_b32_e32 v76, v208, v76, vcc
	v_cmp_le_i32_e32 vcc, v119, v148
	s_and_b64 vcc, vcc, s[10:11]
	v_add_u32_e32 v119, -7, v110
	v_cndmask_b32_e32 v77, v208, v77, vcc
	v_cmp_le_i32_e32 vcc, v119, v148
	s_and_b64 vcc, vcc, s[10:11]
	v_add_u32_e32 v119, -6, v110
	v_cndmask_b32_e32 v78, v208, v78, vcc
	v_cmp_le_i32_e32 vcc, v119, v148
	s_and_b64 vcc, vcc, s[10:11]
	v_add_u32_e32 v119, -5, v110
	v_cndmask_b32_e32 v79, v208, v79, vcc
	v_cmp_le_i32_e32 vcc, v119, v148
	s_and_b64 vcc, vcc, s[10:11]
	v_add_u32_e32 v110, -4, v110
	v_cndmask_b32_e32 v80, v208, v80, vcc
	v_cmp_le_i32_e32 vcc, v110, v148
	s_and_b64 vcc, vcc, s[10:11]
	s_nop 0
	v_cndmask_b32_e32 v81, v208, v81, vcc

; #define MFMA(a, b, c) __builtin_amdgcn_mfma_f32_32x32x16_bf16((a), (b), (c), 0, 0, 0)
;     ...
;   float mc = m * c2;
;   if (MODE == 2) mc = selbit ? mc : 1e30f;
;   const f32x2v c2v = {c2, c2}, mcv = {-mc, -mc};
;   f32x2v rs2 = {0.f, 0.f};
; #pragma unroll
;   for (int ks = 0; ks < 2; ++ks)
; #pragma unroll
;     for (int st = 0; st < 2; ++st) {
;       union { unsigned u[4]; bf16x8 v; } pf;
; #pragma unroll
;       for (int j = 0; j < 4; ++j) {
;         const int i0 = 8 * st + 2 * j;
;         f32x2v t = {S[ks][i0], S[ks][i0 + 1]};
;         t = __builtin_elementwise_fma(t, c2v, mcv);
;         f32x2v pv;
;         if (variant == 1) { pv = t; } else {
;         pv.x = __builtin_amdgcn_exp2f(t.x);
;         pv.y = __builtin_amdgcn_exp2f(t.y);
;         }
;         if (MODE != 0) {
;           if (need_mask) {
;             pv.x = (S[ks][i0] > -1e29f) ? pv.x : 0.f;
;             pv.y = (S[ks][i0 + 1] > -1e29f) ? pv.y : 0.f;
;           }
;         }
;         rs2 += pv;
;         pf.u[j] = __builtin_bit_cast(unsigned, __builtin_convertvector(pv, hwbf16x2));
;       }
; #pragma unroll
;       for (int d = 0; d < DV / 32; ++d) {
;         const char* vp = base + C::KBYTES + (d * 32 + lr) * C::VSTR + (ks * 32 + 16 * st + 4 * lh) * 2;
;         const s16x4 lo = *(const s16x4*)vp, hi = *(const s16x4*)(vp + 16);
;         const bf16x8 vf = __builtin_shufflevector(lo, hi, 0, 1, 2, 3, 4, 5, 6, 7);
;         O[d] = MFMA(vf, pf.v, O[d]);
;       }
;     }
;   float rs = rs2.x + rs2.y;
;   rs += __shfl_xor(rs, 32);
;   l += rs;
.LBB0_455:
	s_cmp_eq_u64 s[8:9], 0
	s_cbranch_scc1 .Lfast_win1
	v_mul_f32_e32 v162, 0xbe38aa3b, v162
	v_pk_fma_f32 v[180:181], v[114:115], s[96:97], v[162:163] op_sel_hi:[1,0,0]
	v_cmp_lt_f32_e32 vcc, s33, v114
	v_exp_f32_e32 v179, v180
	v_exp_f32_e32 v180, v181
	v_cndmask_b32_e32 v114, 0, v179, vcc
	v_cmp_lt_f32_e32 vcc, s33, v115
	v_cndmask_b32_e64 v188, v179, v114, s[8:9]
	s_nop 0
	v_cndmask_b32_e32 v115, 0, v180, vcc
	v_cndmask_b32_e64 v189, v180, v115, s[8:9]
	v_pk_fma_f32 v[114:115], v[116:117], s[96:97], v[162:163] op_sel_hi:[1,0,0]
	v_cmp_lt_f32_e32 vcc, s33, v116
	v_exp_f32_e32 v114, v114
	v_exp_f32_e32 v115, v115
	v_cvt_pk_bf16_f32 v180, v188, v189
	v_cndmask_b32_e32 v116, 0, v114, vcc
	v_cmp_lt_f32_e32 vcc, s33, v117
	v_cndmask_b32_e64 v190, v114, v116, s[8:9]
	s_nop 0
	v_cndmask_b32_e32 v117, 0, v115, vcc
	v_cndmask_b32_e64 v191, v115, v117, s[8:9]
	v_pk_fma_f32 v[114:115], v[118:119], s[96:97], v[162:163] op_sel_hi:[1,0,0]
	v_cmp_lt_f32_e32 vcc, s33, v118
	v_exp_f32_e32 v114, v114
	v_exp_f32_e32 v115, v115
	v_cvt_pk_bf16_f32 v181, v190, v191
	v_cndmask_b32_e32 v116, 0, v114, vcc
	v_cmp_lt_f32_e32 vcc, s33, v119
	v_cndmask_b32_e64 v192, v114, v116, s[8:9]
	s_nop 0
	v_cndmask_b32_e32 v117, 0, v115, vcc
	v_cndmask_b32_e64 v193, v115, v117, s[8:9]
	v_pk_fma_f32 v[114:115], v[120:121], s[96:97], v[162:163] op_sel_hi:[1,0,0]
	v_cmp_lt_f32_e32 vcc, s33, v120
	v_exp_f32_e32 v114, v114
	v_exp_f32_e32 v115, v115
	v_cvt_pk_bf16_f32 v182, v192, v193
	v_cndmask_b32_e32 v116, 0, v114, vcc
	v_cmp_lt_f32_e32 vcc, s33, v121
	v_cndmask_b32_e64 v120, v114, v116, s[8:9]
	s_nop 0
	v_cndmask_b32_e32 v117, 0, v115, vcc
	v_cndmask_b32_e64 v121, v115, v117, s[8:9]
	s_nop 0
	s_nop 0
	s_nop 0
	s_nop 0
	v_cvt_pk_bf16_f32 v183, v120, v121
	s_nop 0
	v_cmp_lt_f32_e32 vcc, s33, v122
	s_waitcnt lgkmcnt(0)
	v_mfma_f32_32x32x16_bf16 v[82:97], v[216:219], v[180:183], v[82:97]
	s_nop 0
	s_waitcnt lgkmcnt(0)
	v_mfma_f32_32x32x16_bf16 v[66:81], v[220:223], v[180:183], v[66:81]
	v_add_f32_e64 v116, v188, 0
	v_add_f32_e64 v117, v189, 0
	v_add_f32_e64 v116, v190, v116
	v_add_f32_e64 v117, v191, v117
	v_add_f32_e64 v116, v192, v116
	v_add_f32_e64 v117, v193, v117
	v_pk_add_f32 v[180:181], v[120:121], v[116:117]
	v_pk_fma_f32 v[116:117], v[122:123], s[96:97], v[162:163] op_sel_hi:[1,0,0]
	s_nop 0
	v_exp_f32_e32 v116, v116
	v_exp_f32_e32 v117, v117
	v_cndmask_b32_e32 v118, 0, v116, vcc
	v_cmp_lt_f32_e32 vcc, s33, v123
	v_cndmask_b32_e64 v182, v116, v118, s[8:9]
	s_nop 0
	v_cndmask_b32_e32 v119, 0, v117, vcc
	v_cndmask_b32_e64 v183, v117, v119, s[8:9]
	v_pk_fma_f32 v[118:119], v[124:125], s[96:97], v[162:163] op_sel_hi:[1,0,0]
	v_cmp_lt_f32_e32 vcc, s33, v124
	v_exp_f32_e32 v117, v118
	v_exp_f32_e32 v118, v119
	v_cvt_pk_bf16_f32 v116, v182, v183
	v_cndmask_b32_e32 v119, 0, v117, vcc
	v_cmp_lt_f32_e32 vcc, s33, v125
	v_cndmask_b32_e64 v124, v117, v119, s[8:9]
	s_nop 0
	v_cndmask_b32_e32 v120, 0, v118, vcc
	v_cndmask_b32_e64 v125, v118, v120, s[8:9]
	v_pk_fma_f32 v[118:119], v[126:127], s[96:97], v[162:163] op_sel_hi:[1,0,0]
	v_cmp_lt_f32_e32 vcc, s33, v126
	v_exp_f32_e32 v118, v118
	v_exp_f32_e32 v119, v119
	v_cvt_pk_bf16_f32 v117, v124, v125
	v_cndmask_b32_e32 v120, 0, v118, vcc
	v_cmp_lt_f32_e32 vcc, s33, v127
	v_cndmask_b32_e64 v126, v118, v120, s[8:9]
	s_nop 0
	v_cndmask_b32_e32 v121, 0, v119, vcc
	v_cndmask_b32_e64 v127, v119, v121, s[8:9]
	v_pk_fma_f32 v[120:121], v[128:129], s[96:97], v[162:163] op_sel_hi:[1,0,0]
	v_cmp_lt_f32_e32 vcc, s33, v128
	v_exp_f32_e32 v119, v120
	v_exp_f32_e32 v120, v121
	v_cvt_pk_bf16_f32 v118, v126, v127
	v_cndmask_b32_e32 v121, 0, v119, vcc
	v_cmp_lt_f32_e32 vcc, s33, v129
	v_cndmask_b32_e64 v128, v119, v121, s[8:9]
	s_nop 0
	v_cndmask_b32_e32 v122, 0, v120, vcc
	v_cndmask_b32_e64 v129, v120, v122, s[8:9]
	s_nop 0
	v_cvt_pk_bf16_f32 v119, v128, v129
	v_cmp_lt_f32_e32 vcc, s33, v98
	s_nop 0
	v_mfma_f32_32x32x16_bf16 v[82:97], v[224:227], v[116:119], v[82:97]
	s_waitcnt lgkmcnt(0)
	v_mfma_f32_32x32x16_bf16 v[66:81], v[228:231], v[116:119], v[66:81]
	v_fma_f32 v118, v98, s96, v162
	v_fma_f32 v119, v99, s96, v162
	v_fma_f32 v120, v100, s96, v162
	v_fma_f32 v121, v101, s96, v162
	v_exp_f32_e32 v118, v118
	v_exp_f32_e32 v119, v119
	v_pk_add_f32 v[116:117], v[182:183], v[180:181]
	v_cndmask_b32_e32 v98, 0, v118, vcc
	v_cmp_lt_f32_e32 vcc, s33, v99
	v_pk_add_f32 v[116:117], v[124:125], v[116:117]
	v_cndmask_b32_e64 v118, v118, v98, s[8:9]
	v_cndmask_b32_e32 v99, 0, v119, vcc
	v_cndmask_b32_e64 v119, v119, v99, s[8:9]
	v_exp_f32_e32 v99, v120
	v_exp_f32_e32 v120, v121
	v_cmp_lt_f32_e32 vcc, s33, v100
	v_cvt_pk_bf16_f32 v98, v118, v119
	v_pk_add_f32 v[116:117], v[126:127], v[116:117]
	v_cndmask_b32_e32 v100, 0, v99, vcc
	v_cmp_lt_f32_e32 vcc, s33, v101
	v_pk_add_f32 v[116:117], v[128:129], v[116:117]
	s_nop 0
	v_cndmask_b32_e32 v101, 0, v120, vcc
	v_cndmask_b32_e64 v121, v120, v101, s[8:9]
	v_cndmask_b32_e64 v120, v99, v100, s[8:9]
	v_pk_fma_f32 v[100:101], v[102:103], s[96:97], v[162:163] op_sel_hi:[1,0,0]
	v_cmp_lt_f32_e32 vcc, s33, v102
	v_exp_f32_e32 v100, v100
	v_exp_f32_e32 v101, v101
	v_cvt_pk_bf16_f32 v99, v120, v121
	v_cndmask_b32_e32 v102, 0, v100, vcc
	v_cmp_lt_f32_e32 vcc, s33, v103
	v_cndmask_b32_e64 v122, v100, v102, s[8:9]
	s_nop 0
	v_cndmask_b32_e32 v103, 0, v101, vcc
	v_cndmask_b32_e64 v123, v101, v103, s[8:9]
	v_pk_fma_f32 v[102:103], v[104:105], s[96:97], v[162:163] op_sel_hi:[1,0,0]
	v_cmp_lt_f32_e32 vcc, s33, v104
	v_exp_f32_e32 v101, v102
	v_exp_f32_e32 v102, v103
	v_cvt_pk_bf16_f32 v100, v122, v123
	v_cndmask_b32_e32 v103, 0, v101, vcc
	v_cmp_lt_f32_e32 vcc, s33, v105
	v_cndmask_b32_e64 v124, v101, v103, s[8:9]
	s_nop 0
	v_cndmask_b32_e32 v104, 0, v102, vcc
	v_cndmask_b32_e64 v125, v102, v104, s[8:9]
	s_nop 0
	v_cvt_pk_bf16_f32 v101, v124, v125
	v_cmp_lt_f32_e32 vcc, s33, v106
	s_waitcnt lgkmcnt(0)
; #define MFMA(a, b, c) __builtin_amdgcn_mfma_f32_32x32x16_bf16((a), (b), (c), 0, 0, 0)
;     ...
;   for (int ks = 0; ks < 2; ++ks)
; #pragma unroll
;     for (int st = 0; st < 2; ++st) {
;       union { unsigned u[4]; bf16x8 v; } pf;
; #pragma unroll
;       for (int j = 0; j < 4; ++j) {
;         const int i0 = 8 * st + 2 * j;
;         f32x2v t = {S[ks][i0], S[ks][i0 + 1]};
;         t = __builtin_elementwise_fma(t, c2v, mcv);
;         f32x2v pv;
;         if (variant == 1) { pv = t; } else {
;         pv.x = __builtin_amdgcn_exp2f(t.x);
;         pv.y = __builtin_amdgcn_exp2f(t.y);
;         }
;         if (MODE != 0) {
;           if (need_mask) {
;             pv.x = (S[ks][i0] > -1e29f) ? pv.x : 0.f;
;             pv.y = (S[ks][i0 + 1] > -1e29f) ? pv.y : 0.f;
;           }
;         }
;         rs2 += pv;
;         pf.u[j] = __builtin_bit_cast(unsigned, __builtin_convertvector(pv, hwbf16x2));
;       }
; #pragma unroll
;       for (int d = 0; d < DV / 32; ++d) {
;         const char* vp = base + C::KBYTES + (d * 32 + lr) * C::VSTR + (ks * 32 + 16 * st + 4 * lh) * 2;
;         const s16x4 lo = *(const s16x4*)vp, hi = *(const s16x4*)(vp + 16);
;         const bf16x8 vf = __builtin_shufflevector(lo, hi, 0, 1, 2, 3, 4, 5, 6, 7);
;         O[d] = MFMA(vf, pf.v, O[d]);
;       }
;     }
;   float rs = rs2.x + rs2.y;
;   rs += __shfl_xor(rs, 32);
;   l += rs;
	v_mfma_f32_32x32x16_bf16 v[82:97], v[232:235], v[98:101], v[82:97]
	s_nop 0
	s_waitcnt lgkmcnt(0)
	v_mfma_f32_32x32x16_bf16 v[66:81], v[236:239], v[98:101], v[66:81]
	v_add_f32_e64 v98, v118, v116
	v_add_f32_e64 v99, v119, v117
	v_add_f32_e64 v98, v120, v98
	v_add_f32_e64 v99, v121, v99
	v_add_f32_e64 v98, v122, v98
	v_add_f32_e64 v99, v123, v99
	v_pk_add_f32 v[116:117], v[124:125], v[98:99]
	v_pk_fma_f32 v[98:99], v[106:107], s[96:97], v[162:163] op_sel_hi:[1,0,0]
	s_nop 0
	v_exp_f32_e32 v98, v98
	v_exp_f32_e32 v99, v99
	v_cndmask_b32_e32 v100, 0, v98, vcc
	v_cmp_lt_f32_e32 vcc, s33, v107
	v_cndmask_b32_e64 v106, v98, v100, s[8:9]
	s_nop 0
	v_cndmask_b32_e32 v101, 0, v99, vcc
	v_cndmask_b32_e64 v107, v99, v101, s[8:9]
	v_pk_fma_f32 v[100:101], v[108:109], s[96:97], v[162:163] op_sel_hi:[1,0,0]
	v_cmp_lt_f32_e32 vcc, s33, v108
	v_exp_f32_e32 v99, v100
	v_exp_f32_e32 v100, v101
	v_cvt_pk_bf16_f32 v98, v106, v107
	v_cndmask_b32_e32 v101, 0, v99, vcc
	v_cmp_lt_f32_e32 vcc, s33, v109
	v_cndmask_b32_e64 v108, v99, v101, s[8:9]
	s_nop 0
	v_cndmask_b32_e32 v102, 0, v100, vcc
	v_cndmask_b32_e64 v109, v100, v102, s[8:9]
	v_pk_fma_f32 v[100:101], v[110:111], s[96:97], v[162:163] op_sel_hi:[1,0,0]
	v_cmp_lt_f32_e32 vcc, s33, v110
	v_exp_f32_e32 v100, v100
	v_exp_f32_e32 v101, v101
	v_cvt_pk_bf16_f32 v99, v108, v109
	v_cndmask_b32_e32 v102, 0, v100, vcc
	v_cmp_lt_f32_e32 vcc, s33, v111
	v_cndmask_b32_e64 v110, v100, v102, s[8:9]
	s_nop 0
	v_cndmask_b32_e32 v103, 0, v101, vcc
	v_cndmask_b32_e64 v111, v101, v103, s[8:9]
	v_pk_fma_f32 v[102:103], v[112:113], s[96:97], v[162:163] op_sel_hi:[1,0,0]
	v_cmp_lt_f32_e32 vcc, s33, v112
	v_exp_f32_e32 v101, v102
	v_exp_f32_e32 v102, v103
	v_cvt_pk_bf16_f32 v100, v110, v111
	v_cndmask_b32_e32 v103, 0, v101, vcc
	v_cmp_lt_f32_e32 vcc, s33, v113
	v_cndmask_b32_e64 v112, v101, v103, s[8:9]
	s_nop 0
	v_cndmask_b32_e32 v104, 0, v102, vcc
	v_cndmask_b32_e64 v113, v102, v104, s[8:9]
	s_nop 0
	v_cvt_pk_bf16_f32 v101, v112, v113
	s_waitcnt lgkmcnt(0)
	s_nop 0
	v_mfma_f32_32x32x16_bf16 v[82:97], v[240:243], v[98:101], v[82:97]
	s_nop 0
	s_waitcnt lgkmcnt(0)
	v_mfma_f32_32x32x16_bf16 v[66:81], v[244:247], v[98:101], v[66:81]
	v_add_f32_e64 v98, v106, v116
	v_add_f32_e64 v99, v107, v117
	v_add_f32_e64 v98, v108, v98
	v_add_f32_e64 v99, v109, v99
	v_add_f32_e64 v98, v110, v98
	v_add_f32_e64 v99, v111, v99
	v_pk_add_f32 v[98:99], v[112:113], v[98:99]
	s_nop 0
	v_add_f32_e32 v98, v98, v99
	ds_bpermute_b32 v99, v165, v98
	s_waitcnt lgkmcnt(0)
	v_add_f32_e32 v98, v98, v99
	v_add_f32_e32 v172, v172, v98
	s_branch .LBB0_456
.Lfast_win1:
	v_mul_f32_e32 v162, 0xbe38aa3b, v162
	v_pk_fma_f32 v[180:181], v[114:115], s[96:97], v[162:163] op_sel_hi:[1,0,0]
	v_exp_f32_e32 v188, v180
	v_exp_f32_e32 v189, v181
	v_pk_fma_f32 v[114:115], v[116:117], s[96:97], v[162:163] op_sel_hi:[1,0,0]
	v_exp_f32_e32 v190, v114
	v_exp_f32_e32 v191, v115
	v_cvt_pk_bf16_f32 v180, v188, v189
	v_pk_fma_f32 v[114:115], v[118:119], s[96:97], v[162:163] op_sel_hi:[1,0,0]
	v_exp_f32_e32 v192, v114
	v_exp_f32_e32 v193, v115
	v_cvt_pk_bf16_f32 v181, v190, v191
	v_pk_fma_f32 v[114:115], v[120:121], s[96:97], v[162:163] op_sel_hi:[1,0,0]
	v_exp_f32_e32 v120, v114
	v_exp_f32_e32 v121, v115
	v_cvt_pk_bf16_f32 v182, v192, v193
	v_cvt_pk_bf16_f32 v183, v120, v121
	s_waitcnt lgkmcnt(0)
	s_nop 0
	v_mfma_f32_32x32x16_bf16 v[82:97], v[216:219], v[180:183], v[82:97]
	s_waitcnt lgkmcnt(0)
	v_mfma_f32_32x32x16_bf16 v[66:81], v[220:223], v[180:183], v[66:81]
	v_add_f32_e64 v116, v188, 0
	v_add_f32_e64 v117, v189, 0
	v_add_f32_e64 v116, v190, v116
	v_add_f32_e64 v117, v191, v117
	v_add_f32_e64 v116, v192, v116
	v_add_f32_e64 v117, v193, v117
	v_pk_add_f32 v[180:181], v[120:121], v[116:117]
	v_pk_fma_f32 v[116:117], v[122:123], s[96:97], v[162:163] op_sel_hi:[1,0,0]
	v_exp_f32_e32 v182, v116
	v_exp_f32_e32 v183, v117
	v_pk_fma_f32 v[118:119], v[124:125], s[96:97], v[162:163] op_sel_hi:[1,0,0]
	v_exp_f32_e32 v124, v118
	v_exp_f32_e32 v125, v119
	v_cvt_pk_bf16_f32 v116, v182, v183
	v_pk_fma_f32 v[118:119], v[126:127], s[96:97], v[162:163] op_sel_hi:[1,0,0]
	v_exp_f32_e32 v126, v118
	v_exp_f32_e32 v127, v119
	v_cvt_pk_bf16_f32 v117, v124, v125
	v_pk_fma_f32 v[120:121], v[128:129], s[96:97], v[162:163] op_sel_hi:[1,0,0]
	v_exp_f32_e32 v128, v120
	v_exp_f32_e32 v129, v121
	v_cvt_pk_bf16_f32 v118, v126, v127
	v_cvt_pk_bf16_f32 v119, v128, v129
	s_nop 1
	v_mfma_f32_32x32x16_bf16 v[82:97], v[224:227], v[116:119], v[82:97]
	s_waitcnt lgkmcnt(0)
	v_mfma_f32_32x32x16_bf16 v[66:81], v[228:231], v[116:119], v[66:81]
	v_fma_f32 v118, v98, s96, v162
	v_fma_f32 v119, v99, s96, v162
	v_fma_f32 v120, v100, s96, v162
	v_fma_f32 v121, v101, s96, v162
	v_exp_f32_e32 v118, v118
	v_exp_f32_e32 v119, v119
	v_pk_add_f32 v[116:117], v[182:183], v[180:181]
	v_pk_add_f32 v[116:117], v[124:125], v[116:117]
	v_exp_f32_e32 v120, v120
	v_exp_f32_e32 v121, v121
	v_cvt_pk_bf16_f32 v98, v118, v119
	v_pk_add_f32 v[116:117], v[126:127], v[116:117]
	v_pk_add_f32 v[116:117], v[128:129], v[116:117]
	v_pk_fma_f32 v[100:101], v[102:103], s[96:97], v[162:163] op_sel_hi:[1,0,0]
	v_exp_f32_e32 v122, v100
	v_exp_f32_e32 v123, v101
	v_cvt_pk_bf16_f32 v99, v120, v121
	v_pk_fma_f32 v[102:103], v[104:105], s[96:97], v[162:163] op_sel_hi:[1,0,0]
	v_exp_f32_e32 v124, v102
	v_exp_f32_e32 v125, v103
	v_cvt_pk_bf16_f32 v100, v122, v123
	v_cvt_pk_bf16_f32 v101, v124, v125
	s_waitcnt lgkmcnt(0)
	s_nop 0
	v_mfma_f32_32x32x16_bf16 v[82:97], v[232:235], v[98:101], v[82:97]
	s_waitcnt lgkmcnt(0)
	v_mfma_f32_32x32x16_bf16 v[66:81], v[236:239], v[98:101], v[66:81]
	v_add_f32_e64 v98, v118, v116
	v_add_f32_e64 v99, v119, v117
	v_add_f32_e64 v98, v120, v98
	v_add_f32_e64 v99, v121, v99
	v_add_f32_e64 v98, v122, v98
	v_add_f32_e64 v99, v123, v99
	v_pk_add_f32 v[116:117], v[124:125], v[98:99]
	v_pk_fma_f32 v[98:99], v[106:107], s[96:97], v[162:163] op_sel_hi:[1,0,0]
	v_exp_f32_e32 v106, v98
	v_exp_f32_e32 v107, v99
	v_pk_fma_f32 v[100:101], v[108:109], s[96:97], v[162:163] op_sel_hi:[1,0,0]
	v_exp_f32_e32 v108, v100
	v_exp_f32_e32 v109, v101
	v_cvt_pk_bf16_f32 v98, v106, v107
	v_pk_fma_f32 v[100:101], v[110:111], s[96:97], v[162:163] op_sel_hi:[1,0,0]
	v_exp_f32_e32 v110, v100
	v_exp_f32_e32 v111, v101
	v_cvt_pk_bf16_f32 v99, v108, v109
	v_pk_fma_f32 v[102:103], v[112:113], s[96:97], v[162:163] op_sel_hi:[1,0,0]
	v_exp_f32_e32 v112, v102
	v_exp_f32_e32 v113, v103
	v_cvt_pk_bf16_f32 v100, v110, v111
	v_cvt_pk_bf16_f32 v101, v112, v113
	s_waitcnt lgkmcnt(0)
	s_nop 0
	v_mfma_f32_32x32x16_bf16 v[82:97], v[240:243], v[98:101], v[82:97]
	s_waitcnt lgkmcnt(0)
	v_mfma_f32_32x32x16_bf16 v[66:81], v[244:247], v[98:101], v[66:81]
	v_add_f32_e64 v98, v106, v116
	v_add_f32_e64 v99, v107, v117
	v_add_f32_e64 v98, v108, v98
	v_add_f32_e64 v99, v109, v99
	v_add_f32_e64 v98, v110, v98
	v_add_f32_e64 v99, v111, v99
	v_pk_add_f32 v[98:99], v[112:113], v[98:99]
	v_add_f32_e32 v98, v98, v99
	ds_bpermute_b32 v99, v165, v98
	s_waitcnt lgkmcnt(0)
	v_add_f32_e32 v98, v98, v99
	v_add_f32_e32 v172, v172, v98

; #define MFMA(a, b, c) __builtin_amdgcn_mfma_f32_32x32x16_bf16((a), (b), (c), 0, 0, 0)
; template <int DK, int DV, int MODE>
; DI void fa_qk(f32x16 (&S)[2], const bf16x8 (&q)[DK / 16], const char* base, int lr, int lh) {
;   using C = FA<DK, DV>;
; #pragma unroll
;   for (int ks = 0; ks < 2; ++ks) {
; #pragma unroll
;     for (int kk = 0; kk < DK / 16; ++kk) {
;       const bf16x8 kf = *(const bf16x8*)(base + (ks * 32 + lr) * C::KSTR + (kk * 2 + lh) * 16);
;       if (kk == 0) {
; #pragma unroll
;         for (int i = 0; i < 16; ++i) S[ks][i] = 0.f;
;       }
;       S[ks] = MFMA(kf, q[kk], S[ks]);
;     }
;   }
; }
;     ...
;   if (MODE != 0) need_mask = (kb * 64 + 63 > wave_qmax - 31);
;   if (MODE == 2) selbit = (sel >> kb) & 1ull;
;   if (MODE == 3) need_mask = need_mask || (kb * 64 <= wave_qmax - 512);
.LBB0_467:
	s_add_i32 s6, s38, s17
	s_add_i32 s1, s6, 0xdc0
	s_cmp_gt_u32 s1, s20
	s_cbranch_scc1 .LBB0_456
	s_add_i32 s0, s0, 0
	v_add3_u32 v162, s0, v174, v173
	ds_read_b128 v[216:219], v162
	ds_read_b128 v[220:223], v162 offset:32
	ds_read_b128 v[224:227], v162 offset:64
	ds_read_b128 v[228:231], v162 offset:96
	ds_read_b128 v[232:235], v162 offset:4608
	ds_read_b128 v[236:239], v162 offset:4640
	ds_read_b128 v[240:243], v162 offset:4672
	ds_read_b128 v[244:247], v162 offset:4704
	s_addk_i32 s6, 0xddf
	s_cmp_gt_u32 s6, s45
	s_cselect_b64 s[8:9], -1, 0
	s_cmp_le_i32 s1, s16
	s_cselect_b64 s[10:11], -1, 0
	s_or_b64 s[8:9], s[8:9], s[10:11]
	s_andn2_b64 vcc, exec, s[8:9]
	s_waitcnt lgkmcnt(7)
	v_mfma_f32_32x32x16_bf16 v[114:129], v[216:219], v[138:141], 0
	s_waitcnt lgkmcnt(6)
	v_mfma_f32_32x32x16_bf16 v[114:129], v[220:223], v[130:133], v[114:129]
	s_waitcnt lgkmcnt(5)
	v_mfma_f32_32x32x16_bf16 v[114:129], v[224:227], v[134:137], v[114:129]
	s_waitcnt lgkmcnt(4)
	v_mfma_f32_32x32x16_bf16 v[114:129], v[228:231], v[142:145], v[114:129]
	s_waitcnt lgkmcnt(3)
	v_mfma_f32_32x32x16_bf16 v[98:113], v[232:235], v[138:141], 0
	s_waitcnt lgkmcnt(2)
	v_mfma_f32_32x32x16_bf16 v[98:113], v[236:239], v[130:133], v[98:113]
	s_waitcnt lgkmcnt(1)
	v_mfma_f32_32x32x16_bf16 v[98:113], v[240:243], v[134:137], v[98:113]
	s_waitcnt lgkmcnt(0)
	v_mfma_f32_32x32x16_bf16 v[98:113], v[244:247], v[142:145], v[98:113]
	v_add3_u32 v247, s0, v176, v174
	v_add_u32_e32 v243, 0x2000, v247
	v_add_u32_e32 v247, 0x3000, v247
	ds_read2_b64 v[216:219], v243 offset0:128 offset1:130
	ds_read2_b64 v[220:223], v247 offset0:192 offset1:194
	ds_read2_b64 v[224:227], v243 offset0:132 offset1:134
	ds_read2_b64 v[228:231], v247 offset0:196 offset1:198
	ds_read2_b64 v[232:235], v243 offset0:136 offset1:138
	ds_read2_b64 v[236:239], v247 offset0:200 offset1:202
	ds_read2_b64 v[240:243], v243 offset0:140 offset1:142
	ds_read2_b64 v[244:247], v247 offset0:204 offset1:206
	s_cbranch_vccnz .LBB0_470
; DI int crow(int i, int h) { return (i & 3) + 8 * (i >> 2) + 4 * h; }
;     ...
;   if (need_mask) {
; #pragma unroll
;     for (int ks = 0; ks < 2; ++ks)
; #pragma unroll
;       for (int i = 0; i < 16; ++i) {
;         const int key = kb * 64 + ks * 32 + crow(i, lh);
;         bool valid = key <= qpos;
;         if (MODE == 2) valid = valid && selbit;
;         if (MODE == 3) valid = valid && (qpos - key < 512);
;         S[ks][i] = valid ? S[ks][i] : -1e30f;
;       }
	v_add_u32_e32 v162, s17, v177
	v_add_u32_e32 v179, 0xdc0, v162
	v_cmp_le_i32_e32 vcc, v179, v148
	v_cmp_gt_i32_e64 s[10:11], v179, v175
	s_and_b64 vcc, vcc, s[10:11]
	v_cndmask_b32_e32 v114, v208, v114, vcc
	v_cmp_lt_i32_e32 vcc, v179, v148
	v_cmp_ge_i32_e64 s[10:11], v179, v175
	s_and_b64 vcc, vcc, s[10:11]
	v_add_u32_e32 v179, 0xdc2, v162
	v_cndmask_b32_e32 v115, v208, v115, vcc
	v_cmp_le_i32_e32 vcc, v179, v148
	v_cmp_gt_i32_e64 s[10:11], v179, v175
	s_and_b64 vcc, vcc, s[10:11]
	v_add_u32_e32 v179, 0xdc3, v162
	v_cndmask_b32_e32 v116, v208, v116, vcc
	v_cmp_le_i32_e32 vcc, v179, v148
	v_cmp_gt_i32_e64 s[10:11], v179, v175
	s_and_b64 vcc, vcc, s[10:11]
	v_add_u32_e32 v179, 0xdc8, v162
	v_cndmask_b32_e32 v117, v208, v117, vcc
	v_cmp_le_i32_e32 vcc, v179, v148
	v_cmp_gt_i32_e64 s[10:11], v179, v175
	s_and_b64 vcc, vcc, s[10:11]
	v_add_u32_e32 v179, 0xdc9, v162
	v_cndmask_b32_e32 v118, v208, v118, vcc
	v_cmp_le_i32_e32 vcc, v179, v148
	v_cmp_gt_i32_e64 s[10:11], v179, v175
	s_and_b64 vcc, vcc, s[10:11]
	v_add_u32_e32 v179, 0xdca, v162
	v_cndmask_b32_e32 v119, v208, v119, vcc
	v_cmp_le_i32_e32 vcc, v179, v148
	v_cmp_gt_i32_e64 s[10:11], v179, v175
	s_and_b64 vcc, vcc, s[10:11]
	v_add_u32_e32 v179, 0xdcb, v162
	v_cndmask_b32_e32 v120, v208, v120, vcc
	v_cmp_le_i32_e32 vcc, v179, v148
	v_cmp_gt_i32_e64 s[10:11], v179, v175
	s_and_b64 vcc, vcc, s[10:11]
	v_add_u32_e32 v179, 0xdd0, v162
	v_cndmask_b32_e32 v121, v208, v121, vcc
	v_cmp_le_i32_e32 vcc, v179, v148
	v_cmp_gt_i32_e64 s[10:11], v179, v175
	s_and_b64 vcc, vcc, s[10:11]
	v_add_u32_e32 v179, 0xdd1, v162
	v_cndmask_b32_e32 v122, v208, v122, vcc
	v_cmp_le_i32_e32 vcc, v179, v148
	v_cmp_gt_i32_e64 s[10:11], v179, v175
	s_and_b64 vcc, vcc, s[10:11]
	v_add_u32_e32 v179, 0xdd2, v162
	v_cndmask_b32_e32 v123, v208, v123, vcc
	v_cmp_le_i32_e32 vcc, v179, v148
	v_cmp_gt_i32_e64 s[10:11], v179, v175
	s_and_b64 vcc, vcc, s[10:11]
	v_add_u32_e32 v179, 0xdd3, v162
	v_cndmask_b32_e32 v124, v208, v124, vcc
	v_cmp_le_i32_e32 vcc, v179, v148
	v_cmp_gt_i32_e64 s[10:11], v179, v175
	s_and_b64 vcc, vcc, s[10:11]
	v_add_u32_e32 v179, 0xdd8, v162
	v_cndmask_b32_e32 v125, v208, v125, vcc
	v_cmp_le_i32_e32 vcc, v179, v148
	v_cmp_gt_i32_e64 s[10:11], v179, v175
	s_and_b64 vcc, vcc, s[10:11]
	v_add_u32_e32 v179, 0xdd9, v162
	v_cndmask_b32_e32 v126, v208, v126, vcc
	v_cmp_le_i32_e32 vcc, v179, v148
	v_cmp_gt_i32_e64 s[10:11], v179, v175
	s_and_b64 vcc, vcc, s[10:11]
	v_add_u32_e32 v179, 0xdda, v162
	v_cndmask_b32_e32 v127, v208, v127, vcc
	v_cmp_le_i32_e32 vcc, v179, v148
	v_cmp_gt_i32_e64 s[10:11], v179, v175
	s_and_b64 vcc, vcc, s[10:11]
	v_add_u32_e32 v179, 0xddb, v162
	v_cndmask_b32_e32 v128, v208, v128, vcc
	v_cmp_le_i32_e32 vcc, v179, v148
	v_cmp_gt_i32_e64 s[10:11], v179, v175
	s_and_b64 vcc, vcc, s[10:11]
	v_add_u32_e32 v179, 0xde0, v162
	v_cndmask_b32_e32 v129, v208, v129, vcc
	v_cmp_le_i32_e32 vcc, v179, v148
	v_cmp_gt_i32_e64 s[10:11], v179, v175
	s_and_b64 vcc, vcc, s[10:11]
	v_add_u32_e32 v179, 0xde1, v162
	v_cndmask_b32_e32 v98, v208, v98, vcc
	v_cmp_le_i32_e32 vcc, v179, v148
	v_cmp_gt_i32_e64 s[10:11], v179, v175
	s_and_b64 vcc, vcc, s[10:11]
	v_add_u32_e32 v179, 0xde2, v162
	v_cndmask_b32_e32 v99, v208, v99, vcc
	v_cmp_le_i32_e32 vcc, v179, v148
	v_cmp_gt_i32_e64 s[10:11], v179, v175
	s_and_b64 vcc, vcc, s[10:11]
	v_add_u32_e32 v179, 0xde3, v162
	v_cndmask_b32_e32 v100, v208, v100, vcc
	v_cmp_le_i32_e32 vcc, v179, v148
	v_cmp_gt_i32_e64 s[10:11], v179, v175
	s_and_b64 vcc, vcc, s[10:11]
	v_add_u32_e32 v179, 0xde8, v162
	v_cndmask_b32_e32 v101, v208, v101, vcc
	v_cmp_le_i32_e32 vcc, v179, v148
	v_cmp_gt_i32_e64 s[10:11], v179, v175
	s_and_b64 vcc, vcc, s[10:11]
	v_add_u32_e32 v179, 0xde9, v162
	v_cndmask_b32_e32 v102, v208, v102, vcc
	v_cmp_le_i32_e32 vcc, v179, v148
	v_cmp_gt_i32_e64 s[10:11], v179, v175
	s_and_b64 vcc, vcc, s[10:11]
	v_add_u32_e32 v179, 0xdea, v162
	v_cndmask_b32_e32 v103, v208, v103, vcc
	v_cmp_le_i32_e32 vcc, v179, v148
	v_cmp_gt_i32_e64 s[10:11], v179, v175
	s_and_b64 vcc, vcc, s[10:11]
	v_add_u32_e32 v179, 0xdeb, v162
	v_cndmask_b32_e32 v104, v208, v104, vcc
	v_cmp_le_i32_e32 vcc, v179, v148
	v_cmp_gt_i32_e64 s[10:11], v179, v175
	s_and_b64 vcc, vcc, s[10:11]
	v_add_u32_e32 v179, 0xdf0, v162
	v_cndmask_b32_e32 v105, v208, v105, vcc
	v_cmp_le_i32_e32 vcc, v179, v148
	v_cmp_gt_i32_e64 s[10:11], v179, v175
	s_and_b64 vcc, vcc, s[10:11]
	v_add_u32_e32 v179, 0xdf1, v162
	v_cndmask_b32_e32 v106, v208, v106, vcc
	v_cmp_le_i32_e32 vcc, v179, v148
	v_cmp_gt_i32_e64 s[10:11], v179, v175
	s_and_b64 vcc, vcc, s[10:11]
	v_add_u32_e32 v179, 0xdf2, v162
	v_cndmask_b32_e32 v107, v208, v107, vcc
	v_cmp_le_i32_e32 vcc, v179, v148
	v_cmp_gt_i32_e64 s[10:11], v179, v175
	s_and_b64 vcc, vcc, s[10:11]
	v_add_u32_e32 v179, 0xdf3, v162
	v_cndmask_b32_e32 v108, v208, v108, vcc
	v_cmp_le_i32_e32 vcc, v179, v148
	v_cmp_gt_i32_e64 s[10:11], v179, v175
	s_and_b64 vcc, vcc, s[10:11]
	v_add_u32_e32 v179, 0xdf8, v162
	v_cndmask_b32_e32 v109, v208, v109, vcc
	v_cmp_le_i32_e32 vcc, v179, v148
	v_cmp_gt_i32_e64 s[10:11], v179, v175
	s_and_b64 vcc, vcc, s[10:11]
	v_add_u32_e32 v179, 0xdf9, v162
	v_cndmask_b32_e32 v110, v208, v110, vcc
	v_cmp_le_i32_e32 vcc, v179, v148
	v_cmp_gt_i32_e64 s[10:11], v179, v175
	s_and_b64 vcc, vcc, s[10:11]
	v_add_u32_e32 v179, 0xdfa, v162
	v_cndmask_b32_e32 v111, v208, v111, vcc
	v_cmp_le_i32_e32 vcc, v179, v148
	v_cmp_gt_i32_e64 s[10:11], v179, v175
	s_and_b64 vcc, vcc, s[10:11]
	v_add_u32_e32 v162, 0xdfb, v162
	v_cndmask_b32_e32 v112, v208, v112, vcc
	v_cmp_le_i32_e32 vcc, v162, v148
	v_cmp_gt_i32_e64 s[10:11], v162, v175
	s_and_b64 vcc, vcc, s[10:11]
	v_cndmask_b32_e32 v113, v208, v113, vcc

; #define MFMA(a, b, c) __builtin_amdgcn_mfma_f32_32x32x16_bf16((a), (b), (c), 0, 0, 0)
;     ...
;   float mc = m * c2;
;   if (MODE == 2) mc = selbit ? mc : 1e30f;
;   const f32x2v c2v = {c2, c2}, mcv = {-mc, -mc};
;   f32x2v rs2 = {0.f, 0.f};
; #pragma unroll
;   for (int ks = 0; ks < 2; ++ks)
; #pragma unroll
;     for (int st = 0; st < 2; ++st) {
;       union { unsigned u[4]; bf16x8 v; } pf;
; #pragma unroll
;       for (int j = 0; j < 4; ++j) {
;         const int i0 = 8 * st + 2 * j;
;         f32x2v t = {S[ks][i0], S[ks][i0 + 1]};
;         t = __builtin_elementwise_fma(t, c2v, mcv);
;         f32x2v pv;
;         if (variant == 1) { pv = t; } else {
;         pv.x = __builtin_amdgcn_exp2f(t.x);
;         pv.y = __builtin_amdgcn_exp2f(t.y);
;         }
;         if (MODE != 0) {
;           if (need_mask) {
;             pv.x = (S[ks][i0] > -1e29f) ? pv.x : 0.f;
;             pv.y = (S[ks][i0 + 1] > -1e29f) ? pv.y : 0.f;
;           }
;         }
;         rs2 += pv;
;         pf.u[j] = __builtin_bit_cast(unsigned, __builtin_convertvector(pv, hwbf16x2));
;       }
; #pragma unroll
;       for (int d = 0; d < DV / 32; ++d) {
;         const char* vp = base + C::KBYTES + (d * 32 + lr) * C::VSTR + (ks * 32 + 16 * st + 4 * lh) * 2;
;         const s16x4 lo = *(const s16x4*)vp, hi = *(const s16x4*)(vp + 16);
;         const bf16x8 vf = __builtin_shufflevector(lo, hi, 0, 1, 2, 3, 4, 5, 6, 7);
;         O[d] = MFMA(vf, pf.v, O[d]);
;       }
;     }
;   float rs = rs2.x + rs2.y;
;   rs += __shfl_xor(rs, 32);
;   l += rs;
.LBB0_549:
	s_cmp_eq_u64 s[8:9], 0
	s_cbranch_scc1 .Lfast_sel2
	v_mul_f32_e32 v14, 0xbe38aa3b, v14
	v_cndmask_b32_e64 v14, v208, v14, s[10:11]
	v_pk_fma_f32 v[120:121], v[96:97], s[96:97], v[14:15] op_sel_hi:[1,0,0]
	v_cmp_lt_f32_e32 vcc, s33, v96
	v_exp_f32_e32 v119, v120
	v_exp_f32_e32 v120, v121
	v_cndmask_b32_e32 v96, 0, v119, vcc
	v_cmp_lt_f32_e32 vcc, s33, v97
	v_cndmask_b32_e64 v128, v119, v96, s[8:9]
	s_nop 0
	v_cndmask_b32_e32 v97, 0, v120, vcc
	v_cndmask_b32_e64 v129, v120, v97, s[8:9]
	v_pk_fma_f32 v[96:97], v[98:99], s[96:97], v[14:15] op_sel_hi:[1,0,0]
	v_cmp_lt_f32_e32 vcc, s33, v98
	v_exp_f32_e32 v96, v96
	v_exp_f32_e32 v97, v97
	v_cvt_pk_bf16_f32 v120, v128, v129
	v_cndmask_b32_e32 v98, 0, v96, vcc
	v_cmp_lt_f32_e32 vcc, s33, v99
	v_cndmask_b32_e64 v130, v96, v98, s[8:9]
	s_nop 0
	v_cndmask_b32_e32 v99, 0, v97, vcc
	v_cndmask_b32_e64 v131, v97, v99, s[8:9]
	v_pk_fma_f32 v[96:97], v[100:101], s[96:97], v[14:15] op_sel_hi:[1,0,0]
	v_cmp_lt_f32_e32 vcc, s33, v100
	v_exp_f32_e32 v96, v96
	v_exp_f32_e32 v97, v97
	v_cvt_pk_bf16_f32 v121, v130, v131
	v_cndmask_b32_e32 v98, 0, v96, vcc
	v_cmp_lt_f32_e32 vcc, s33, v101
	v_cndmask_b32_e64 v132, v96, v98, s[8:9]
	s_nop 0
	v_cndmask_b32_e32 v99, 0, v97, vcc
	v_cndmask_b32_e64 v133, v97, v99, s[8:9]
	v_pk_fma_f32 v[96:97], v[102:103], s[96:97], v[14:15] op_sel_hi:[1,0,0]
	v_cmp_lt_f32_e32 vcc, s33, v102
	v_exp_f32_e32 v96, v96
	v_exp_f32_e32 v97, v97
	v_cvt_pk_bf16_f32 v122, v132, v133
	v_cndmask_b32_e32 v98, 0, v96, vcc
	v_cmp_lt_f32_e32 vcc, s33, v103
	v_cndmask_b32_e64 v102, v96, v98, s[8:9]
	s_nop 0
	v_cndmask_b32_e32 v99, 0, v97, vcc
	v_cndmask_b32_e64 v103, v97, v99, s[8:9]
	s_nop 0
	s_nop 0
	s_nop 0
	s_nop 0
	v_cvt_pk_bf16_f32 v123, v102, v103
	s_nop 0
	v_cmp_lt_f32_e32 vcc, s33, v104
	s_waitcnt lgkmcnt(0)
	v_mfma_f32_32x32x16_bf16 v[64:79], v[216:219], v[120:123], v[64:79]
	s_nop 0
	s_waitcnt lgkmcnt(0)
	v_mfma_f32_32x32x16_bf16 v[48:63], v[220:223], v[120:123], v[48:63]
	v_add_f32_e64 v98, v128, 0
	v_add_f32_e64 v99, v129, 0
	v_add_f32_e64 v98, v130, v98
	v_add_f32_e64 v99, v131, v99
	v_add_f32_e64 v98, v132, v98
	v_add_f32_e64 v99, v133, v99
	v_pk_add_f32 v[120:121], v[102:103], v[98:99]
	v_pk_fma_f32 v[98:99], v[104:105], s[96:97], v[14:15] op_sel_hi:[1,0,0]
	s_nop 0
	v_exp_f32_e32 v98, v98
	v_exp_f32_e32 v99, v99
	v_cndmask_b32_e32 v100, 0, v98, vcc
	v_cmp_lt_f32_e32 vcc, s33, v105
	v_cndmask_b32_e64 v122, v98, v100, s[8:9]
	s_nop 0
	v_cndmask_b32_e32 v101, 0, v99, vcc
	v_cndmask_b32_e64 v123, v99, v101, s[8:9]
	v_pk_fma_f32 v[100:101], v[106:107], s[96:97], v[14:15] op_sel_hi:[1,0,0]
	v_cmp_lt_f32_e32 vcc, s33, v106
	v_exp_f32_e32 v99, v100
	v_exp_f32_e32 v100, v101
	v_cvt_pk_bf16_f32 v98, v122, v123
	v_cndmask_b32_e32 v101, 0, v99, vcc
	v_cmp_lt_f32_e32 vcc, s33, v107
	v_cndmask_b32_e64 v106, v99, v101, s[8:9]
	s_nop 0
	v_cndmask_b32_e32 v102, 0, v100, vcc
	v_cndmask_b32_e64 v107, v100, v102, s[8:9]
	v_pk_fma_f32 v[100:101], v[108:109], s[96:97], v[14:15] op_sel_hi:[1,0,0]
	v_cmp_lt_f32_e32 vcc, s33, v108
	v_exp_f32_e32 v100, v100
	v_exp_f32_e32 v101, v101
	v_cvt_pk_bf16_f32 v99, v106, v107
	v_cndmask_b32_e32 v102, 0, v100, vcc
	v_cmp_lt_f32_e32 vcc, s33, v109
	v_cndmask_b32_e64 v108, v100, v102, s[8:9]
	s_nop 0
	v_cndmask_b32_e32 v103, 0, v101, vcc
	v_cndmask_b32_e64 v109, v101, v103, s[8:9]
	v_pk_fma_f32 v[102:103], v[110:111], s[96:97], v[14:15] op_sel_hi:[1,0,0]
	v_cmp_lt_f32_e32 vcc, s33, v110
	v_exp_f32_e32 v101, v102
	v_exp_f32_e32 v102, v103
	v_cvt_pk_bf16_f32 v100, v108, v109
	v_cndmask_b32_e32 v103, 0, v101, vcc
	v_cmp_lt_f32_e32 vcc, s33, v111
	v_cndmask_b32_e64 v110, v101, v103, s[8:9]
	s_nop 0
	v_cndmask_b32_e32 v104, 0, v102, vcc
	v_cndmask_b32_e64 v111, v102, v104, s[8:9]
	s_nop 0
	v_cvt_pk_bf16_f32 v101, v110, v111
	v_cmp_lt_f32_e32 vcc, s33, v80
	s_nop 0
	v_mfma_f32_32x32x16_bf16 v[64:79], v[224:227], v[98:101], v[64:79]
	s_waitcnt lgkmcnt(0)
	v_mfma_f32_32x32x16_bf16 v[48:63], v[228:231], v[98:101], v[48:63]
	v_fma_f32 v100, v80, s96, v14
	v_fma_f32 v101, v81, s96, v14
	v_fma_f32 v102, v82, s96, v14
	v_fma_f32 v103, v83, s96, v14
	v_exp_f32_e32 v100, v100
	v_exp_f32_e32 v101, v101
	v_pk_add_f32 v[98:99], v[122:123], v[120:121]
	v_cndmask_b32_e32 v80, 0, v100, vcc
	v_cmp_lt_f32_e32 vcc, s33, v81
	v_pk_add_f32 v[98:99], v[106:107], v[98:99]
	v_cndmask_b32_e64 v100, v100, v80, s[8:9]
	v_cndmask_b32_e32 v81, 0, v101, vcc
	v_cndmask_b32_e64 v101, v101, v81, s[8:9]
	v_exp_f32_e32 v81, v102
	v_exp_f32_e32 v102, v103
	v_cmp_lt_f32_e32 vcc, s33, v82
	v_cvt_pk_bf16_f32 v80, v100, v101
	v_pk_add_f32 v[98:99], v[108:109], v[98:99]
	v_cndmask_b32_e32 v82, 0, v81, vcc
	v_cmp_lt_f32_e32 vcc, s33, v83
	v_pk_add_f32 v[98:99], v[110:111], v[98:99]
	s_nop 0
	v_cndmask_b32_e32 v83, 0, v102, vcc
	v_cndmask_b32_e64 v103, v102, v83, s[8:9]
	v_cndmask_b32_e64 v102, v81, v82, s[8:9]
	v_pk_fma_f32 v[82:83], v[84:85], s[96:97], v[14:15] op_sel_hi:[1,0,0]
	v_cmp_lt_f32_e32 vcc, s33, v84
	v_exp_f32_e32 v82, v82
	v_exp_f32_e32 v83, v83
	v_cvt_pk_bf16_f32 v81, v102, v103
	v_cndmask_b32_e32 v84, 0, v82, vcc
	v_cmp_lt_f32_e32 vcc, s33, v85
	v_cndmask_b32_e64 v104, v82, v84, s[8:9]
	s_nop 0
	v_cndmask_b32_e32 v85, 0, v83, vcc
	v_cndmask_b32_e64 v105, v83, v85, s[8:9]
	v_pk_fma_f32 v[84:85], v[86:87], s[96:97], v[14:15] op_sel_hi:[1,0,0]
	v_cmp_lt_f32_e32 vcc, s33, v86
	v_exp_f32_e32 v83, v84
	v_exp_f32_e32 v84, v85
	v_cvt_pk_bf16_f32 v82, v104, v105
	v_cndmask_b32_e32 v85, 0, v83, vcc
	v_cmp_lt_f32_e32 vcc, s33, v87
	v_cndmask_b32_e64 v106, v83, v85, s[8:9]
	s_nop 0
	v_cndmask_b32_e32 v86, 0, v84, vcc
	v_cndmask_b32_e64 v107, v84, v86, s[8:9]
	s_nop 0
	v_cvt_pk_bf16_f32 v83, v106, v107
	v_cmp_lt_f32_e32 vcc, s33, v88
	s_waitcnt lgkmcnt(0)
; #define MFMA(a, b, c) __builtin_amdgcn_mfma_f32_32x32x16_bf16((a), (b), (c), 0, 0, 0)
;     ...
;   for (int ks = 0; ks < 2; ++ks)
; #pragma unroll
;     for (int st = 0; st < 2; ++st) {
;       union { unsigned u[4]; bf16x8 v; } pf;
; #pragma unroll
;       for (int j = 0; j < 4; ++j) {
;         const int i0 = 8 * st + 2 * j;
;         f32x2v t = {S[ks][i0], S[ks][i0 + 1]};
;         t = __builtin_elementwise_fma(t, c2v, mcv);
;         f32x2v pv;
;         if (variant == 1) { pv = t; } else {
;         pv.x = __builtin_amdgcn_exp2f(t.x);
;         pv.y = __builtin_amdgcn_exp2f(t.y);
;         }
;         if (MODE != 0) {
;           if (need_mask) {
;             pv.x = (S[ks][i0] > -1e29f) ? pv.x : 0.f;
;             pv.y = (S[ks][i0 + 1] > -1e29f) ? pv.y : 0.f;
;           }
;         }
;         rs2 += pv;
;         pf.u[j] = __builtin_bit_cast(unsigned, __builtin_convertvector(pv, hwbf16x2));
;       }
; #pragma unroll
;       for (int d = 0; d < DV / 32; ++d) {
;         const char* vp = base + C::KBYTES + (d * 32 + lr) * C::VSTR + (ks * 32 + 16 * st + 4 * lh) * 2;
;         const s16x4 lo = *(const s16x4*)vp, hi = *(const s16x4*)(vp + 16);
;         const bf16x8 vf = __builtin_shufflevector(lo, hi, 0, 1, 2, 3, 4, 5, 6, 7);
;         O[d] = MFMA(vf, pf.v, O[d]);
;       }
;     }
;   float rs = rs2.x + rs2.y;
;   rs += __shfl_xor(rs, 32);
;   l += rs;
	v_mfma_f32_32x32x16_bf16 v[64:79], v[232:235], v[80:83], v[64:79]
	s_nop 0
	s_waitcnt lgkmcnt(0)
	v_mfma_f32_32x32x16_bf16 v[48:63], v[236:239], v[80:83], v[48:63]
	v_add_f32_e64 v80, v100, v98
	v_add_f32_e64 v81, v101, v99
	v_add_f32_e64 v80, v102, v80
	v_add_f32_e64 v81, v103, v81
	v_add_f32_e64 v80, v104, v80
	v_add_f32_e64 v81, v105, v81
	v_pk_add_f32 v[98:99], v[106:107], v[80:81]
	v_pk_fma_f32 v[80:81], v[88:89], s[96:97], v[14:15] op_sel_hi:[1,0,0]
	s_nop 0
	v_exp_f32_e32 v80, v80
	v_exp_f32_e32 v81, v81
	v_cndmask_b32_e32 v82, 0, v80, vcc
	v_cmp_lt_f32_e32 vcc, s33, v89
	v_cndmask_b32_e64 v88, v80, v82, s[8:9]
	s_nop 0
	v_cndmask_b32_e32 v83, 0, v81, vcc
	v_cndmask_b32_e64 v89, v81, v83, s[8:9]
	v_pk_fma_f32 v[82:83], v[90:91], s[96:97], v[14:15] op_sel_hi:[1,0,0]
	v_cmp_lt_f32_e32 vcc, s33, v90
	v_exp_f32_e32 v81, v82
	v_exp_f32_e32 v82, v83
	v_cvt_pk_bf16_f32 v80, v88, v89
	v_cndmask_b32_e32 v83, 0, v81, vcc
	v_cmp_lt_f32_e32 vcc, s33, v91
	v_cndmask_b32_e64 v90, v81, v83, s[8:9]
	s_nop 0
	v_cndmask_b32_e32 v84, 0, v82, vcc
	v_cndmask_b32_e64 v91, v82, v84, s[8:9]
	v_pk_fma_f32 v[82:83], v[92:93], s[96:97], v[14:15] op_sel_hi:[1,0,0]
	v_cmp_lt_f32_e32 vcc, s33, v92
	v_exp_f32_e32 v82, v82
	v_exp_f32_e32 v83, v83
	v_cvt_pk_bf16_f32 v81, v90, v91
	v_cndmask_b32_e32 v84, 0, v82, vcc
	v_cmp_lt_f32_e32 vcc, s33, v93
	v_cndmask_b32_e64 v92, v82, v84, s[8:9]
	s_nop 0
	v_cndmask_b32_e32 v85, 0, v83, vcc
	v_cndmask_b32_e64 v93, v83, v85, s[8:9]
	v_pk_fma_f32 v[84:85], v[94:95], s[96:97], v[14:15] op_sel_hi:[1,0,0]
	v_cmp_lt_f32_e32 vcc, s33, v94
	v_exp_f32_e32 v14, v84
	v_exp_f32_e32 v83, v85
	v_cvt_pk_bf16_f32 v82, v92, v93
	v_cndmask_b32_e32 v84, 0, v14, vcc
	v_cmp_lt_f32_e32 vcc, s33, v95
	v_cndmask_b32_e64 v94, v14, v84, s[8:9]
	s_nop 0
	v_cndmask_b32_e32 v85, 0, v83, vcc
	v_cndmask_b32_e64 v95, v83, v85, s[8:9]
	s_nop 0
	v_cvt_pk_bf16_f32 v83, v94, v95
	s_waitcnt lgkmcnt(0)
	s_nop 0
	v_mfma_f32_32x32x16_bf16 v[64:79], v[240:243], v[80:83], v[64:79]
	s_nop 0
	s_waitcnt lgkmcnt(0)
	v_mfma_f32_32x32x16_bf16 v[48:63], v[244:247], v[80:83], v[48:63]
	v_add_f32_e64 v80, v88, v98
	v_add_f32_e64 v81, v89, v99
	v_add_f32_e64 v80, v90, v80
	v_add_f32_e64 v81, v91, v81
	v_add_f32_e64 v80, v92, v80
	v_add_f32_e64 v81, v93, v81
	v_pk_add_f32 v[80:81], v[94:95], v[80:81]
	s_nop 0
	v_add_f32_e32 v14, v80, v81
	ds_bpermute_b32 v80, v165, v14
	s_waitcnt lgkmcnt(0)
	v_add_f32_e32 v14, v14, v80
	v_add_f32_e32 v168, v168, v14
	s_branch .LBB0_550
.Lfast_sel2:
	v_mul_f32_e32 v14, 0xbe38aa3b, v14
	v_cndmask_b32_e64 v14, v208, v14, s[10:11]
	v_pk_fma_f32 v[120:121], v[96:97], s[96:97], v[14:15] op_sel_hi:[1,0,0]
	v_exp_f32_e32 v128, v120
	v_exp_f32_e32 v129, v121
	v_pk_fma_f32 v[96:97], v[98:99], s[96:97], v[14:15] op_sel_hi:[1,0,0]
	v_exp_f32_e32 v130, v96
	v_exp_f32_e32 v131, v97
	v_cvt_pk_bf16_f32 v120, v128, v129
	v_pk_fma_f32 v[96:97], v[100:101], s[96:97], v[14:15] op_sel_hi:[1,0,0]
	v_exp_f32_e32 v132, v96
	v_exp_f32_e32 v133, v97
	v_cvt_pk_bf16_f32 v121, v130, v131
	v_pk_fma_f32 v[96:97], v[102:103], s[96:97], v[14:15] op_sel_hi:[1,0,0]
	v_exp_f32_e32 v102, v96
	v_exp_f32_e32 v103, v97
	v_cvt_pk_bf16_f32 v122, v132, v133
	v_cvt_pk_bf16_f32 v123, v102, v103
	s_waitcnt lgkmcnt(0)
	s_nop 0
	v_mfma_f32_32x32x16_bf16 v[64:79], v[216:219], v[120:123], v[64:79]
	s_waitcnt lgkmcnt(0)
	v_mfma_f32_32x32x16_bf16 v[48:63], v[220:223], v[120:123], v[48:63]
	v_add_f32_e64 v98, v128, 0
	v_add_f32_e64 v99, v129, 0
	v_add_f32_e64 v98, v130, v98
	v_add_f32_e64 v99, v131, v99
	v_add_f32_e64 v98, v132, v98
	v_add_f32_e64 v99, v133, v99
	v_pk_add_f32 v[120:121], v[102:103], v[98:99]
	v_pk_fma_f32 v[98:99], v[104:105], s[96:97], v[14:15] op_sel_hi:[1,0,0]
	v_exp_f32_e32 v122, v98
	v_exp_f32_e32 v123, v99
	v_pk_fma_f32 v[100:101], v[106:107], s[96:97], v[14:15] op_sel_hi:[1,0,0]
	v_exp_f32_e32 v106, v100
	v_exp_f32_e32 v107, v101
	v_cvt_pk_bf16_f32 v98, v122, v123
	v_pk_fma_f32 v[100:101], v[108:109], s[96:97], v[14:15] op_sel_hi:[1,0,0]
	v_exp_f32_e32 v108, v100
	v_exp_f32_e32 v109, v101
	v_cvt_pk_bf16_f32 v99, v106, v107
	v_pk_fma_f32 v[102:103], v[110:111], s[96:97], v[14:15] op_sel_hi:[1,0,0]
	v_exp_f32_e32 v110, v102
	v_exp_f32_e32 v111, v103
	v_cvt_pk_bf16_f32 v100, v108, v109
	v_cvt_pk_bf16_f32 v101, v110, v111
	s_nop 1
	v_mfma_f32_32x32x16_bf16 v[64:79], v[224:227], v[98:101], v[64:79]
	s_waitcnt lgkmcnt(0)
	v_mfma_f32_32x32x16_bf16 v[48:63], v[228:231], v[98:101], v[48:63]
	v_fma_f32 v100, v80, s96, v14
	v_fma_f32 v101, v81, s96, v14
	v_fma_f32 v102, v82, s96, v14
	v_fma_f32 v103, v83, s96, v14
	v_exp_f32_e32 v100, v100
	v_exp_f32_e32 v101, v101
	v_pk_add_f32 v[98:99], v[122:123], v[120:121]
	v_pk_add_f32 v[98:99], v[106:107], v[98:99]
	v_exp_f32_e32 v102, v102
	v_exp_f32_e32 v103, v103
	v_cvt_pk_bf16_f32 v80, v100, v101
	v_pk_add_f32 v[98:99], v[108:109], v[98:99]
	v_pk_add_f32 v[98:99], v[110:111], v[98:99]
	v_pk_fma_f32 v[82:83], v[84:85], s[96:97], v[14:15] op_sel_hi:[1,0,0]
	v_exp_f32_e32 v104, v82
	v_exp_f32_e32 v105, v83
	v_cvt_pk_bf16_f32 v81, v102, v103
	v_pk_fma_f32 v[84:85], v[86:87], s[96:97], v[14:15] op_sel_hi:[1,0,0]
	v_exp_f32_e32 v106, v84
	v_exp_f32_e32 v107, v85
	v_cvt_pk_bf16_f32 v82, v104, v105
	v_cvt_pk_bf16_f32 v83, v106, v107
	s_waitcnt lgkmcnt(0)
	s_nop 0
	v_mfma_f32_32x32x16_bf16 v[64:79], v[232:235], v[80:83], v[64:79]
	s_waitcnt lgkmcnt(0)
	v_mfma_f32_32x32x16_bf16 v[48:63], v[236:239], v[80:83], v[48:63]
	v_add_f32_e64 v80, v100, v98
	v_add_f32_e64 v81, v101, v99
	v_add_f32_e64 v80, v102, v80
	v_add_f32_e64 v81, v103, v81
	v_add_f32_e64 v80, v104, v80
	v_add_f32_e64 v81, v105, v81
	v_pk_add_f32 v[98:99], v[106:107], v[80:81]
	v_pk_fma_f32 v[80:81], v[88:89], s[96:97], v[14:15] op_sel_hi:[1,0,0]
	v_exp_f32_e32 v88, v80
	v_exp_f32_e32 v89, v81
	v_pk_fma_f32 v[82:83], v[90:91], s[96:97], v[14:15] op_sel_hi:[1,0,0]
	v_exp_f32_e32 v90, v82
	v_exp_f32_e32 v91, v83
	v_cvt_pk_bf16_f32 v80, v88, v89
	v_pk_fma_f32 v[82:83], v[92:93], s[96:97], v[14:15] op_sel_hi:[1,0,0]
	v_exp_f32_e32 v92, v82
	v_exp_f32_e32 v93, v83
	v_cvt_pk_bf16_f32 v81, v90, v91
	v_pk_fma_f32 v[84:85], v[94:95], s[96:97], v[14:15] op_sel_hi:[1,0,0]
	v_exp_f32_e32 v94, v84
	v_exp_f32_e32 v95, v85
	v_cvt_pk_bf16_f32 v82, v92, v93
	v_cvt_pk_bf16_f32 v83, v94, v95
	s_waitcnt lgkmcnt(0)
	s_nop 0
	v_mfma_f32_32x32x16_bf16 v[64:79], v[240:243], v[80:83], v[64:79]
	s_waitcnt lgkmcnt(0)
	v_mfma_f32_32x32x16_bf16 v[48:63], v[244:247], v[80:83], v[48:63]
	v_add_f32_e64 v80, v88, v98
	v_add_f32_e64 v81, v89, v99
	v_add_f32_e64 v80, v90, v80
	v_add_f32_e64 v81, v91, v81
	v_add_f32_e64 v80, v92, v80
	v_add_f32_e64 v81, v93, v81
	v_pk_add_f32 v[80:81], v[94:95], v[80:81]
	v_add_f32_e32 v14, v80, v81
	ds_bpermute_b32 v80, v165, v14
	s_waitcnt lgkmcnt(0)
	v_add_f32_e32 v14, v14, v80
	v_add_f32_e32 v168, v168, v14

; #define MFMA(a, b, c) __builtin_amdgcn_mfma_f32_32x32x16_bf16((a), (b), (c), 0, 0, 0)
; DI int crow(int i, int h) { return (i & 3) + 8 * (i >> 2) + 4 * h; }
; template <int DK, int DV, int MODE>
; DI void fa_qk(f32x16 (&S)[2], const bf16x8 (&q)[DK / 16], const char* base, int lr, int lh) {
;   using C = FA<DK, DV>;
; #pragma unroll
;   for (int ks = 0; ks < 2; ++ks) {
; #pragma unroll
;     for (int kk = 0; kk < DK / 16; ++kk) {
;       const bf16x8 kf = *(const bf16x8*)(base + (ks * 32 + lr) * C::KSTR + (kk * 2 + lh) * 16);
;       if (kk == 0) {
; #pragma unroll
;         for (int i = 0; i < 16; ++i) S[ks][i] = 0.f;
;       }
;       S[ks] = MFMA(kf, q[kk], S[ks]);
;     }
;   }
; }
;     ...
;   if (MODE != 0) need_mask = (kb * 64 + 63 > wave_qmax - 31);
;   if (MODE == 2) selbit = (sel >> kb) & 1ull;
;   if (MODE == 3) need_mask = need_mask || (kb * 64 <= wave_qmax - 512);
;   const float c2 = scale * 1.4426950408889634f;
;   if (need_mask) {
; #pragma unroll
;     for (int ks = 0; ks < 2; ++ks)
; #pragma unroll
;       for (int i = 0; i < 16; ++i) {
;         const int key = kb * 64 + ks * 32 + crow(i, lh);
;         bool valid = key <= qpos;
;         if (MODE == 2) valid = valid && selbit;
;         if (MODE == 3) valid = valid && (qpos - key < 512);
;         S[ks][i] = valid ? S[ks][i] : -1e30f;
;       }
;   }
.LBB0_561:
	v_lshrrev_b64 v[80:81], s0, v[2:3]
	s_sub_i32 s8, s7, 63
	v_and_b32_e32 v14, 1, v80
	s_cmp_le_u32 s8, s20
	v_cmp_ne_u32_e32 vcc, 0, v14
	s_cselect_b64 s[8:9], -1, 0
	s_cmp_lg_u64 vcc, 0
	s_cselect_b64 s[10:11], -1, 0
	s_and_b64 s[8:9], s[10:11], s[8:9]
	s_andn2_b64 vcc, exec, s[8:9]
	v_cmp_eq_u32_e64 s[10:11], 1, v14
	s_cbranch_vccnz .LBB0_550
	s_add_i32 s6, s6, 0
	v_add3_u32 v14, s6, v115, v114
	ds_read_b128 v[216:219], v14
	ds_read_b128 v[220:223], v14 offset:32
	ds_read_b128 v[224:227], v14 offset:64
	ds_read_b128 v[228:231], v14 offset:96
	ds_read_b128 v[232:235], v14 offset:4608
	ds_read_b128 v[236:239], v14 offset:4640
	ds_read_b128 v[240:243], v14 offset:4672
	ds_read_b128 v[244:247], v14 offset:4704
	s_cmp_gt_u32 s7, s35
	s_cselect_b64 s[8:9], -1, 0
	s_cmp_le_u32 s7, s35
	s_waitcnt lgkmcnt(7)
	v_mfma_f32_32x32x16_bf16 v[96:111], v[216:219], v[152:155], 0
	s_waitcnt lgkmcnt(6)
	v_mfma_f32_32x32x16_bf16 v[96:111], v[220:223], v[144:147], v[96:111]
	s_waitcnt lgkmcnt(5)
	v_mfma_f32_32x32x16_bf16 v[96:111], v[224:227], v[148:151], v[96:111]
	s_waitcnt lgkmcnt(4)
	v_mfma_f32_32x32x16_bf16 v[96:111], v[228:231], v[156:159], v[96:111]
	s_waitcnt lgkmcnt(3)
	v_mfma_f32_32x32x16_bf16 v[80:95], v[232:235], v[152:155], 0
	s_waitcnt lgkmcnt(2)
	v_mfma_f32_32x32x16_bf16 v[80:95], v[236:239], v[144:147], v[80:95]
	s_waitcnt lgkmcnt(1)
	v_mfma_f32_32x32x16_bf16 v[80:95], v[240:243], v[148:151], v[80:95]
	s_waitcnt lgkmcnt(0)
	v_mfma_f32_32x32x16_bf16 v[80:95], v[244:247], v[156:159], v[80:95]
	v_add3_u32 v247, s6, v117, v115
	v_add_u32_e32 v243, 0x2000, v247
	v_add_u32_e32 v247, 0x3000, v247
	ds_read2_b64 v[216:219], v243 offset0:128 offset1:130
	ds_read2_b64 v[220:223], v247 offset0:192 offset1:194
	ds_read2_b64 v[224:227], v243 offset0:132 offset1:134
	ds_read2_b64 v[228:231], v247 offset0:196 offset1:198
	ds_read2_b64 v[232:235], v243 offset0:136 offset1:138
	ds_read2_b64 v[236:239], v247 offset0:200 offset1:202
	ds_read2_b64 v[240:243], v243 offset0:140 offset1:142
	ds_read2_b64 v[244:247], v247 offset0:204 offset1:206
	s_cbranch_scc1 .LBB0_564
	v_add_u32_e32 v14, s7, v116
	v_subrev_u32_e32 v119, 63, v14
	v_cmp_le_i32_e32 vcc, v119, v162
	s_and_b64 vcc, vcc, s[10:11]
	s_nop 0
	v_cndmask_b32_e32 v96, v208, v96, vcc
	v_cmp_lt_i32_e32 vcc, v119, v162
	s_and_b64 vcc, vcc, s[10:11]
	v_subrev_u32_e32 v119, 61, v14
	v_cndmask_b32_e32 v97, v208, v97, vcc
	v_cmp_le_i32_e32 vcc, v119, v162
	s_and_b64 vcc, vcc, s[10:11]
	v_subrev_u32_e32 v119, 60, v14
	v_cndmask_b32_e32 v98, v208, v98, vcc
	v_cmp_le_i32_e32 vcc, v119, v162
	s_and_b64 vcc, vcc, s[10:11]
	v_subrev_u32_e32 v119, 55, v14
	v_cndmask_b32_e32 v99, v208, v99, vcc
	v_cmp_le_i32_e32 vcc, v119, v162
	s_and_b64 vcc, vcc, s[10:11]
	v_subrev_u32_e32 v119, 54, v14
	v_cndmask_b32_e32 v100, v208, v100, vcc
	v_cmp_le_i32_e32 vcc, v119, v162
	s_and_b64 vcc, vcc, s[10:11]
	v_subrev_u32_e32 v119, 53, v14
	v_cndmask_b32_e32 v101, v208, v101, vcc
	v_cmp_le_i32_e32 vcc, v119, v162
	s_and_b64 vcc, vcc, s[10:11]
	v_subrev_u32_e32 v119, 52, v14
	v_cndmask_b32_e32 v102, v208, v102, vcc
	v_cmp_le_i32_e32 vcc, v119, v162
	s_and_b64 vcc, vcc, s[10:11]
	v_subrev_u32_e32 v119, 47, v14
	v_cndmask_b32_e32 v103, v208, v103, vcc
	v_cmp_le_i32_e32 vcc, v119, v162
	s_and_b64 vcc, vcc, s[10:11]
	v_subrev_u32_e32 v119, 46, v14
	v_cndmask_b32_e32 v104, v208, v104, vcc
	v_cmp_le_i32_e32 vcc, v119, v162
	s_and_b64 vcc, vcc, s[10:11]
	v_subrev_u32_e32 v119, 45, v14
	v_cndmask_b32_e32 v105, v208, v105, vcc
	v_cmp_le_i32_e32 vcc, v119, v162
	s_and_b64 vcc, vcc, s[10:11]
	v_subrev_u32_e32 v119, 44, v14
	v_cndmask_b32_e32 v106, v208, v106, vcc
	v_cmp_le_i32_e32 vcc, v119, v162
	s_and_b64 vcc, vcc, s[10:11]
	v_subrev_u32_e32 v119, 39, v14
	v_cndmask_b32_e32 v107, v208, v107, vcc
	v_cmp_le_i32_e32 vcc, v119, v162
	s_and_b64 vcc, vcc, s[10:11]
	v_subrev_u32_e32 v119, 38, v14
	v_cndmask_b32_e32 v108, v208, v108, vcc
	v_cmp_le_i32_e32 vcc, v119, v162
	s_and_b64 vcc, vcc, s[10:11]
	v_subrev_u32_e32 v119, 37, v14
	v_cndmask_b32_e32 v109, v208, v109, vcc
	v_cmp_le_i32_e32 vcc, v119, v162
	s_and_b64 vcc, vcc, s[10:11]
	v_subrev_u32_e32 v119, 36, v14
	v_cndmask_b32_e32 v110, v208, v110, vcc
	v_cmp_le_i32_e32 vcc, v119, v162
	s_and_b64 vcc, vcc, s[10:11]
	v_subrev_u32_e32 v119, 31, v14
	v_cndmask_b32_e32 v111, v208, v111, vcc
	v_cmp_le_i32_e32 vcc, v119, v162
	s_and_b64 vcc, vcc, s[10:11]
	v_subrev_u32_e32 v119, 30, v14
	v_cndmask_b32_e32 v80, v208, v80, vcc
	v_cmp_le_i32_e32 vcc, v119, v162
	s_and_b64 vcc, vcc, s[10:11]
	v_subrev_u32_e32 v119, 29, v14
	v_cndmask_b32_e32 v81, v208, v81, vcc
	v_cmp_le_i32_e32 vcc, v119, v162
	s_and_b64 vcc, vcc, s[10:11]
	v_subrev_u32_e32 v119, 28, v14
	v_cndmask_b32_e32 v82, v208, v82, vcc
	v_cmp_le_i32_e32 vcc, v119, v162
	s_and_b64 vcc, vcc, s[10:11]
	v_subrev_u32_e32 v119, 23, v14
	v_cndmask_b32_e32 v83, v208, v83, vcc
	v_cmp_le_i32_e32 vcc, v119, v162
	s_and_b64 vcc, vcc, s[10:11]
	v_subrev_u32_e32 v119, 22, v14
	v_cndmask_b32_e32 v84, v208, v84, vcc
	v_cmp_le_i32_e32 vcc, v119, v162
	s_and_b64 vcc, vcc, s[10:11]
	v_subrev_u32_e32 v119, 21, v14
	v_cndmask_b32_e32 v85, v208, v85, vcc
	v_cmp_le_i32_e32 vcc, v119, v162
	s_and_b64 vcc, vcc, s[10:11]
	v_subrev_u32_e32 v119, 20, v14
	v_cndmask_b32_e32 v86, v208, v86, vcc
	v_cmp_le_i32_e32 vcc, v119, v162
	s_and_b64 vcc, vcc, s[10:11]
	v_add_u32_e32 v119, -15, v14
	v_cndmask_b32_e32 v87, v208, v87, vcc
	v_cmp_le_i32_e32 vcc, v119, v162
	s_and_b64 vcc, vcc, s[10:11]
	v_add_u32_e32 v119, -14, v14
	v_cndmask_b32_e32 v88, v208, v88, vcc
	v_cmp_le_i32_e32 vcc, v119, v162
	s_and_b64 vcc, vcc, s[10:11]
	v_add_u32_e32 v119, -13, v14
	v_cndmask_b32_e32 v89, v208, v89, vcc
	v_cmp_le_i32_e32 vcc, v119, v162
	s_and_b64 vcc, vcc, s[10:11]
	v_add_u32_e32 v119, -12, v14
	v_cndmask_b32_e32 v90, v208, v90, vcc
	v_cmp_le_i32_e32 vcc, v119, v162
	s_and_b64 vcc, vcc, s[10:11]
	v_add_u32_e32 v119, -7, v14
	v_cndmask_b32_e32 v91, v208, v91, vcc
	v_cmp_le_i32_e32 vcc, v119, v162
	s_and_b64 vcc, vcc, s[10:11]
	v_add_u32_e32 v119, -6, v14
	v_cndmask_b32_e32 v92, v208, v92, vcc
	v_cmp_le_i32_e32 vcc, v119, v162
	s_and_b64 vcc, vcc, s[10:11]
	v_add_u32_e32 v119, -5, v14
	v_cndmask_b32_e32 v93, v208, v93, vcc
	v_cmp_le_i32_e32 vcc, v119, v162
	s_and_b64 vcc, vcc, s[10:11]
	v_add_u32_e32 v14, -4, v14
	v_cndmask_b32_e32 v94, v208, v94, vcc
	v_cmp_le_i32_e32 vcc, v14, v162
	s_and_b64 vcc, vcc, s[10:11]
	s_nop 0
	v_cndmask_b32_e32 v95, v208, v95, vcc

; #define MFMA(a, b, c) __builtin_amdgcn_mfma_f32_32x32x16_bf16((a), (b), (c), 0, 0, 0)
;     ...
;   float mc = m * c2;
;   if (MODE == 2) mc = selbit ? mc : 1e30f;
;   const f32x2v c2v = {c2, c2}, mcv = {-mc, -mc};
;   f32x2v rs2 = {0.f, 0.f};
; #pragma unroll
;   for (int ks = 0; ks < 2; ++ks)
; #pragma unroll
;     for (int st = 0; st < 2; ++st) {
;       union { unsigned u[4]; bf16x8 v; } pf;
; #pragma unroll
;       for (int j = 0; j < 4; ++j) {
;         const int i0 = 8 * st + 2 * j;
;         f32x2v t = {S[ks][i0], S[ks][i0 + 1]};
;         t = __builtin_elementwise_fma(t, c2v, mcv);
;         f32x2v pv;
;         if (variant == 1) { pv = t; } else {
;         pv.x = __builtin_amdgcn_exp2f(t.x);
;         pv.y = __builtin_amdgcn_exp2f(t.y);
;         }
;         if (MODE != 0) {
;           if (need_mask) {
;             pv.x = (S[ks][i0] > -1e29f) ? pv.x : 0.f;
;             pv.y = (S[ks][i0 + 1] > -1e29f) ? pv.y : 0.f;
;           }
;         }
;         rs2 += pv;
;         pf.u[j] = __builtin_bit_cast(unsigned, __builtin_convertvector(pv, hwbf16x2));
;       }
; #pragma unroll
;       for (int d = 0; d < DV / 32; ++d) {
;         const char* vp = base + C::KBYTES + (d * 32 + lr) * C::VSTR + (ks * 32 + 16 * st + 4 * lh) * 2;
;         const s16x4 lo = *(const s16x4*)vp, hi = *(const s16x4*)(vp + 16);
;         const bf16x8 vf = __builtin_shufflevector(lo, hi, 0, 1, 2, 3, 4, 5, 6, 7);
;         O[d] = MFMA(vf, pf.v, O[d]);
;       }
;     }
;   float rs = rs2.x + rs2.y;
;   rs += __shfl_xor(rs, 32);
;   l += rs;
.LBB0_585:
	s_cmp_eq_u64 s[8:9], 0
	s_cbranch_scc1 .Lfast_win2
	v_mul_f32_e32 v12, 0xbe38aa3b, v12
	v_pk_fma_f32 v[176:177], v[128:129], s[96:97], v[12:13] op_sel_hi:[1,0,0]
	v_cmp_lt_f32_e32 vcc, s33, v128
	v_exp_f32_e32 v176, v176
	v_exp_f32_e32 v177, v177
	v_cndmask_b32_e32 v128, 0, v176, vcc
	v_cmp_lt_f32_e32 vcc, s33, v129
	v_cndmask_b32_e64 v184, v176, v128, s[8:9]
	s_nop 0
	v_cndmask_b32_e32 v129, 0, v177, vcc
	v_cndmask_b32_e64 v185, v177, v129, s[8:9]
	v_pk_fma_f32 v[128:129], v[130:131], s[96:97], v[12:13] op_sel_hi:[1,0,0]
	v_cmp_lt_f32_e32 vcc, s33, v130
	v_exp_f32_e32 v128, v128
	v_exp_f32_e32 v129, v129
	v_cvt_pk_bf16_f32 v176, v184, v185
	v_cndmask_b32_e32 v130, 0, v128, vcc
	v_cmp_lt_f32_e32 vcc, s33, v131
	v_cndmask_b32_e64 v186, v128, v130, s[8:9]
	s_nop 0
	v_cndmask_b32_e32 v131, 0, v129, vcc
	v_cndmask_b32_e64 v187, v129, v131, s[8:9]
	v_pk_fma_f32 v[128:129], v[132:133], s[96:97], v[12:13] op_sel_hi:[1,0,0]
	v_cmp_lt_f32_e32 vcc, s33, v132
	v_exp_f32_e32 v128, v128
	v_exp_f32_e32 v129, v129
	v_cvt_pk_bf16_f32 v177, v186, v187
	v_cndmask_b32_e32 v130, 0, v128, vcc
	v_cmp_lt_f32_e32 vcc, s33, v133
	v_cndmask_b32_e64 v188, v128, v130, s[8:9]
	s_nop 0
	v_cndmask_b32_e32 v131, 0, v129, vcc
	v_cndmask_b32_e64 v189, v129, v131, s[8:9]
	v_pk_fma_f32 v[128:129], v[134:135], s[96:97], v[12:13] op_sel_hi:[1,0,0]
	v_cmp_lt_f32_e32 vcc, s33, v134
	v_exp_f32_e32 v128, v128
	v_exp_f32_e32 v129, v129
	v_cvt_pk_bf16_f32 v178, v188, v189
	v_cndmask_b32_e32 v130, 0, v128, vcc
	v_cmp_lt_f32_e32 vcc, s33, v135
	v_cndmask_b32_e64 v134, v128, v130, s[8:9]
	s_nop 0
	v_cndmask_b32_e32 v131, 0, v129, vcc
	v_cndmask_b32_e64 v135, v129, v131, s[8:9]
	s_nop 0
	s_nop 0
	s_nop 0
	s_nop 0
	v_cvt_pk_bf16_f32 v179, v134, v135
	s_nop 0
	v_cmp_lt_f32_e32 vcc, s33, v136
	s_waitcnt lgkmcnt(0)
	v_mfma_f32_32x32x16_bf16 v[96:111], v[216:219], v[176:179], v[96:111]
	s_nop 0
	s_waitcnt lgkmcnt(0)
	v_mfma_f32_32x32x16_bf16 v[80:95], v[220:223], v[176:179], v[80:95]
	v_add_f32_e64 v130, v184, 0
	v_add_f32_e64 v131, v185, 0
	v_add_f32_e64 v130, v186, v130
	v_add_f32_e64 v131, v187, v131
	v_add_f32_e64 v130, v188, v130
	v_add_f32_e64 v131, v189, v131
	v_pk_add_f32 v[176:177], v[134:135], v[130:131]
	v_pk_fma_f32 v[130:131], v[136:137], s[96:97], v[12:13] op_sel_hi:[1,0,0]
	s_nop 0
	v_exp_f32_e32 v130, v130
	v_exp_f32_e32 v131, v131
	v_cndmask_b32_e32 v132, 0, v130, vcc
	v_cmp_lt_f32_e32 vcc, s33, v137
	v_cndmask_b32_e64 v178, v130, v132, s[8:9]
	s_nop 0
	v_cndmask_b32_e32 v133, 0, v131, vcc
	v_cndmask_b32_e64 v179, v131, v133, s[8:9]
	v_pk_fma_f32 v[132:133], v[138:139], s[96:97], v[12:13] op_sel_hi:[1,0,0]
	v_cmp_lt_f32_e32 vcc, s33, v138
	v_exp_f32_e32 v131, v132
	v_exp_f32_e32 v132, v133
	v_cvt_pk_bf16_f32 v130, v178, v179
	v_cndmask_b32_e32 v133, 0, v131, vcc
	v_cmp_lt_f32_e32 vcc, s33, v139
	v_cndmask_b32_e64 v138, v131, v133, s[8:9]
	s_nop 0
	v_cndmask_b32_e32 v134, 0, v132, vcc
	v_cndmask_b32_e64 v139, v132, v134, s[8:9]
	v_pk_fma_f32 v[132:133], v[140:141], s[96:97], v[12:13] op_sel_hi:[1,0,0]
	v_cmp_lt_f32_e32 vcc, s33, v140
	v_exp_f32_e32 v132, v132
	v_exp_f32_e32 v133, v133
	v_cvt_pk_bf16_f32 v131, v138, v139
	v_cndmask_b32_e32 v134, 0, v132, vcc
	v_cmp_lt_f32_e32 vcc, s33, v141
	v_cndmask_b32_e64 v140, v132, v134, s[8:9]
	s_nop 0
	v_cndmask_b32_e32 v135, 0, v133, vcc
	v_cndmask_b32_e64 v141, v133, v135, s[8:9]
	v_pk_fma_f32 v[134:135], v[142:143], s[96:97], v[12:13] op_sel_hi:[1,0,0]
	v_cmp_lt_f32_e32 vcc, s33, v142
	v_exp_f32_e32 v133, v134
	v_exp_f32_e32 v134, v135
	v_cvt_pk_bf16_f32 v132, v140, v141
	v_cndmask_b32_e32 v135, 0, v133, vcc
	v_cmp_lt_f32_e32 vcc, s33, v143
	v_cndmask_b32_e64 v142, v133, v135, s[8:9]
	s_nop 0
	v_cndmask_b32_e32 v136, 0, v134, vcc
	v_cndmask_b32_e64 v143, v134, v136, s[8:9]
	s_nop 0
	v_cvt_pk_bf16_f32 v133, v142, v143
	v_cmp_lt_f32_e32 vcc, s33, v112
	s_nop 0
	v_mfma_f32_32x32x16_bf16 v[96:111], v[224:227], v[130:133], v[96:111]
	s_waitcnt lgkmcnt(0)
	v_mfma_f32_32x32x16_bf16 v[80:95], v[228:231], v[130:133], v[80:95]
	v_fma_f32 v132, v112, s96, v12
	v_fma_f32 v133, v113, s96, v12
	v_fma_f32 v134, v114, s96, v12
	v_fma_f32 v135, v115, s96, v12
	v_exp_f32_e32 v132, v132
	v_exp_f32_e32 v133, v133
	v_pk_add_f32 v[130:131], v[178:179], v[176:177]
	v_cndmask_b32_e32 v112, 0, v132, vcc
	v_cmp_lt_f32_e32 vcc, s33, v113
	v_pk_add_f32 v[130:131], v[138:139], v[130:131]
	v_cndmask_b32_e64 v132, v132, v112, s[8:9]
	v_cndmask_b32_e32 v113, 0, v133, vcc
	v_cndmask_b32_e64 v133, v133, v113, s[8:9]
	v_exp_f32_e32 v113, v134
	v_exp_f32_e32 v134, v135
	v_cmp_lt_f32_e32 vcc, s33, v114
	v_cvt_pk_bf16_f32 v112, v132, v133
	v_pk_add_f32 v[130:131], v[140:141], v[130:131]
	v_cndmask_b32_e32 v114, 0, v113, vcc
	v_cmp_lt_f32_e32 vcc, s33, v115
	v_pk_add_f32 v[130:131], v[142:143], v[130:131]
	s_nop 0
	v_cndmask_b32_e32 v115, 0, v134, vcc
	v_cndmask_b32_e64 v135, v134, v115, s[8:9]
	v_cndmask_b32_e64 v134, v113, v114, s[8:9]
	v_pk_fma_f32 v[114:115], v[116:117], s[96:97], v[12:13] op_sel_hi:[1,0,0]
	v_cmp_lt_f32_e32 vcc, s33, v116
	v_exp_f32_e32 v114, v114
	v_exp_f32_e32 v115, v115
	v_cvt_pk_bf16_f32 v113, v134, v135
	v_cndmask_b32_e32 v116, 0, v114, vcc
	v_cmp_lt_f32_e32 vcc, s33, v117
	v_cndmask_b32_e64 v136, v114, v116, s[8:9]
	s_nop 0
	v_cndmask_b32_e32 v117, 0, v115, vcc
	v_cndmask_b32_e64 v137, v115, v117, s[8:9]
	v_pk_fma_f32 v[116:117], v[118:119], s[96:97], v[12:13] op_sel_hi:[1,0,0]
	v_cmp_lt_f32_e32 vcc, s33, v118
	v_exp_f32_e32 v115, v116
	v_exp_f32_e32 v116, v117
	v_cvt_pk_bf16_f32 v114, v136, v137
	v_cndmask_b32_e32 v117, 0, v115, vcc
	v_cmp_lt_f32_e32 vcc, s33, v119
	v_cndmask_b32_e64 v138, v115, v117, s[8:9]
	s_nop 0
	v_cndmask_b32_e32 v118, 0, v116, vcc
	v_cndmask_b32_e64 v139, v116, v118, s[8:9]
	s_nop 0
	v_cvt_pk_bf16_f32 v115, v138, v139
	v_cmp_lt_f32_e32 vcc, s33, v120
	s_waitcnt lgkmcnt(0)
; #define MFMA(a, b, c) __builtin_amdgcn_mfma_f32_32x32x16_bf16((a), (b), (c), 0, 0, 0)
;     ...
;   for (int ks = 0; ks < 2; ++ks)
; #pragma unroll
;     for (int st = 0; st < 2; ++st) {
;       union { unsigned u[4]; bf16x8 v; } pf;
; #pragma unroll
;       for (int j = 0; j < 4; ++j) {
;         const int i0 = 8 * st + 2 * j;
;         f32x2v t = {S[ks][i0], S[ks][i0 + 1]};
;         t = __builtin_elementwise_fma(t, c2v, mcv);
;         f32x2v pv;
;         if (variant == 1) { pv = t; } else {
;         pv.x = __builtin_amdgcn_exp2f(t.x);
;         pv.y = __builtin_amdgcn_exp2f(t.y);
;         }
;         if (MODE != 0) {
;           if (need_mask) {
;             pv.x = (S[ks][i0] > -1e29f) ? pv.x : 0.f;
;             pv.y = (S[ks][i0 + 1] > -1e29f) ? pv.y : 0.f;
;           }
;         }
;         rs2 += pv;
;         pf.u[j] = __builtin_bit_cast(unsigned, __builtin_convertvector(pv, hwbf16x2));
;       }
; #pragma unroll
;       for (int d = 0; d < DV / 32; ++d) {
;         const char* vp = base + C::KBYTES + (d * 32 + lr) * C::VSTR + (ks * 32 + 16 * st + 4 * lh) * 2;
;         const s16x4 lo = *(const s16x4*)vp, hi = *(const s16x4*)(vp + 16);
;         const bf16x8 vf = __builtin_shufflevector(lo, hi, 0, 1, 2, 3, 4, 5, 6, 7);
;         O[d] = MFMA(vf, pf.v, O[d]);
;       }
;     }
;   float rs = rs2.x + rs2.y;
;   rs += __shfl_xor(rs, 32);
;   l += rs;
	v_mfma_f32_32x32x16_bf16 v[96:111], v[232:235], v[112:115], v[96:111]
	s_nop 0
	s_waitcnt lgkmcnt(0)
	v_mfma_f32_32x32x16_bf16 v[80:95], v[236:239], v[112:115], v[80:95]
	v_add_f32_e64 v112, v132, v130
	v_add_f32_e64 v113, v133, v131
	v_add_f32_e64 v112, v134, v112
	v_add_f32_e64 v113, v135, v113
	v_add_f32_e64 v112, v136, v112
	v_add_f32_e64 v113, v137, v113
	v_pk_add_f32 v[130:131], v[138:139], v[112:113]
	v_pk_fma_f32 v[112:113], v[120:121], s[96:97], v[12:13] op_sel_hi:[1,0,0]
	s_nop 0
	v_exp_f32_e32 v112, v112
	v_exp_f32_e32 v113, v113
	v_cndmask_b32_e32 v114, 0, v112, vcc
	v_cmp_lt_f32_e32 vcc, s33, v121
	v_cndmask_b32_e64 v120, v112, v114, s[8:9]
	s_nop 0
	v_cndmask_b32_e32 v115, 0, v113, vcc
	v_cndmask_b32_e64 v121, v113, v115, s[8:9]
	v_pk_fma_f32 v[114:115], v[122:123], s[96:97], v[12:13] op_sel_hi:[1,0,0]
	v_cmp_lt_f32_e32 vcc, s33, v122
	v_exp_f32_e32 v113, v114
	v_exp_f32_e32 v114, v115
	v_cvt_pk_bf16_f32 v112, v120, v121
	v_cndmask_b32_e32 v115, 0, v113, vcc
	v_cmp_lt_f32_e32 vcc, s33, v123
	v_cndmask_b32_e64 v122, v113, v115, s[8:9]
	s_nop 0
	v_cndmask_b32_e32 v116, 0, v114, vcc
	v_cndmask_b32_e64 v123, v114, v116, s[8:9]
	v_pk_fma_f32 v[114:115], v[124:125], s[96:97], v[12:13] op_sel_hi:[1,0,0]
	v_cmp_lt_f32_e32 vcc, s33, v124
	v_exp_f32_e32 v114, v114
	v_exp_f32_e32 v115, v115
	v_cvt_pk_bf16_f32 v113, v122, v123
	v_cndmask_b32_e32 v116, 0, v114, vcc
	v_cmp_lt_f32_e32 vcc, s33, v125
	v_cndmask_b32_e64 v124, v114, v116, s[8:9]
	s_nop 0
	v_cndmask_b32_e32 v117, 0, v115, vcc
	v_cndmask_b32_e64 v125, v115, v117, s[8:9]
	v_pk_fma_f32 v[116:117], v[126:127], s[96:97], v[12:13] op_sel_hi:[1,0,0]
	v_cmp_lt_f32_e32 vcc, s33, v126
	v_exp_f32_e32 v12, v116
	v_exp_f32_e32 v115, v117
	v_cvt_pk_bf16_f32 v114, v124, v125
	v_cndmask_b32_e32 v116, 0, v12, vcc
	v_cmp_lt_f32_e32 vcc, s33, v127
	v_cndmask_b32_e64 v126, v12, v116, s[8:9]
	s_nop 0
	v_cndmask_b32_e32 v117, 0, v115, vcc
	v_cndmask_b32_e64 v127, v115, v117, s[8:9]
	s_nop 0
	v_cvt_pk_bf16_f32 v115, v126, v127
	s_waitcnt lgkmcnt(0)
	s_nop 0
	v_mfma_f32_32x32x16_bf16 v[96:111], v[240:243], v[112:115], v[96:111]
	s_nop 0
	s_waitcnt lgkmcnt(0)
	v_mfma_f32_32x32x16_bf16 v[80:95], v[244:247], v[112:115], v[80:95]
	v_add_f32_e64 v112, v120, v130
	v_add_f32_e64 v113, v121, v131
	v_add_f32_e64 v112, v122, v112
	v_add_f32_e64 v113, v123, v113
	v_add_f32_e64 v112, v124, v112
	v_add_f32_e64 v113, v125, v113
	v_pk_add_f32 v[112:113], v[126:127], v[112:113]
	s_nop 0
	v_add_f32_e32 v12, v112, v113
	ds_bpermute_b32 v112, v165, v12
	s_waitcnt lgkmcnt(0)
	v_add_f32_e32 v12, v12, v112
	v_add_f32_e32 v170, v170, v12
	s_branch .LBB0_586
; #define MFMA(a, b, c) __builtin_amdgcn_mfma_f32_32x32x16_bf16((a), (b), (c), 0, 0, 0)
;     ...
;   for (int ks = 0; ks < 2; ++ks)
; #pragma unroll
;     for (int st = 0; st < 2; ++st) {
;       union { unsigned u[4]; bf16x8 v; } pf;
; #pragma unroll
;       for (int j = 0; j < 4; ++j) {
;         const int i0 = 8 * st + 2 * j;
;         f32x2v t = {S[ks][i0], S[ks][i0 + 1]};
;         t = __builtin_elementwise_fma(t, c2v, mcv);
;         f32x2v pv;
;         if (variant == 1) { pv = t; } else {
;         pv.x = __builtin_amdgcn_exp2f(t.x);
;         pv.y = __builtin_amdgcn_exp2f(t.y);
;         }
;         if (MODE != 0) {
;           if (need_mask) {
;             pv.x = (S[ks][i0] > -1e29f) ? pv.x : 0.f;
;             pv.y = (S[ks][i0 + 1] > -1e29f) ? pv.y : 0.f;
;           }
;         }
;         rs2 += pv;
;         pf.u[j] = __builtin_bit_cast(unsigned, __builtin_convertvector(pv, hwbf16x2));
;       }
; #pragma unroll
;       for (int d = 0; d < DV / 32; ++d) {
;         const char* vp = base + C::KBYTES + (d * 32 + lr) * C::VSTR + (ks * 32 + 16 * st + 4 * lh) * 2;
;         const s16x4 lo = *(const s16x4*)vp, hi = *(const s16x4*)(vp + 16);
;         const bf16x8 vf = __builtin_shufflevector(lo, hi, 0, 1, 2, 3, 4, 5, 6, 7);
;         O[d] = MFMA(vf, pf.v, O[d]);
;       }
;     }
;   float rs = rs2.x + rs2.y;
;   rs += __shfl_xor(rs, 32);
;   l += rs;
.Lfast_win2:
	v_mul_f32_e32 v12, 0xbe38aa3b, v12
	v_pk_fma_f32 v[176:177], v[128:129], s[96:97], v[12:13] op_sel_hi:[1,0,0]
	v_exp_f32_e32 v184, v176
	v_exp_f32_e32 v185, v177
	v_pk_fma_f32 v[128:129], v[130:131], s[96:97], v[12:13] op_sel_hi:[1,0,0]
	v_exp_f32_e32 v186, v128
	v_exp_f32_e32 v187, v129
	v_cvt_pk_bf16_f32 v176, v184, v185
	v_pk_fma_f32 v[128:129], v[132:133], s[96:97], v[12:13] op_sel_hi:[1,0,0]
	v_exp_f32_e32 v188, v128
	v_exp_f32_e32 v189, v129
	v_cvt_pk_bf16_f32 v177, v186, v187
	v_pk_fma_f32 v[128:129], v[134:135], s[96:97], v[12:13] op_sel_hi:[1,0,0]
	v_exp_f32_e32 v134, v128
	v_exp_f32_e32 v135, v129
	v_cvt_pk_bf16_f32 v178, v188, v189
	v_cvt_pk_bf16_f32 v179, v134, v135
	s_waitcnt lgkmcnt(0)
	s_nop 0
	v_mfma_f32_32x32x16_bf16 v[96:111], v[216:219], v[176:179], v[96:111]
	s_waitcnt lgkmcnt(0)
	v_mfma_f32_32x32x16_bf16 v[80:95], v[220:223], v[176:179], v[80:95]
	v_add_f32_e64 v130, v184, 0
	v_add_f32_e64 v131, v185, 0
	v_add_f32_e64 v130, v186, v130
	v_add_f32_e64 v131, v187, v131
	v_add_f32_e64 v130, v188, v130
	v_add_f32_e64 v131, v189, v131
	v_pk_add_f32 v[176:177], v[134:135], v[130:131]
	v_pk_fma_f32 v[130:131], v[136:137], s[96:97], v[12:13] op_sel_hi:[1,0,0]
	v_exp_f32_e32 v178, v130
	v_exp_f32_e32 v179, v131
	v_pk_fma_f32 v[132:133], v[138:139], s[96:97], v[12:13] op_sel_hi:[1,0,0]
	v_exp_f32_e32 v138, v132
	v_exp_f32_e32 v139, v133
	v_cvt_pk_bf16_f32 v130, v178, v179
	v_pk_fma_f32 v[132:133], v[140:141], s[96:97], v[12:13] op_sel_hi:[1,0,0]
	v_exp_f32_e32 v140, v132
	v_exp_f32_e32 v141, v133
	v_cvt_pk_bf16_f32 v131, v138, v139
	v_pk_fma_f32 v[134:135], v[142:143], s[96:97], v[12:13] op_sel_hi:[1,0,0]
	v_exp_f32_e32 v142, v134
	v_exp_f32_e32 v143, v135
	v_cvt_pk_bf16_f32 v132, v140, v141
	v_cvt_pk_bf16_f32 v133, v142, v143
	s_nop 1
	v_mfma_f32_32x32x16_bf16 v[96:111], v[224:227], v[130:133], v[96:111]
	s_waitcnt lgkmcnt(0)
	v_mfma_f32_32x32x16_bf16 v[80:95], v[228:231], v[130:133], v[80:95]
	v_fma_f32 v132, v112, s96, v12
	v_fma_f32 v133, v113, s96, v12
	v_fma_f32 v134, v114, s96, v12
	v_fma_f32 v135, v115, s96, v12
	v_exp_f32_e32 v132, v132
	v_exp_f32_e32 v133, v133
	v_pk_add_f32 v[130:131], v[178:179], v[176:177]
	v_pk_add_f32 v[130:131], v[138:139], v[130:131]
	v_exp_f32_e32 v134, v134
	v_exp_f32_e32 v135, v135
	v_cvt_pk_bf16_f32 v112, v132, v133
	v_pk_add_f32 v[130:131], v[140:141], v[130:131]
	v_pk_add_f32 v[130:131], v[142:143], v[130:131]
	v_pk_fma_f32 v[114:115], v[116:117], s[96:97], v[12:13] op_sel_hi:[1,0,0]
	v_exp_f32_e32 v136, v114
	v_exp_f32_e32 v137, v115
	v_cvt_pk_bf16_f32 v113, v134, v135
	v_pk_fma_f32 v[116:117], v[118:119], s[96:97], v[12:13] op_sel_hi:[1,0,0]
	v_exp_f32_e32 v138, v116
	v_exp_f32_e32 v139, v117
	v_cvt_pk_bf16_f32 v114, v136, v137
	v_cvt_pk_bf16_f32 v115, v138, v139
	s_waitcnt lgkmcnt(0)
	s_nop 0
	v_mfma_f32_32x32x16_bf16 v[96:111], v[232:235], v[112:115], v[96:111]
	s_waitcnt lgkmcnt(0)
	v_mfma_f32_32x32x16_bf16 v[80:95], v[236:239], v[112:115], v[80:95]
	v_add_f32_e64 v112, v132, v130
	v_add_f32_e64 v113, v133, v131
	v_add_f32_e64 v112, v134, v112
	v_add_f32_e64 v113, v135, v113
	v_add_f32_e64 v112, v136, v112
	v_add_f32_e64 v113, v137, v113
	v_pk_add_f32 v[130:131], v[138:139], v[112:113]
	v_pk_fma_f32 v[112:113], v[120:121], s[96:97], v[12:13] op_sel_hi:[1,0,0]
	v_exp_f32_e32 v120, v112
	v_exp_f32_e32 v121, v113
	v_pk_fma_f32 v[114:115], v[122:123], s[96:97], v[12:13] op_sel_hi:[1,0,0]
	v_exp_f32_e32 v122, v114
	v_exp_f32_e32 v123, v115
	v_cvt_pk_bf16_f32 v112, v120, v121
	v_pk_fma_f32 v[114:115], v[124:125], s[96:97], v[12:13] op_sel_hi:[1,0,0]
	v_exp_f32_e32 v124, v114
	v_exp_f32_e32 v125, v115
	v_cvt_pk_bf16_f32 v113, v122, v123
	v_pk_fma_f32 v[116:117], v[126:127], s[96:97], v[12:13] op_sel_hi:[1,0,0]
	v_exp_f32_e32 v126, v116
	v_exp_f32_e32 v127, v117
	v_cvt_pk_bf16_f32 v114, v124, v125
	v_cvt_pk_bf16_f32 v115, v126, v127
	s_waitcnt lgkmcnt(0)
	s_nop 0
	v_mfma_f32_32x32x16_bf16 v[96:111], v[240:243], v[112:115], v[96:111]
	s_waitcnt lgkmcnt(0)
	v_mfma_f32_32x32x16_bf16 v[80:95], v[244:247], v[112:115], v[80:95]
	v_add_f32_e64 v112, v120, v130
	v_add_f32_e64 v113, v121, v131
	v_add_f32_e64 v112, v122, v112
	v_add_f32_e64 v113, v123, v113
	v_add_f32_e64 v112, v124, v112
	v_add_f32_e64 v113, v125, v113
	v_pk_add_f32 v[112:113], v[126:127], v[112:113]
	v_add_f32_e32 v12, v112, v113
	ds_bpermute_b32 v112, v165, v12
	s_waitcnt lgkmcnt(0)
	v_add_f32_e32 v12, v12, v112
	v_add_f32_e32 v170, v170, v12

; #define MFMA(a, b, c) __builtin_amdgcn_mfma_f32_32x32x16_bf16((a), (b), (c), 0, 0, 0)
; template <int DK, int DV, int MODE>
; DI void fa_qk(f32x16 (&S)[2], const bf16x8 (&q)[DK / 16], const char* base, int lr, int lh) {
;   using C = FA<DK, DV>;
; #pragma unroll
;   for (int ks = 0; ks < 2; ++ks) {
; #pragma unroll
;     for (int kk = 0; kk < DK / 16; ++kk) {
;       const bf16x8 kf = *(const bf16x8*)(base + (ks * 32 + lr) * C::KSTR + (kk * 2 + lh) * 16);
;       if (kk == 0) {
; #pragma unroll
;         for (int i = 0; i < 16; ++i) S[ks][i] = 0.f;
;       }
;       S[ks] = MFMA(kf, q[kk], S[ks]);
;     }
;   }
; }
;     ...
;   if (MODE != 0) need_mask = (kb * 64 + 63 > wave_qmax - 31);
;   if (MODE == 2) selbit = (sel >> kb) & 1ull;
;   if (MODE == 3) need_mask = need_mask || (kb * 64 <= wave_qmax - 512);
.LBB0_597:
	s_cmp_gt_i32 s7, s20
	s_cbranch_scc1 .LBB0_586
	s_add_i32 s0, s0, 0
	v_add3_u32 v12, s0, v172, v171
	ds_read_b128 v[216:219], v12
	ds_read_b128 v[220:223], v12 offset:32
	ds_read_b128 v[224:227], v12 offset:64
	ds_read_b128 v[228:231], v12 offset:96
	ds_read_b128 v[232:235], v12 offset:4608
	ds_read_b128 v[236:239], v12 offset:4640
	ds_read_b128 v[240:243], v12 offset:4672
	ds_read_b128 v[244:247], v12 offset:4704
	s_add_i32 s1, s7, 31
	s_cmp_gt_i32 s1, s43
	s_cselect_b64 s[8:9], -1, 0
	s_cmp_le_i32 s7, s19
	s_cselect_b64 s[10:11], -1, 0
	s_or_b64 s[8:9], s[8:9], s[10:11]
	s_andn2_b64 vcc, exec, s[8:9]
	s_waitcnt lgkmcnt(7)
	v_mfma_f32_32x32x16_bf16 v[128:143], v[216:219], v[152:155], 0
	s_waitcnt lgkmcnt(6)
	v_mfma_f32_32x32x16_bf16 v[128:143], v[220:223], v[144:147], v[128:143]
	s_waitcnt lgkmcnt(5)
	v_mfma_f32_32x32x16_bf16 v[128:143], v[224:227], v[148:151], v[128:143]
	s_waitcnt lgkmcnt(4)
	v_mfma_f32_32x32x16_bf16 v[128:143], v[228:231], v[156:159], v[128:143]
	s_waitcnt lgkmcnt(3)
	v_mfma_f32_32x32x16_bf16 v[112:127], v[232:235], v[152:155], 0
	s_waitcnt lgkmcnt(2)
	v_mfma_f32_32x32x16_bf16 v[112:127], v[236:239], v[144:147], v[112:127]
	s_waitcnt lgkmcnt(1)
	v_mfma_f32_32x32x16_bf16 v[112:127], v[240:243], v[148:151], v[112:127]
	s_waitcnt lgkmcnt(0)
	v_mfma_f32_32x32x16_bf16 v[112:127], v[244:247], v[156:159], v[112:127]
	v_add3_u32 v247, s0, v175, v172
	v_add_u32_e32 v243, 0x2000, v247
	v_add_u32_e32 v247, 0x3000, v247
	ds_read2_b64 v[216:219], v243 offset0:128 offset1:130
	ds_read2_b64 v[220:223], v247 offset0:192 offset1:194
	ds_read2_b64 v[224:227], v243 offset0:132 offset1:134
	ds_read2_b64 v[228:231], v247 offset0:196 offset1:198
	ds_read2_b64 v[232:235], v243 offset0:136 offset1:138
	ds_read2_b64 v[236:239], v247 offset0:200 offset1:202
	ds_read2_b64 v[240:243], v243 offset0:140 offset1:142
	ds_read2_b64 v[244:247], v247 offset0:204 offset1:206
	s_cbranch_vccnz .LBB0_600
; DI int crow(int i, int h) { return (i & 3) + 8 * (i >> 2) + 4 * h; }
;     ...
;   if (need_mask) {
; #pragma unroll
;     for (int ks = 0; ks < 2; ++ks)
; #pragma unroll
;       for (int i = 0; i < 16; ++i) {
;         const int key = kb * 64 + ks * 32 + crow(i, lh);
;         bool valid = key <= qpos;
;         if (MODE == 2) valid = valid && selbit;
;         if (MODE == 3) valid = valid && (qpos - key < 512);
;         S[ks][i] = valid ? S[ks][i] : -1e30f;
;       }
	v_add_u32_e32 v12, s7, v173
	v_cmp_le_i32_e32 vcc, v12, v162
	v_cmp_gt_i32_e64 s[10:11], v12, v174
	s_and_b64 vcc, vcc, s[10:11]
	v_cndmask_b32_e32 v128, v208, v128, vcc
	v_cmp_lt_i32_e32 vcc, v12, v162
	v_cmp_ge_i32_e64 s[10:11], v12, v174
	s_and_b64 vcc, vcc, s[10:11]
	v_add_u32_e32 v176, 2, v12
	v_cndmask_b32_e32 v129, v208, v129, vcc
	v_cmp_le_i32_e32 vcc, v176, v162
	v_cmp_gt_i32_e64 s[10:11], v176, v174
	s_and_b64 vcc, vcc, s[10:11]
	v_add_u32_e32 v176, 3, v12
	v_cndmask_b32_e32 v130, v208, v130, vcc
	v_cmp_le_i32_e32 vcc, v176, v162
	v_cmp_gt_i32_e64 s[10:11], v176, v174
	s_and_b64 vcc, vcc, s[10:11]
	v_add_u32_e32 v176, 8, v12
	v_cndmask_b32_e32 v131, v208, v131, vcc
	v_cmp_le_i32_e32 vcc, v176, v162
	v_cmp_gt_i32_e64 s[10:11], v176, v174
	s_and_b64 vcc, vcc, s[10:11]
	v_add_u32_e32 v176, 9, v12
	v_cndmask_b32_e32 v132, v208, v132, vcc
	v_cmp_le_i32_e32 vcc, v176, v162
	v_cmp_gt_i32_e64 s[10:11], v176, v174
	s_and_b64 vcc, vcc, s[10:11]
	v_add_u32_e32 v176, 10, v12
	v_cndmask_b32_e32 v133, v208, v133, vcc
	v_cmp_le_i32_e32 vcc, v176, v162
	v_cmp_gt_i32_e64 s[10:11], v176, v174
	s_and_b64 vcc, vcc, s[10:11]
	v_add_u32_e32 v176, 11, v12
	v_cndmask_b32_e32 v134, v208, v134, vcc
	v_cmp_le_i32_e32 vcc, v176, v162
	v_cmp_gt_i32_e64 s[10:11], v176, v174
	s_and_b64 vcc, vcc, s[10:11]
	v_add_u32_e32 v176, 16, v12
	v_cndmask_b32_e32 v135, v208, v135, vcc
	v_cmp_le_i32_e32 vcc, v176, v162
	v_cmp_gt_i32_e64 s[10:11], v176, v174
	s_and_b64 vcc, vcc, s[10:11]
	v_add_u32_e32 v176, 17, v12
	v_cndmask_b32_e32 v136, v208, v136, vcc
	v_cmp_le_i32_e32 vcc, v176, v162
	v_cmp_gt_i32_e64 s[10:11], v176, v174
	s_and_b64 vcc, vcc, s[10:11]
	v_add_u32_e32 v176, 18, v12
	v_cndmask_b32_e32 v137, v208, v137, vcc
	v_cmp_le_i32_e32 vcc, v176, v162
	v_cmp_gt_i32_e64 s[10:11], v176, v174
	s_and_b64 vcc, vcc, s[10:11]
	v_add_u32_e32 v176, 19, v12
	v_cndmask_b32_e32 v138, v208, v138, vcc
	v_cmp_le_i32_e32 vcc, v176, v162
	v_cmp_gt_i32_e64 s[10:11], v176, v174
	s_and_b64 vcc, vcc, s[10:11]
	v_add_u32_e32 v176, 24, v12
	v_cndmask_b32_e32 v139, v208, v139, vcc
	v_cmp_le_i32_e32 vcc, v176, v162
	v_cmp_gt_i32_e64 s[10:11], v176, v174
	s_and_b64 vcc, vcc, s[10:11]
	v_add_u32_e32 v176, 25, v12
	v_cndmask_b32_e32 v140, v208, v140, vcc
	v_cmp_le_i32_e32 vcc, v176, v162
	v_cmp_gt_i32_e64 s[10:11], v176, v174
	s_and_b64 vcc, vcc, s[10:11]
	v_add_u32_e32 v176, 26, v12
	v_cndmask_b32_e32 v141, v208, v141, vcc
	v_cmp_le_i32_e32 vcc, v176, v162
	v_cmp_gt_i32_e64 s[10:11], v176, v174
	s_and_b64 vcc, vcc, s[10:11]
	v_add_u32_e32 v176, 27, v12
	v_cndmask_b32_e32 v142, v208, v142, vcc
	v_cmp_le_i32_e32 vcc, v176, v162
	v_cmp_gt_i32_e64 s[10:11], v176, v174
	s_and_b64 vcc, vcc, s[10:11]
	v_add_u32_e32 v176, 32, v12
	v_cndmask_b32_e32 v143, v208, v143, vcc
	v_cmp_le_i32_e32 vcc, v176, v162
	v_cmp_gt_i32_e64 s[10:11], v176, v174
	s_and_b64 vcc, vcc, s[10:11]
	v_add_u32_e32 v176, 33, v12
	v_cndmask_b32_e32 v112, v208, v112, vcc
	v_cmp_le_i32_e32 vcc, v176, v162
	v_cmp_gt_i32_e64 s[10:11], v176, v174
	s_and_b64 vcc, vcc, s[10:11]
	v_add_u32_e32 v176, 34, v12
	v_cndmask_b32_e32 v113, v208, v113, vcc
	v_cmp_le_i32_e32 vcc, v176, v162
	v_cmp_gt_i32_e64 s[10:11], v176, v174
	s_and_b64 vcc, vcc, s[10:11]
	v_add_u32_e32 v176, 35, v12
	v_cndmask_b32_e32 v114, v208, v114, vcc
	v_cmp_le_i32_e32 vcc, v176, v162
	v_cmp_gt_i32_e64 s[10:11], v176, v174
	s_and_b64 vcc, vcc, s[10:11]
	v_add_u32_e32 v176, 40, v12
	v_cndmask_b32_e32 v115, v208, v115, vcc
	v_cmp_le_i32_e32 vcc, v176, v162
	v_cmp_gt_i32_e64 s[10:11], v176, v174
	s_and_b64 vcc, vcc, s[10:11]
	v_add_u32_e32 v176, 41, v12
	v_cndmask_b32_e32 v116, v208, v116, vcc
	v_cmp_le_i32_e32 vcc, v176, v162
	v_cmp_gt_i32_e64 s[10:11], v176, v174
	s_and_b64 vcc, vcc, s[10:11]
	v_add_u32_e32 v176, 42, v12
	v_cndmask_b32_e32 v117, v208, v117, vcc
	v_cmp_le_i32_e32 vcc, v176, v162
	v_cmp_gt_i32_e64 s[10:11], v176, v174
	s_and_b64 vcc, vcc, s[10:11]
	v_add_u32_e32 v176, 43, v12
	v_cndmask_b32_e32 v118, v208, v118, vcc
	v_cmp_le_i32_e32 vcc, v176, v162
	v_cmp_gt_i32_e64 s[10:11], v176, v174
	s_and_b64 vcc, vcc, s[10:11]
	v_add_u32_e32 v176, 48, v12
	v_cndmask_b32_e32 v119, v208, v119, vcc
	v_cmp_le_i32_e32 vcc, v176, v162
	v_cmp_gt_i32_e64 s[10:11], v176, v174
	s_and_b64 vcc, vcc, s[10:11]
	v_add_u32_e32 v176, 49, v12
	v_cndmask_b32_e32 v120, v208, v120, vcc
	v_cmp_le_i32_e32 vcc, v176, v162
	v_cmp_gt_i32_e64 s[10:11], v176, v174
	s_and_b64 vcc, vcc, s[10:11]
	v_add_u32_e32 v176, 50, v12
	v_cndmask_b32_e32 v121, v208, v121, vcc
	v_cmp_le_i32_e32 vcc, v176, v162
	v_cmp_gt_i32_e64 s[10:11], v176, v174
	s_and_b64 vcc, vcc, s[10:11]
	v_add_u32_e32 v176, 51, v12
	v_cndmask_b32_e32 v122, v208, v122, vcc
	v_cmp_le_i32_e32 vcc, v176, v162
	v_cmp_gt_i32_e64 s[10:11], v176, v174
	s_and_b64 vcc, vcc, s[10:11]
	v_add_u32_e32 v176, 56, v12
	v_cndmask_b32_e32 v123, v208, v123, vcc
	v_cmp_le_i32_e32 vcc, v176, v162
	v_cmp_gt_i32_e64 s[10:11], v176, v174
	s_and_b64 vcc, vcc, s[10:11]
	v_add_u32_e32 v176, 57, v12
	v_cndmask_b32_e32 v124, v208, v124, vcc
	v_cmp_le_i32_e32 vcc, v176, v162
	v_cmp_gt_i32_e64 s[10:11], v176, v174
	s_and_b64 vcc, vcc, s[10:11]
	v_add_u32_e32 v176, 58, v12
	v_cndmask_b32_e32 v125, v208, v125, vcc
	v_cmp_le_i32_e32 vcc, v176, v162
	v_cmp_gt_i32_e64 s[10:11], v176, v174
	s_and_b64 vcc, vcc, s[10:11]
	v_add_u32_e32 v12, 59, v12
	v_cndmask_b32_e32 v126, v208, v126, vcc
	v_cmp_le_i32_e32 vcc, v12, v162
	v_cmp_gt_i32_e64 s[10:11], v12, v174
	s_and_b64 vcc, vcc, s[10:11]
	v_cndmask_b32_e32 v127, v208, v127, vcc

; DI float bf2f(u16 v) { return __uint_as_float(((unsigned)v) << 16); }
; DI int crow(int i, int h) { return (i & 3) + 8 * (i >> 2) + 4 * h; }
; DI void phase_gemm_resid(const Params& p, const u16* A, int lda, int K, const u16* Bt, bool last_sub, float scl,
;                          int row0, int nrows, char* smem) {
;     ...
;   auto epi = [&](int xcd, int q, f32x16 (&acc)[4][2]) __attribute__((always_inline)) {
;     G256_EPI_IDS
;     const int mt = xcd * mpx + (q >> 5) * 8 + (q & 7), nt = (q >> 3) & 3;
; #pragma unroll
;     for (int ms = 0; ms < 4; ++ms)
; #pragma unroll
;       for (int ns = 0; ns < 2; ++ns)
; #pragma unroll
;         for (int i = 0; i < 16; ++i) {
;           const size_t row = (size_t)row0 + mt * 256 + wm * 128 + ms * 32 + crow(i, lh);
;           const int col = nt * 256 + wn * 64 + ns * 32 + lr;
;           __builtin_nontemporal_store(__builtin_bit_cast(u16, (_Float16)(ALPHA * bf2f(xres[row * D + col]) + scl * acc[ms][ns][i])), &r16[row * D + col]);
;         }
;   };
.LBB0_842:
	s_lshr_b32 s6, s48, 2
	s_and_b32 s7, s48, 7
	s_waitcnt vmcnt(1)
	v_mov_b32_e32 v132, v196
	s_and_b32 s6, s6, 8
	s_or_b32 s7, s7, s42
	s_waitcnt lgkmcnt(0)
	s_barrier
	s_add_i32 s7, s7, s6
	s_lshl_b32 s6, s7, 8
	s_add_i32 s62, s6, s37
	s_lshl_b32 s6, s48, 5
	s_and_b32 s6, s6, 0x300
	v_mfma_f32_32x32x16_bf16 v[18:33], v[134:137], v[150:153], v[18:33]
	v_mfma_f32_32x32x16_bf16 v[2:17], v[134:137], v[154:157], v[2:17]
	v_mfma_f32_32x32x16_bf16 v[114:129], v[158:161], v[150:153], v[114:129]
	v_mfma_f32_32x32x16_bf16 v[50:65], v[138:141], v[150:153], v[50:65]
	v_mfma_f32_32x32x16_bf16 v[34:49], v[138:141], v[154:157], v[34:49]
	v_mfma_f32_32x32x16_bf16 v[82:97], v[146:149], v[150:153], v[82:97]
	v_mfma_f32_32x32x16_bf16 v[66:81], v[146:149], v[154:157], v[66:81]
	v_mfma_f32_32x32x16_bf16 v[98:113], v[158:161], v[154:157], v[98:113]
	s_mov_b64 s[8:9], -1
	s_and_b64 vcc, exec, s[0:1]
	v_lshrrev_b32_e32 v163, 1, v196
	v_and_b32_e32 v163, 0xffffff80, v163
	v_lshrrev_b32_e32 v164, 3, v196
	v_and_b32_e32 v164, 4, v164
	v_add3_u32 v163, v163, v164, s62
	v_and_b32_e32 v164, 0xdf, v196
	v_or_b32_e32 v164, s6, v164
	v_lshl_add_u32 v162, v163, 10, v164
	v_lshlrev_b32_e32 v162, 1, v162
	s_add_u32 s98, s14, 0x1000
	s_addc_u32 s99, s15, 0
	s_add_u32 s100, s12, 0x1000
	s_addc_u32 s101, s13, 0
	global_load_ushort v130, v162, s[98:99] offset:-4096
	global_load_ushort v131, v162, s[98:99] offset:-4032
	global_load_ushort v132, v162, s[98:99] offset:-2048
	global_load_ushort v133, v162, s[98:99] offset:-1984
	global_load_ushort v134, v162, s[98:99] offset:0
	global_load_ushort v135, v162, s[98:99] offset:64
	global_load_ushort v136, v162, s[98:99] offset:2048
	global_load_ushort v137, v162, s[98:99] offset:2112
	s_add_u32 s98, s98, 0x4000
	s_addc_u32 s99, s99, 0
	global_load_ushort v138, v162, s[98:99] offset:-4096
	global_load_ushort v139, v162, s[98:99] offset:-4032
	global_load_ushort v140, v162, s[98:99] offset:-2048
	global_load_ushort v141, v162, s[98:99] offset:-1984
	global_load_ushort v142, v162, s[98:99] offset:0
	global_load_ushort v143, v162, s[98:99] offset:64
	global_load_ushort v144, v162, s[98:99] offset:2048
	global_load_ushort v145, v162, s[98:99] offset:2112
	s_add_u32 s98, s98, 0x4000
	s_addc_u32 s99, s99, 0
	global_load_ushort v146, v162, s[98:99] offset:-4096
	global_load_ushort v147, v162, s[98:99] offset:-4032
	global_load_ushort v148, v162, s[98:99] offset:-2048
	global_load_ushort v149, v162, s[98:99] offset:-1984
	global_load_ushort v150, v162, s[98:99] offset:0
	global_load_ushort v151, v162, s[98:99] offset:64
	global_load_ushort v152, v162, s[98:99] offset:2048
	global_load_ushort v153, v162, s[98:99] offset:2112
	s_add_u32 s98, s98, 0x4000
	s_addc_u32 s99, s99, 0
	global_load_ushort v154, v162, s[98:99] offset:-4096
	global_load_ushort v155, v162, s[98:99] offset:-4032
	global_load_ushort v156, v162, s[98:99] offset:-2048
	global_load_ushort v157, v162, s[98:99] offset:-1984
	global_load_ushort v158, v162, s[98:99] offset:0
	global_load_ushort v159, v162, s[98:99] offset:64
	global_load_ushort v160, v162, s[98:99] offset:2048
	global_load_ushort v161, v162, s[98:99] offset:2112
	s_add_u32 s98, s98, 0x4000
	s_addc_u32 s99, s99, 0
	s_waitcnt vmcnt(16)
	v_lshlrev_b32_e32 v130, 16, v130
	v_mul_f32_e32 v130, 0x3fb504f3, v130
	v_fma_mixlo_f16 v130, s36, v114, v130
	global_store_short v162, v130, s[100:101] offset:-4096 nt
	v_lshlrev_b32_e32 v131, 16, v131
	v_mul_f32_e32 v131, 0x3fb504f3, v131
	v_fma_mixlo_f16 v131, s36, v98, v131
	global_store_short v162, v131, s[100:101] offset:-4032 nt
	v_lshlrev_b32_e32 v132, 16, v132
	v_mul_f32_e32 v132, 0x3fb504f3, v132
	v_fma_mixlo_f16 v132, s36, v115, v132
	global_store_short v162, v132, s[100:101] offset:-2048 nt
	v_lshlrev_b32_e32 v133, 16, v133
	v_mul_f32_e32 v133, 0x3fb504f3, v133
	v_fma_mixlo_f16 v133, s36, v99, v133
	global_store_short v162, v133, s[100:101] offset:-1984 nt
	v_lshlrev_b32_e32 v134, 16, v134
	v_mul_f32_e32 v134, 0x3fb504f3, v134
	v_fma_mixlo_f16 v134, s36, v116, v134
	global_store_short v162, v134, s[100:101] offset:0 nt
	v_lshlrev_b32_e32 v135, 16, v135
	v_mul_f32_e32 v135, 0x3fb504f3, v135
	v_fma_mixlo_f16 v135, s36, v100, v135
	global_store_short v162, v135, s[100:101] offset:64 nt
	v_lshlrev_b32_e32 v136, 16, v136
	v_mul_f32_e32 v136, 0x3fb504f3, v136
	v_fma_mixlo_f16 v136, s36, v117, v136
	global_store_short v162, v136, s[100:101] offset:2048 nt
	v_lshlrev_b32_e32 v137, 16, v137
	v_mul_f32_e32 v137, 0x3fb504f3, v137
	v_fma_mixlo_f16 v137, s36, v101, v137
	global_store_short v162, v137, s[100:101] offset:2112 nt
	s_add_u32 s100, s100, 0x4000
	s_addc_u32 s101, s101, 0
	v_lshlrev_b32_e32 v138, 16, v138
	v_mul_f32_e32 v138, 0x3fb504f3, v138
	v_fma_mixlo_f16 v138, s36, v118, v138
	global_store_short v162, v138, s[100:101] offset:-4096 nt
	v_lshlrev_b32_e32 v139, 16, v139
	v_mul_f32_e32 v139, 0x3fb504f3, v139
	v_fma_mixlo_f16 v139, s36, v102, v139
	global_store_short v162, v139, s[100:101] offset:-4032 nt
	v_lshlrev_b32_e32 v140, 16, v140
	v_mul_f32_e32 v140, 0x3fb504f3, v140
	v_fma_mixlo_f16 v140, s36, v119, v140
	global_store_short v162, v140, s[100:101] offset:-2048 nt
	v_lshlrev_b32_e32 v141, 16, v141
	v_mul_f32_e32 v141, 0x3fb504f3, v141
	v_fma_mixlo_f16 v141, s36, v103, v141
	global_store_short v162, v141, s[100:101] offset:-1984 nt
	v_lshlrev_b32_e32 v142, 16, v142
	v_mul_f32_e32 v142, 0x3fb504f3, v142
	v_fma_mixlo_f16 v142, s36, v120, v142
	global_store_short v162, v142, s[100:101] offset:0 nt
	v_lshlrev_b32_e32 v143, 16, v143
	v_mul_f32_e32 v143, 0x3fb504f3, v143
	v_fma_mixlo_f16 v143, s36, v104, v143
	global_store_short v162, v143, s[100:101] offset:64 nt
	v_lshlrev_b32_e32 v144, 16, v144
	v_mul_f32_e32 v144, 0x3fb504f3, v144
	v_fma_mixlo_f16 v144, s36, v121, v144
	global_store_short v162, v144, s[100:101] offset:2048 nt
	v_lshlrev_b32_e32 v145, 16, v145
	v_mul_f32_e32 v145, 0x3fb504f3, v145
	v_fma_mixlo_f16 v145, s36, v105, v145
	global_store_short v162, v145, s[100:101] offset:2112 nt
	s_add_u32 s100, s100, 0x4000
	s_addc_u32 s101, s101, 0
	global_load_ushort v130, v162, s[98:99] offset:-4096
	global_load_ushort v131, v162, s[98:99] offset:-4032
	global_load_ushort v132, v162, s[98:99] offset:-2048
	global_load_ushort v133, v162, s[98:99] offset:-1984
	global_load_ushort v134, v162, s[98:99] offset:0
	global_load_ushort v135, v162, s[98:99] offset:64
	global_load_ushort v136, v162, s[98:99] offset:2048
	global_load_ushort v137, v162, s[98:99] offset:2112
	s_add_u32 s98, s98, 0x4000
	s_addc_u32 s99, s99, 0
	global_load_ushort v138, v162, s[98:99] offset:-4096
	global_load_ushort v139, v162, s[98:99] offset:-4032
	global_load_ushort v140, v162, s[98:99] offset:-2048
	global_load_ushort v141, v162, s[98:99] offset:-1984
	global_load_ushort v142, v162, s[98:99] offset:0
	global_load_ushort v143, v162, s[98:99] offset:64
	global_load_ushort v144, v162, s[98:99] offset:2048
	global_load_ushort v145, v162, s[98:99] offset:2112
	s_add_u32 s98, s98, 0x4000
	s_addc_u32 s99, s99, 0
	s_waitcnt vmcnt(32)
; DI float bf2f(u16 v) { return __uint_as_float(((unsigned)v) << 16); }
; DI int crow(int i, int h) { return (i & 3) + 8 * (i >> 2) + 4 * h; }
; DI void phase_gemm_resid(const Params& p, const u16* A, int lda, int K, const u16* Bt, bool last_sub, float scl,
;                          int row0, int nrows, char* smem) {
;     ...
; #pragma unroll
;     for (int ms = 0; ms < 4; ++ms)
; #pragma unroll
;       for (int ns = 0; ns < 2; ++ns)
; #pragma unroll
;         for (int i = 0; i < 16; ++i) {
;           const size_t row = (size_t)row0 + mt * 256 + wm * 128 + ms * 32 + crow(i, lh);
;           const int col = nt * 256 + wn * 64 + ns * 32 + lr;
;           __builtin_nontemporal_store(__builtin_bit_cast(u16, (_Float16)(ALPHA * bf2f(xres[row * D + col]) + scl * acc[ms][ns][i])), &r16[row * D + col]);
;         }
;   };
	v_lshlrev_b32_e32 v146, 16, v146
	v_mul_f32_e32 v146, 0x3fb504f3, v146
	v_fma_mixlo_f16 v146, s36, v122, v146
	global_store_short v162, v146, s[100:101] offset:-4096 nt
	v_lshlrev_b32_e32 v147, 16, v147
	v_mul_f32_e32 v147, 0x3fb504f3, v147
	v_fma_mixlo_f16 v147, s36, v106, v147
	global_store_short v162, v147, s[100:101] offset:-4032 nt
	v_lshlrev_b32_e32 v148, 16, v148
	v_mul_f32_e32 v148, 0x3fb504f3, v148
	v_fma_mixlo_f16 v148, s36, v123, v148
	global_store_short v162, v148, s[100:101] offset:-2048 nt
	v_lshlrev_b32_e32 v149, 16, v149
	v_mul_f32_e32 v149, 0x3fb504f3, v149
	v_fma_mixlo_f16 v149, s36, v107, v149
	global_store_short v162, v149, s[100:101] offset:-1984 nt
	v_lshlrev_b32_e32 v150, 16, v150
	v_mul_f32_e32 v150, 0x3fb504f3, v150
	v_fma_mixlo_f16 v150, s36, v124, v150
	global_store_short v162, v150, s[100:101] offset:0 nt
	v_lshlrev_b32_e32 v151, 16, v151
	v_mul_f32_e32 v151, 0x3fb504f3, v151
	v_fma_mixlo_f16 v151, s36, v108, v151
	global_store_short v162, v151, s[100:101] offset:64 nt
	v_lshlrev_b32_e32 v152, 16, v152
	v_mul_f32_e32 v152, 0x3fb504f3, v152
	v_fma_mixlo_f16 v152, s36, v125, v152
	global_store_short v162, v152, s[100:101] offset:2048 nt
	v_lshlrev_b32_e32 v153, 16, v153
	v_mul_f32_e32 v153, 0x3fb504f3, v153
	v_fma_mixlo_f16 v153, s36, v109, v153
	global_store_short v162, v153, s[100:101] offset:2112 nt
	s_add_u32 s100, s100, 0x4000
	s_addc_u32 s101, s101, 0
	v_lshlrev_b32_e32 v154, 16, v154
	v_mul_f32_e32 v154, 0x3fb504f3, v154
	v_fma_mixlo_f16 v154, s36, v126, v154
	global_store_short v162, v154, s[100:101] offset:-4096 nt
	v_lshlrev_b32_e32 v155, 16, v155
	v_mul_f32_e32 v155, 0x3fb504f3, v155
	v_fma_mixlo_f16 v155, s36, v110, v155
	global_store_short v162, v155, s[100:101] offset:-4032 nt
	v_lshlrev_b32_e32 v156, 16, v156
	v_mul_f32_e32 v156, 0x3fb504f3, v156
	v_fma_mixlo_f16 v156, s36, v127, v156
	global_store_short v162, v156, s[100:101] offset:-2048 nt
	v_lshlrev_b32_e32 v157, 16, v157
	v_mul_f32_e32 v157, 0x3fb504f3, v157
	v_fma_mixlo_f16 v157, s36, v111, v157
	global_store_short v162, v157, s[100:101] offset:-1984 nt
	v_lshlrev_b32_e32 v158, 16, v158
	v_mul_f32_e32 v158, 0x3fb504f3, v158
	v_fma_mixlo_f16 v158, s36, v128, v158
	global_store_short v162, v158, s[100:101] offset:0 nt
	v_lshlrev_b32_e32 v159, 16, v159
	v_mul_f32_e32 v159, 0x3fb504f3, v159
	v_fma_mixlo_f16 v159, s36, v112, v159
	global_store_short v162, v159, s[100:101] offset:64 nt
	v_lshlrev_b32_e32 v160, 16, v160
	v_mul_f32_e32 v160, 0x3fb504f3, v160
	v_fma_mixlo_f16 v160, s36, v129, v160
	global_store_short v162, v160, s[100:101] offset:2048 nt
	v_lshlrev_b32_e32 v161, 16, v161
	v_mul_f32_e32 v161, 0x3fb504f3, v161
	v_fma_mixlo_f16 v161, s36, v113, v161
	global_store_short v162, v161, s[100:101] offset:2112 nt
	s_add_u32 s100, s100, 0x4000
	s_addc_u32 s101, s101, 0
	global_load_ushort v146, v162, s[98:99] offset:-4096
	global_load_ushort v147, v162, s[98:99] offset:-4032
	global_load_ushort v148, v162, s[98:99] offset:-2048
	global_load_ushort v149, v162, s[98:99] offset:-1984
	global_load_ushort v150, v162, s[98:99] offset:0
	global_load_ushort v151, v162, s[98:99] offset:64
	global_load_ushort v152, v162, s[98:99] offset:2048
	global_load_ushort v153, v162, s[98:99] offset:2112
	s_add_u32 s98, s98, 0x4000
	s_addc_u32 s99, s99, 0
	global_load_ushort v154, v162, s[98:99] offset:-4096
	global_load_ushort v155, v162, s[98:99] offset:-4032
	global_load_ushort v156, v162, s[98:99] offset:-2048
	global_load_ushort v157, v162, s[98:99] offset:-1984
	global_load_ushort v158, v162, s[98:99] offset:0
	global_load_ushort v159, v162, s[98:99] offset:64
	global_load_ushort v160, v162, s[98:99] offset:2048
	global_load_ushort v161, v162, s[98:99] offset:2112
	s_add_u32 s98, s98, 0x4000
	s_addc_u32 s99, s99, 0
	s_waitcnt vmcnt(32)
	v_lshlrev_b32_e32 v130, 16, v130
	v_mul_f32_e32 v130, 0x3fb504f3, v130
	v_fma_mixlo_f16 v130, s36, v82, v130
	global_store_short v162, v130, s[100:101] offset:-4096 nt
	v_lshlrev_b32_e32 v131, 16, v131
	v_mul_f32_e32 v131, 0x3fb504f3, v131
	v_fma_mixlo_f16 v131, s36, v66, v131
	global_store_short v162, v131, s[100:101] offset:-4032 nt
	v_lshlrev_b32_e32 v132, 16, v132
	v_mul_f32_e32 v132, 0x3fb504f3, v132
	v_fma_mixlo_f16 v132, s36, v83, v132
	global_store_short v162, v132, s[100:101] offset:-2048 nt
	v_lshlrev_b32_e32 v133, 16, v133
	v_mul_f32_e32 v133, 0x3fb504f3, v133
	v_fma_mixlo_f16 v133, s36, v67, v133
	global_store_short v162, v133, s[100:101] offset:-1984 nt
	v_lshlrev_b32_e32 v134, 16, v134
	v_mul_f32_e32 v134, 0x3fb504f3, v134
	v_fma_mixlo_f16 v134, s36, v84, v134
	global_store_short v162, v134, s[100:101] offset:0 nt
	v_lshlrev_b32_e32 v135, 16, v135
	v_mul_f32_e32 v135, 0x3fb504f3, v135
	v_fma_mixlo_f16 v135, s36, v68, v135
	global_store_short v162, v135, s[100:101] offset:64 nt
	v_lshlrev_b32_e32 v136, 16, v136
	v_mul_f32_e32 v136, 0x3fb504f3, v136
	v_fma_mixlo_f16 v136, s36, v85, v136
	global_store_short v162, v136, s[100:101] offset:2048 nt
	v_lshlrev_b32_e32 v137, 16, v137
	v_mul_f32_e32 v137, 0x3fb504f3, v137
	v_fma_mixlo_f16 v137, s36, v69, v137
	global_store_short v162, v137, s[100:101] offset:2112 nt
	s_add_u32 s100, s100, 0x4000
	s_addc_u32 s101, s101, 0
	v_lshlrev_b32_e32 v138, 16, v138
	v_mul_f32_e32 v138, 0x3fb504f3, v138
	v_fma_mixlo_f16 v138, s36, v86, v138
	global_store_short v162, v138, s[100:101] offset:-4096 nt
	v_lshlrev_b32_e32 v139, 16, v139
	v_mul_f32_e32 v139, 0x3fb504f3, v139
	v_fma_mixlo_f16 v139, s36, v70, v139
	global_store_short v162, v139, s[100:101] offset:-4032 nt
	v_lshlrev_b32_e32 v140, 16, v140
	v_mul_f32_e32 v140, 0x3fb504f3, v140
	v_fma_mixlo_f16 v140, s36, v87, v140
; DI float bf2f(u16 v) { return __uint_as_float(((unsigned)v) << 16); }
; DI int crow(int i, int h) { return (i & 3) + 8 * (i >> 2) + 4 * h; }
; DI void phase_gemm_resid(const Params& p, const u16* A, int lda, int K, const u16* Bt, bool last_sub, float scl,
;                          int row0, int nrows, char* smem) {
;     ...
; #pragma unroll
;     for (int ms = 0; ms < 4; ++ms)
; #pragma unroll
;       for (int ns = 0; ns < 2; ++ns)
; #pragma unroll
;         for (int i = 0; i < 16; ++i) {
;           const size_t row = (size_t)row0 + mt * 256 + wm * 128 + ms * 32 + crow(i, lh);
;           const int col = nt * 256 + wn * 64 + ns * 32 + lr;
;           __builtin_nontemporal_store(__builtin_bit_cast(u16, (_Float16)(ALPHA * bf2f(xres[row * D + col]) + scl * acc[ms][ns][i])), &r16[row * D + col]);
;         }
;   };
	global_store_short v162, v140, s[100:101] offset:-2048 nt
	v_lshlrev_b32_e32 v141, 16, v141
	v_mul_f32_e32 v141, 0x3fb504f3, v141
	v_fma_mixlo_f16 v141, s36, v71, v141
	global_store_short v162, v141, s[100:101] offset:-1984 nt
	v_lshlrev_b32_e32 v142, 16, v142
	v_mul_f32_e32 v142, 0x3fb504f3, v142
	v_fma_mixlo_f16 v142, s36, v88, v142
	global_store_short v162, v142, s[100:101] offset:0 nt
	v_lshlrev_b32_e32 v143, 16, v143
	v_mul_f32_e32 v143, 0x3fb504f3, v143
	v_fma_mixlo_f16 v143, s36, v72, v143
	global_store_short v162, v143, s[100:101] offset:64 nt
	v_lshlrev_b32_e32 v144, 16, v144
	v_mul_f32_e32 v144, 0x3fb504f3, v144
	v_fma_mixlo_f16 v144, s36, v89, v144
	global_store_short v162, v144, s[100:101] offset:2048 nt
	v_lshlrev_b32_e32 v145, 16, v145
	v_mul_f32_e32 v145, 0x3fb504f3, v145
	v_fma_mixlo_f16 v145, s36, v73, v145
	global_store_short v162, v145, s[100:101] offset:2112 nt
	s_add_u32 s100, s100, 0x4000
	s_addc_u32 s101, s101, 0
	global_load_ushort v130, v162, s[98:99] offset:-4096
	global_load_ushort v131, v162, s[98:99] offset:-4032
	global_load_ushort v132, v162, s[98:99] offset:-2048
	global_load_ushort v133, v162, s[98:99] offset:-1984
	global_load_ushort v134, v162, s[98:99] offset:0
	global_load_ushort v135, v162, s[98:99] offset:64
	global_load_ushort v136, v162, s[98:99] offset:2048
	global_load_ushort v137, v162, s[98:99] offset:2112
	s_add_u32 s98, s98, 0x4000
	s_addc_u32 s99, s99, 0
	global_load_ushort v138, v162, s[98:99] offset:-4096
	global_load_ushort v139, v162, s[98:99] offset:-4032
	global_load_ushort v140, v162, s[98:99] offset:-2048
	global_load_ushort v141, v162, s[98:99] offset:-1984
	global_load_ushort v142, v162, s[98:99] offset:0
	global_load_ushort v143, v162, s[98:99] offset:64
	global_load_ushort v144, v162, s[98:99] offset:2048
	global_load_ushort v145, v162, s[98:99] offset:2112
	s_add_u32 s98, s98, 0x4000
	s_addc_u32 s99, s99, 0
	s_waitcnt vmcnt(32)
	v_lshlrev_b32_e32 v146, 16, v146
	v_mul_f32_e32 v146, 0x3fb504f3, v146
	v_fma_mixlo_f16 v146, s36, v90, v146
	global_store_short v162, v146, s[100:101] offset:-4096 nt
	v_lshlrev_b32_e32 v147, 16, v147
	v_mul_f32_e32 v147, 0x3fb504f3, v147
	v_fma_mixlo_f16 v147, s36, v74, v147
	global_store_short v162, v147, s[100:101] offset:-4032 nt
	v_lshlrev_b32_e32 v148, 16, v148
	v_mul_f32_e32 v148, 0x3fb504f3, v148
	v_fma_mixlo_f16 v148, s36, v91, v148
	global_store_short v162, v148, s[100:101] offset:-2048 nt
	v_lshlrev_b32_e32 v149, 16, v149
	v_mul_f32_e32 v149, 0x3fb504f3, v149
	v_fma_mixlo_f16 v149, s36, v75, v149
	global_store_short v162, v149, s[100:101] offset:-1984 nt
	v_lshlrev_b32_e32 v150, 16, v150
	v_mul_f32_e32 v150, 0x3fb504f3, v150
	v_fma_mixlo_f16 v150, s36, v92, v150
	global_store_short v162, v150, s[100:101] offset:0 nt
	v_lshlrev_b32_e32 v151, 16, v151
	v_mul_f32_e32 v151, 0x3fb504f3, v151
	v_fma_mixlo_f16 v151, s36, v76, v151
	global_store_short v162, v151, s[100:101] offset:64 nt
	v_lshlrev_b32_e32 v152, 16, v152
	v_mul_f32_e32 v152, 0x3fb504f3, v152
	v_fma_mixlo_f16 v152, s36, v93, v152
	global_store_short v162, v152, s[100:101] offset:2048 nt
	v_lshlrev_b32_e32 v153, 16, v153
	v_mul_f32_e32 v153, 0x3fb504f3, v153
	v_fma_mixlo_f16 v153, s36, v77, v153
	global_store_short v162, v153, s[100:101] offset:2112 nt
	s_add_u32 s100, s100, 0x4000
	s_addc_u32 s101, s101, 0
	v_lshlrev_b32_e32 v154, 16, v154
	v_mul_f32_e32 v154, 0x3fb504f3, v154
	v_fma_mixlo_f16 v154, s36, v94, v154
	global_store_short v162, v154, s[100:101] offset:-4096 nt
	v_lshlrev_b32_e32 v155, 16, v155
	v_mul_f32_e32 v155, 0x3fb504f3, v155
	v_fma_mixlo_f16 v155, s36, v78, v155
	global_store_short v162, v155, s[100:101] offset:-4032 nt
	v_lshlrev_b32_e32 v156, 16, v156
	v_mul_f32_e32 v156, 0x3fb504f3, v156
	v_fma_mixlo_f16 v156, s36, v95, v156
	global_store_short v162, v156, s[100:101] offset:-2048 nt
	v_lshlrev_b32_e32 v157, 16, v157
	v_mul_f32_e32 v157, 0x3fb504f3, v157
	v_fma_mixlo_f16 v157, s36, v79, v157
	global_store_short v162, v157, s[100:101] offset:-1984 nt
	v_lshlrev_b32_e32 v158, 16, v158
	v_mul_f32_e32 v158, 0x3fb504f3, v158
	v_fma_mixlo_f16 v158, s36, v96, v158
	global_store_short v162, v158, s[100:101] offset:0 nt
	v_lshlrev_b32_e32 v159, 16, v159
	v_mul_f32_e32 v159, 0x3fb504f3, v159
	v_fma_mixlo_f16 v159, s36, v80, v159
	global_store_short v162, v159, s[100:101] offset:64 nt
	v_lshlrev_b32_e32 v160, 16, v160
	v_mul_f32_e32 v160, 0x3fb504f3, v160
	v_fma_mixlo_f16 v160, s36, v97, v160
	global_store_short v162, v160, s[100:101] offset:2048 nt
	v_lshlrev_b32_e32 v161, 16, v161
	v_mul_f32_e32 v161, 0x3fb504f3, v161
	v_fma_mixlo_f16 v161, s36, v81, v161
	global_store_short v162, v161, s[100:101] offset:2112 nt
	s_add_u32 s100, s100, 0x4000
	s_addc_u32 s101, s101, 0
	global_load_ushort v146, v162, s[98:99] offset:-4096
	global_load_ushort v147, v162, s[98:99] offset:-4032
	global_load_ushort v148, v162, s[98:99] offset:-2048
	global_load_ushort v149, v162, s[98:99] offset:-1984
	global_load_ushort v150, v162, s[98:99] offset:0
	global_load_ushort v151, v162, s[98:99] offset:64
	global_load_ushort v152, v162, s[98:99] offset:2048
	global_load_ushort v153, v162, s[98:99] offset:2112
	s_add_u32 s98, s98, 0x4000
	s_addc_u32 s99, s99, 0
	global_load_ushort v154, v162, s[98:99] offset:-4096
	global_load_ushort v155, v162, s[98:99] offset:-4032
	global_load_ushort v156, v162, s[98:99] offset:-2048
	global_load_ushort v157, v162, s[98:99] offset:-1984
	global_load_ushort v158, v162, s[98:99] offset:0
	global_load_ushort v159, v162, s[98:99] offset:64
	global_load_ushort v160, v162, s[98:99] offset:2048
	global_load_ushort v161, v162, s[98:99] offset:2112
	s_add_u32 s98, s98, 0x4000
	s_addc_u32 s99, s99, 0
	s_waitcnt vmcnt(32)
; DI float bf2f(u16 v) { return __uint_as_float(((unsigned)v) << 16); }
; DI int crow(int i, int h) { return (i & 3) + 8 * (i >> 2) + 4 * h; }
; DI void phase_gemm_resid(const Params& p, const u16* A, int lda, int K, const u16* Bt, bool last_sub, float scl,
;                          int row0, int nrows, char* smem) {
;     ...
; #pragma unroll
;     for (int ms = 0; ms < 4; ++ms)
; #pragma unroll
;       for (int ns = 0; ns < 2; ++ns)
; #pragma unroll
;         for (int i = 0; i < 16; ++i) {
;           const size_t row = (size_t)row0 + mt * 256 + wm * 128 + ms * 32 + crow(i, lh);
;           const int col = nt * 256 + wn * 64 + ns * 32 + lr;
;           __builtin_nontemporal_store(__builtin_bit_cast(u16, (_Float16)(ALPHA * bf2f(xres[row * D + col]) + scl * acc[ms][ns][i])), &r16[row * D + col]);
;         }
;   };
	v_lshlrev_b32_e32 v130, 16, v130
	v_mul_f32_e32 v130, 0x3fb504f3, v130
	v_fma_mixlo_f16 v130, s36, v50, v130
	global_store_short v162, v130, s[100:101] offset:-4096 nt
	v_lshlrev_b32_e32 v131, 16, v131
	v_mul_f32_e32 v131, 0x3fb504f3, v131
	v_fma_mixlo_f16 v131, s36, v34, v131
	global_store_short v162, v131, s[100:101] offset:-4032 nt
	v_lshlrev_b32_e32 v132, 16, v132
	v_mul_f32_e32 v132, 0x3fb504f3, v132
	v_fma_mixlo_f16 v132, s36, v51, v132
	global_store_short v162, v132, s[100:101] offset:-2048 nt
	v_lshlrev_b32_e32 v133, 16, v133
	v_mul_f32_e32 v133, 0x3fb504f3, v133
	v_fma_mixlo_f16 v133, s36, v35, v133
	global_store_short v162, v133, s[100:101] offset:-1984 nt
	v_lshlrev_b32_e32 v134, 16, v134
	v_mul_f32_e32 v134, 0x3fb504f3, v134
	v_fma_mixlo_f16 v134, s36, v52, v134
	global_store_short v162, v134, s[100:101] offset:0 nt
	v_lshlrev_b32_e32 v135, 16, v135
	v_mul_f32_e32 v135, 0x3fb504f3, v135
	v_fma_mixlo_f16 v135, s36, v36, v135
	global_store_short v162, v135, s[100:101] offset:64 nt
	v_lshlrev_b32_e32 v136, 16, v136
	v_mul_f32_e32 v136, 0x3fb504f3, v136
	v_fma_mixlo_f16 v136, s36, v53, v136
	global_store_short v162, v136, s[100:101] offset:2048 nt
	v_lshlrev_b32_e32 v137, 16, v137
	v_mul_f32_e32 v137, 0x3fb504f3, v137
	v_fma_mixlo_f16 v137, s36, v37, v137
	global_store_short v162, v137, s[100:101] offset:2112 nt
	s_add_u32 s100, s100, 0x4000
	s_addc_u32 s101, s101, 0
	v_lshlrev_b32_e32 v138, 16, v138
	v_mul_f32_e32 v138, 0x3fb504f3, v138
	v_fma_mixlo_f16 v138, s36, v54, v138
	global_store_short v162, v138, s[100:101] offset:-4096 nt
	v_lshlrev_b32_e32 v139, 16, v139
	v_mul_f32_e32 v139, 0x3fb504f3, v139
	v_fma_mixlo_f16 v139, s36, v38, v139
	global_store_short v162, v139, s[100:101] offset:-4032 nt
	v_lshlrev_b32_e32 v140, 16, v140
	v_mul_f32_e32 v140, 0x3fb504f3, v140
	v_fma_mixlo_f16 v140, s36, v55, v140
	global_store_short v162, v140, s[100:101] offset:-2048 nt
	v_lshlrev_b32_e32 v141, 16, v141
	v_mul_f32_e32 v141, 0x3fb504f3, v141
	v_fma_mixlo_f16 v141, s36, v39, v141
	global_store_short v162, v141, s[100:101] offset:-1984 nt
	v_lshlrev_b32_e32 v142, 16, v142
	v_mul_f32_e32 v142, 0x3fb504f3, v142
	v_fma_mixlo_f16 v142, s36, v56, v142
	global_store_short v162, v142, s[100:101] offset:0 nt
	v_lshlrev_b32_e32 v143, 16, v143
	v_mul_f32_e32 v143, 0x3fb504f3, v143
	v_fma_mixlo_f16 v143, s36, v40, v143
	global_store_short v162, v143, s[100:101] offset:64 nt
	v_lshlrev_b32_e32 v144, 16, v144
	v_mul_f32_e32 v144, 0x3fb504f3, v144
	v_fma_mixlo_f16 v144, s36, v57, v144
	global_store_short v162, v144, s[100:101] offset:2048 nt
	v_lshlrev_b32_e32 v145, 16, v145
	v_mul_f32_e32 v145, 0x3fb504f3, v145
	v_fma_mixlo_f16 v145, s36, v41, v145
	global_store_short v162, v145, s[100:101] offset:2112 nt
	s_add_u32 s100, s100, 0x4000
	s_addc_u32 s101, s101, 0
	global_load_ushort v130, v162, s[98:99] offset:-4096
	global_load_ushort v131, v162, s[98:99] offset:-4032
	global_load_ushort v132, v162, s[98:99] offset:-2048
	global_load_ushort v133, v162, s[98:99] offset:-1984
	global_load_ushort v134, v162, s[98:99] offset:0
	global_load_ushort v135, v162, s[98:99] offset:64
	global_load_ushort v136, v162, s[98:99] offset:2048
	global_load_ushort v137, v162, s[98:99] offset:2112
	s_add_u32 s98, s98, 0x4000
	s_addc_u32 s99, s99, 0
	global_load_ushort v138, v162, s[98:99] offset:-4096
	global_load_ushort v139, v162, s[98:99] offset:-4032
	global_load_ushort v140, v162, s[98:99] offset:-2048
	global_load_ushort v141, v162, s[98:99] offset:-1984
	global_load_ushort v142, v162, s[98:99] offset:0
	global_load_ushort v143, v162, s[98:99] offset:64
	global_load_ushort v144, v162, s[98:99] offset:2048
	global_load_ushort v145, v162, s[98:99] offset:2112
	s_add_u32 s98, s98, 0x4000
	s_addc_u32 s99, s99, 0
	s_waitcnt vmcnt(32)
	v_lshlrev_b32_e32 v146, 16, v146
	v_mul_f32_e32 v146, 0x3fb504f3, v146
	v_fma_mixlo_f16 v146, s36, v58, v146
	global_store_short v162, v146, s[100:101] offset:-4096 nt
	v_lshlrev_b32_e32 v147, 16, v147
	v_mul_f32_e32 v147, 0x3fb504f3, v147
	v_fma_mixlo_f16 v147, s36, v42, v147
	global_store_short v162, v147, s[100:101] offset:-4032 nt
	v_lshlrev_b32_e32 v148, 16, v148
	v_mul_f32_e32 v148, 0x3fb504f3, v148
	v_fma_mixlo_f16 v148, s36, v59, v148
	global_store_short v162, v148, s[100:101] offset:-2048 nt
	v_lshlrev_b32_e32 v149, 16, v149
	v_mul_f32_e32 v149, 0x3fb504f3, v149
	v_fma_mixlo_f16 v149, s36, v43, v149
	global_store_short v162, v149, s[100:101] offset:-1984 nt
	v_lshlrev_b32_e32 v150, 16, v150
	v_mul_f32_e32 v150, 0x3fb504f3, v150
	v_fma_mixlo_f16 v150, s36, v60, v150
	global_store_short v162, v150, s[100:101] offset:0 nt
	v_lshlrev_b32_e32 v151, 16, v151
	v_mul_f32_e32 v151, 0x3fb504f3, v151
	v_fma_mixlo_f16 v151, s36, v44, v151
	global_store_short v162, v151, s[100:101] offset:64 nt
	v_lshlrev_b32_e32 v152, 16, v152
	v_mul_f32_e32 v152, 0x3fb504f3, v152
	v_fma_mixlo_f16 v152, s36, v61, v152
	global_store_short v162, v152, s[100:101] offset:2048 nt
	v_lshlrev_b32_e32 v153, 16, v153
	v_mul_f32_e32 v153, 0x3fb504f3, v153
	v_fma_mixlo_f16 v153, s36, v45, v153
	global_store_short v162, v153, s[100:101] offset:2112 nt
	s_add_u32 s100, s100, 0x4000
	s_addc_u32 s101, s101, 0
	v_lshlrev_b32_e32 v154, 16, v154
	v_mul_f32_e32 v154, 0x3fb504f3, v154
	v_fma_mixlo_f16 v154, s36, v62, v154
	global_store_short v162, v154, s[100:101] offset:-4096 nt
	v_lshlrev_b32_e32 v155, 16, v155
	v_mul_f32_e32 v155, 0x3fb504f3, v155
	v_fma_mixlo_f16 v155, s36, v46, v155
	global_store_short v162, v155, s[100:101] offset:-4032 nt
	v_lshlrev_b32_e32 v156, 16, v156
	v_mul_f32_e32 v156, 0x3fb504f3, v156
	v_fma_mixlo_f16 v156, s36, v63, v156
; DI float bf2f(u16 v) { return __uint_as_float(((unsigned)v) << 16); }
; DI int crow(int i, int h) { return (i & 3) + 8 * (i >> 2) + 4 * h; }
; DI void phase_gemm_resid(const Params& p, const u16* A, int lda, int K, const u16* Bt, bool last_sub, float scl,
;                          int row0, int nrows, char* smem) {
;     ...
;         for (int i = 0; i < 16; ++i) {
;           const size_t row = (size_t)row0 + mt * 256 + wm * 128 + ms * 32 + crow(i, lh);
;           const int col = nt * 256 + wn * 64 + ns * 32 + lr;
;           __builtin_nontemporal_store(__builtin_bit_cast(u16, (_Float16)(ALPHA * bf2f(xres[row * D + col]) + scl * acc[ms][ns][i])), &r16[row * D + col]);
	global_store_short v162, v156, s[100:101] offset:-2048 nt
	v_lshlrev_b32_e32 v157, 16, v157
	v_mul_f32_e32 v157, 0x3fb504f3, v157
	v_fma_mixlo_f16 v157, s36, v47, v157
	global_store_short v162, v157, s[100:101] offset:-1984 nt
	v_lshlrev_b32_e32 v158, 16, v158
	v_mul_f32_e32 v158, 0x3fb504f3, v158
	v_fma_mixlo_f16 v158, s36, v64, v158
	global_store_short v162, v158, s[100:101] offset:0 nt
	v_lshlrev_b32_e32 v159, 16, v159
	v_mul_f32_e32 v159, 0x3fb504f3, v159
	v_fma_mixlo_f16 v159, s36, v48, v159
	global_store_short v162, v159, s[100:101] offset:64 nt
	v_lshlrev_b32_e32 v160, 16, v160
	v_mul_f32_e32 v160, 0x3fb504f3, v160
	v_fma_mixlo_f16 v160, s36, v65, v160
	global_store_short v162, v160, s[100:101] offset:2048 nt
	v_lshlrev_b32_e32 v161, 16, v161
	v_mul_f32_e32 v161, 0x3fb504f3, v161
	v_fma_mixlo_f16 v161, s36, v49, v161
	global_store_short v162, v161, s[100:101] offset:2112 nt
	s_add_u32 s100, s100, 0x4000
	s_addc_u32 s101, s101, 0
	global_load_ushort v146, v162, s[98:99] offset:-4096
	global_load_ushort v147, v162, s[98:99] offset:-4032
	global_load_ushort v148, v162, s[98:99] offset:-2048
	global_load_ushort v149, v162, s[98:99] offset:-1984
	global_load_ushort v150, v162, s[98:99] offset:0
	global_load_ushort v151, v162, s[98:99] offset:64
	global_load_ushort v152, v162, s[98:99] offset:2048
	global_load_ushort v153, v162, s[98:99] offset:2112
	s_add_u32 s98, s98, 0x4000
	s_addc_u32 s99, s99, 0
	global_load_ushort v154, v162, s[98:99] offset:-4096
	global_load_ushort v155, v162, s[98:99] offset:-4032
	global_load_ushort v156, v162, s[98:99] offset:-2048
	global_load_ushort v157, v162, s[98:99] offset:-1984
	global_load_ushort v158, v162, s[98:99] offset:0
	global_load_ushort v159, v162, s[98:99] offset:64
	global_load_ushort v160, v162, s[98:99] offset:2048
	global_load_ushort v161, v162, s[98:99] offset:2112
	s_add_u32 s98, s98, 0x4000
	s_addc_u32 s99, s99, 0
	s_waitcnt vmcnt(32)
	v_lshlrev_b32_e32 v130, 16, v130
	v_mul_f32_e32 v130, 0x3fb504f3, v130
	v_fma_mixlo_f16 v130, s36, v18, v130
	global_store_short v162, v130, s[100:101] offset:-4096 nt
	v_lshlrev_b32_e32 v131, 16, v131
	v_mul_f32_e32 v131, 0x3fb504f3, v131
	v_fma_mixlo_f16 v131, s36, v2, v131
	global_store_short v162, v131, s[100:101] offset:-4032 nt
	v_lshlrev_b32_e32 v132, 16, v132
	v_mul_f32_e32 v132, 0x3fb504f3, v132
	v_fma_mixlo_f16 v132, s36, v19, v132
	global_store_short v162, v132, s[100:101] offset:-2048 nt
	v_lshlrev_b32_e32 v133, 16, v133
	v_mul_f32_e32 v133, 0x3fb504f3, v133
	v_fma_mixlo_f16 v133, s36, v3, v133
	global_store_short v162, v133, s[100:101] offset:-1984 nt
	v_lshlrev_b32_e32 v134, 16, v134
	v_mul_f32_e32 v134, 0x3fb504f3, v134
	v_fma_mixlo_f16 v134, s36, v20, v134
	global_store_short v162, v134, s[100:101] offset:0 nt
	v_lshlrev_b32_e32 v135, 16, v135
	v_mul_f32_e32 v135, 0x3fb504f3, v135
	v_fma_mixlo_f16 v135, s36, v4, v135
	global_store_short v162, v135, s[100:101] offset:64 nt
	v_lshlrev_b32_e32 v136, 16, v136
	v_mul_f32_e32 v136, 0x3fb504f3, v136
	v_fma_mixlo_f16 v136, s36, v21, v136
	global_store_short v162, v136, s[100:101] offset:2048 nt
	v_lshlrev_b32_e32 v137, 16, v137
	v_mul_f32_e32 v137, 0x3fb504f3, v137
	v_fma_mixlo_f16 v137, s36, v5, v137
	global_store_short v162, v137, s[100:101] offset:2112 nt
	s_add_u32 s100, s100, 0x4000
	s_addc_u32 s101, s101, 0
	v_lshlrev_b32_e32 v138, 16, v138
	v_mul_f32_e32 v138, 0x3fb504f3, v138
	v_fma_mixlo_f16 v138, s36, v22, v138
	global_store_short v162, v138, s[100:101] offset:-4096 nt
	v_lshlrev_b32_e32 v139, 16, v139
	v_mul_f32_e32 v139, 0x3fb504f3, v139
	v_fma_mixlo_f16 v139, s36, v6, v139
	global_store_short v162, v139, s[100:101] offset:-4032 nt
	v_lshlrev_b32_e32 v140, 16, v140
	v_mul_f32_e32 v140, 0x3fb504f3, v140
	v_fma_mixlo_f16 v140, s36, v23, v140
	global_store_short v162, v140, s[100:101] offset:-2048 nt
	v_lshlrev_b32_e32 v141, 16, v141
	v_mul_f32_e32 v141, 0x3fb504f3, v141
	v_fma_mixlo_f16 v141, s36, v7, v141
	global_store_short v162, v141, s[100:101] offset:-1984 nt
	v_lshlrev_b32_e32 v142, 16, v142
	v_mul_f32_e32 v142, 0x3fb504f3, v142
	v_fma_mixlo_f16 v142, s36, v24, v142
	global_store_short v162, v142, s[100:101] offset:0 nt
	v_lshlrev_b32_e32 v143, 16, v143
	v_mul_f32_e32 v143, 0x3fb504f3, v143
	v_fma_mixlo_f16 v143, s36, v8, v143
	global_store_short v162, v143, s[100:101] offset:64 nt
	v_lshlrev_b32_e32 v144, 16, v144
	v_mul_f32_e32 v144, 0x3fb504f3, v144
	v_fma_mixlo_f16 v144, s36, v25, v144
	global_store_short v162, v144, s[100:101] offset:2048 nt
	v_lshlrev_b32_e32 v145, 16, v145
	v_mul_f32_e32 v145, 0x3fb504f3, v145
	v_fma_mixlo_f16 v145, s36, v9, v145
	global_store_short v162, v145, s[100:101] offset:2112 nt
	s_add_u32 s100, s100, 0x4000
	s_addc_u32 s101, s101, 0
	s_waitcnt vmcnt(16)
; DI float bf2f(u16 v) { return __uint_as_float(((unsigned)v) << 16); }
; DI int crow(int i, int h) { return (i & 3) + 8 * (i >> 2) + 4 * h; }
; template <class Toff, class Setup, class Epi>
; DI void gemm256_stream(int tiles_per_xcd, int K, long ais, long akcs, long bis, Toff toff, Setup setup, Epi epi, char* smem) {
;     ...
;     if (!has_next) break;
;     q = qn;
;     Ac = An;
;     Bc = Bn;
;     G256_GLOAD(Ac, Bc, 1)
; DI void phase_gemm_resid(const Params& p, const u16* A, int lda, int K, const u16* Bt, bool last_sub, float scl,
;                          int row0, int nrows, char* smem) {
;     ...
;         for (int i = 0; i < 16; ++i) {
;           const size_t row = (size_t)row0 + mt * 256 + wm * 128 + ms * 32 + crow(i, lh);
;           const int col = nt * 256 + wn * 64 + ns * 32 + lr;
;           __builtin_nontemporal_store(__builtin_bit_cast(u16, (_Float16)(ALPHA * bf2f(xres[row * D + col]) + scl * acc[ms][ns][i])), &r16[row * D + col]);
	v_lshlrev_b32_e32 v146, 16, v146
	v_mul_f32_e32 v146, 0x3fb504f3, v146
	v_fma_mixlo_f16 v146, s36, v26, v146
	global_store_short v162, v146, s[100:101] offset:-4096 nt
	v_lshlrev_b32_e32 v147, 16, v147
	v_mul_f32_e32 v147, 0x3fb504f3, v147
	v_fma_mixlo_f16 v147, s36, v10, v147
	global_store_short v162, v147, s[100:101] offset:-4032 nt
	v_lshlrev_b32_e32 v148, 16, v148
	v_mul_f32_e32 v148, 0x3fb504f3, v148
	v_fma_mixlo_f16 v148, s36, v27, v148
	global_store_short v162, v148, s[100:101] offset:-2048 nt
	v_lshlrev_b32_e32 v149, 16, v149
	v_mul_f32_e32 v149, 0x3fb504f3, v149
	v_fma_mixlo_f16 v149, s36, v11, v149
	global_store_short v162, v149, s[100:101] offset:-1984 nt
	v_lshlrev_b32_e32 v150, 16, v150
	v_mul_f32_e32 v150, 0x3fb504f3, v150
	v_fma_mixlo_f16 v150, s36, v28, v150
	global_store_short v162, v150, s[100:101] offset:0 nt
	v_lshlrev_b32_e32 v151, 16, v151
	v_mul_f32_e32 v151, 0x3fb504f3, v151
	v_fma_mixlo_f16 v151, s36, v12, v151
	global_store_short v162, v151, s[100:101] offset:64 nt
	v_lshlrev_b32_e32 v152, 16, v152
	v_mul_f32_e32 v152, 0x3fb504f3, v152
	v_fma_mixlo_f16 v152, s36, v29, v152
	global_store_short v162, v152, s[100:101] offset:2048 nt
	v_lshlrev_b32_e32 v153, 16, v153
	v_mul_f32_e32 v153, 0x3fb504f3, v153
	v_fma_mixlo_f16 v153, s36, v13, v153
	global_store_short v162, v153, s[100:101] offset:2112 nt
	s_add_u32 s100, s100, 0x4000
	s_addc_u32 s101, s101, 0
	v_lshlrev_b32_e32 v154, 16, v154
	v_mul_f32_e32 v154, 0x3fb504f3, v154
	v_fma_mixlo_f16 v154, s36, v30, v154
	global_store_short v162, v154, s[100:101] offset:-4096 nt
	v_lshlrev_b32_e32 v155, 16, v155
	v_mul_f32_e32 v155, 0x3fb504f3, v155
	v_fma_mixlo_f16 v155, s36, v14, v155
	global_store_short v162, v155, s[100:101] offset:-4032 nt
	v_lshlrev_b32_e32 v156, 16, v156
	v_mul_f32_e32 v156, 0x3fb504f3, v156
	v_fma_mixlo_f16 v156, s36, v31, v156
	global_store_short v162, v156, s[100:101] offset:-2048 nt
	v_lshlrev_b32_e32 v157, 16, v157
	v_mul_f32_e32 v157, 0x3fb504f3, v157
	v_fma_mixlo_f16 v157, s36, v15, v157
	global_store_short v162, v157, s[100:101] offset:-1984 nt
	v_lshlrev_b32_e32 v158, 16, v158
	v_mul_f32_e32 v158, 0x3fb504f3, v158
	v_fma_mixlo_f16 v158, s36, v32, v158
	global_store_short v162, v158, s[100:101] offset:0 nt
	v_lshlrev_b32_e32 v159, 16, v159
	v_mul_f32_e32 v159, 0x3fb504f3, v159
	v_fma_mixlo_f16 v159, s36, v16, v159
	global_store_short v162, v159, s[100:101] offset:64 nt
	v_lshlrev_b32_e32 v160, 16, v160
	v_mul_f32_e32 v160, 0x3fb504f3, v160
	v_fma_mixlo_f16 v160, s36, v33, v160
	global_store_short v162, v160, s[100:101] offset:2048 nt
	v_lshlrev_b32_e32 v161, 16, v161
	v_mul_f32_e32 v161, 0x3fb504f3, v161
	v_fma_mixlo_f16 v161, s36, v17, v161
	global_store_short v162, v161, s[100:101] offset:2112 nt
	s_add_u32 s100, s100, 0x4000
	s_addc_u32 s101, s101, 0
	s_cbranch_vccz .LBB0_821
	s_lshl_b64 s[0:1], s[76:77], 1
	v_lshl_add_u64 v[2:3], v[190:191], 0, s[0:1]
	v_lshl_add_u64 v[4:5], v[188:189], 0, s[0:1]
	global_load_dwordx4 v[146:149], v[190:191], off offset:128
	global_load_dwordx4 v[158:161], v[188:189], off offset:128
	global_load_dwordx4 v[138:141], v[2:3], off offset:128
	global_load_dwordx4 v[154:157], v[4:5], off offset:128
	v_lshl_add_u64 v[2:3], v[2:3], 0, s[78:79]
	v_lshl_add_u64 v[4:5], v[4:5], 0, s[78:79]
	global_load_dwordx4 v[134:137], v[2:3], off offset:128
	global_load_dwordx4 v[150:153], v[4:5], off offset:128
	v_lshl_add_u64 v[2:3], v[2:3], 0, s[78:79]
	v_lshl_add_u64 v[4:5], v[4:5], 0, s[78:79]
	global_load_dwordx4 v[130:133], v[2:3], off offset:128
	global_load_dwordx4 v[142:145], v[4:5], off offset:128
	s_mov_b64 s[8:9], 0
	s_branch .LBB0_821

; #define PWS(p) launder((p).ws)
; #define LAS __attribute__((address_space(3)))
; __global__ void __launch_bounds__(NTHREADS) k_mega(Params p) {
;   extern __shared__ __attribute__((aligned(16))) char smem[];
;   cg::grid_group grid = cg::this_grid();
;   {
;     volatile LAS unsigned* st = (volatile LAS unsigned*)(smem + XB_LDS_OFF);
;     if (threadIdx.x == 0) { st[0] = 0u; st[1] = 0u; }
;     __syncthreads();
;     (void)xcd_barrier_post((unsigned*)(PWS(p) + WS_BAR), st);
;   }
; #pragma unroll 1
;   for (int step = 0; step < NSTEPS; ++step) {
	.amdhsa_kernel _Z6k_mega6Params
		.amdhsa_group_segment_fixed_size 0
		.amdhsa_private_segment_fixed_size 0
		.amdhsa_kernarg_size 592
		.amdhsa_user_sgpr_count 2
		.amdhsa_user_sgpr_dispatch_ptr 0
		.amdhsa_user_sgpr_queue_ptr 0
		.amdhsa_user_sgpr_kernarg_segment_ptr 1
		.amdhsa_user_sgpr_dispatch_id 0
		.amdhsa_user_sgpr_kernarg_preload_length 0
		.amdhsa_user_sgpr_kernarg_preload_offset 0
		.amdhsa_user_sgpr_private_segment_size 0
		.amdhsa_uses_dynamic_stack 0
		.amdhsa_enable_private_segment 0
		.amdhsa_system_sgpr_workgroup_id_x 1
		.amdhsa_system_sgpr_workgroup_id_y 0
		.amdhsa_system_sgpr_workgroup_id_z 0
		.amdhsa_system_sgpr_workgroup_info 0
		.amdhsa_system_vgpr_workitem_id 2
		.amdhsa_next_free_vgpr 256
		.amdhsa_next_free_sgpr 102
		.amdhsa_accum_offset 256
		.amdhsa_reserve_vcc 1
		.amdhsa_float_round_mode_32 0
		.amdhsa_float_round_mode_16_64 0
		.amdhsa_float_denorm_mode_32 3
		.amdhsa_float_denorm_mode_16_64 3
		.amdhsa_dx10_clamp 1
		.amdhsa_ieee_mode 1
		.amdhsa_fp16_overflow 0
		.amdhsa_tg_split 0
		.amdhsa_exception_fp_ieee_invalid_op 0
		.amdhsa_exception_fp_denorm_src 0
		.amdhsa_exception_fp_ieee_div_zero 0
		.amdhsa_exception_fp_ieee_overflow 0
		.amdhsa_exception_fp_ieee_underflow 0
		.amdhsa_exception_fp_ieee_inexact 0
		.amdhsa_exception_int_div_zero 0
	.end_amdhsa_kernel

; #define PWS(p) launder((p).ws)
; #define LAS __attribute__((address_space(3)))
; __global__ void __launch_bounds__(NTHREADS) k_mega(Params p) {
;   extern __shared__ __attribute__((aligned(16))) char smem[];
;   cg::grid_group grid = cg::this_grid();
;   {
;     volatile LAS unsigned* st = (volatile LAS unsigned*)(smem + XB_LDS_OFF);
;     if (threadIdx.x == 0) { st[0] = 0u; st[1] = 0u; }
;     __syncthreads();
;     (void)xcd_barrier_post((unsigned*)(PWS(p) + WS_BAR), st);
;   }
; #pragma unroll 1
;   for (int step = 0; step < NSTEPS; ++step) {
amdhsa.kernels:
  - .agpr_count:     0
    .args:
      - .offset:         0
        .size:           336
        .value_kind:     by_value
      - .offset:         336
        .size:           4
        .value_kind:     hidden_block_count_x
      - .offset:         340
        .size:           4
        .value_kind:     hidden_block_count_y
      - .offset:         344
        .size:           4
        .value_kind:     hidden_block_count_z
      - .offset:         348
        .size:           2
        .value_kind:     hidden_group_size_x
      - .offset:         350
        .size:           2
        .value_kind:     hidden_group_size_y
      - .offset:         352
        .size:           2
        .value_kind:     hidden_group_size_z
      - .offset:         354
        .size:           2
        .value_kind:     hidden_remainder_x
      - .offset:         356
        .size:           2
        .value_kind:     hidden_remainder_y
      - .offset:         358
        .size:           2
        .value_kind:     hidden_remainder_z
      - .offset:         376
        .size:           8
        .value_kind:     hidden_global_offset_x
      - .offset:         384
        .size:           8
        .value_kind:     hidden_global_offset_y
      - .offset:         392
        .size:           8
        .value_kind:     hidden_global_offset_z
      - .offset:         400
        .size:           2
        .value_kind:     hidden_grid_dims
      - .offset:         424
        .size:           8
        .value_kind:     hidden_multigrid_sync_arg
      - .offset:         456
        .size:           4
        .value_kind:     hidden_dynamic_lds_size
    .group_segment_fixed_size: 0
    .kernarg_segment_align: 8
    .kernarg_segment_size: 592
    .language:       OpenCL C
    .language_version:
      - 2
      - 0
    .max_flat_workgroup_size: 512
    .name:           _Z6k_mega6Params
    .private_segment_fixed_size: 0
    .sgpr_count:     108
    .sgpr_spill_count: 206
    .symbol:         _Z6k_mega6Params.kd
    .uniform_work_group_size: 1
    .uses_dynamic_stack: false
    .vgpr_count:     256
    .vgpr_spill_count: 0
    .wavefront_size: 64
